# M2 chunk-state scan hand-written: 28 chunk loads in flight with counted waits, per-chunk scalars via v_readlane, n-state on 16 lanes of wave 0
# baseline (speedup 1.0000x reference)
.LBB0_430:
	s_or_b64 exec, exec, s[0:1]
	v_add_u32_e32 v86, s65, v214
	s_mov_b32 s0, 0x20000
	v_cmp_gt_i32_e32 vcc, s0, v86
	s_waitcnt lgkmcnt(0)
	s_barrier
	s_and_saveexec_b64 s[0:1], vcc
	s_cbranch_execz .LBB0_483
	v_and_b32_e32 v0, 63, v214
	v_readfirstlane_b32 s14, v214
	s_lshr_b32 s15, s90, 3
	s_lshl_b32 s12, s15, 21
	s_add_u32 s2, s80, s12
	s_addc_u32 s3, s81, 0
	s_add_u32 s4, s82, s12
	s_addc_u32 s5, s83, 0
	s_add_u32 s4, s4, 0x1800000
	s_addc_u32 s5, s5, 0
	s_lshl_b32 s12, s15, 9
	s_add_u32 s12, s82, s12
	s_addc_u32 s13, s83, 0
	s_add_u32 s12, s12, 0x1160000
	s_addc_u32 s13, s13, 0
	v_lshlrev_b32_e32 v1, 3, v0
	global_load_dwordx2 v[2:3], v1, s[12:13]
	s_and_b32 s13, s90, 7
	s_lshl_b32 s12, s13, 9
	v_add_u32_e32 v1, s12, v214
	v_lshlrev_b32_e32 v1, 3, v1
	v_mov_b32_e32 v4, 0
	v_mov_b32_e32 v5, 0
	v_mov_b32_e32 v6, 0
	v_mov_b32_e32 v7, 0
	v_mov_b32_e32 v8, 0
	v_mov_b32_e32 v12, 0
	s_cmp_lt_u32 s14, 64
	s_cbranch_scc1 .Lm2_w0
	global_load_dwordx2 v[100:101], v1, s[2:3]
	s_add_u32 s2, s2, 0x8000
	s_addc_u32 s3, s3, 0
	global_load_dwordx2 v[102:103], v1, s[2:3]
	s_add_u32 s2, s2, 0x8000
	s_addc_u32 s3, s3, 0
	global_load_dwordx2 v[104:105], v1, s[2:3]
	s_add_u32 s2, s2, 0x8000
	s_addc_u32 s3, s3, 0
	global_load_dwordx2 v[106:107], v1, s[2:3]
	s_add_u32 s2, s2, 0x8000
	s_addc_u32 s3, s3, 0
	global_load_dwordx2 v[108:109], v1, s[2:3]
	s_add_u32 s2, s2, 0x8000
	s_addc_u32 s3, s3, 0
	global_load_dwordx2 v[110:111], v1, s[2:3]
	s_add_u32 s2, s2, 0x8000
	s_addc_u32 s3, s3, 0
	global_load_dwordx2 v[112:113], v1, s[2:3]
	s_add_u32 s2, s2, 0x8000
	s_addc_u32 s3, s3, 0
	global_load_dwordx2 v[114:115], v1, s[2:3]
	s_add_u32 s2, s2, 0x8000
	s_addc_u32 s3, s3, 0
	global_load_dwordx2 v[116:117], v1, s[2:3]
	s_add_u32 s2, s2, 0x8000
	s_addc_u32 s3, s3, 0
	global_load_dwordx2 v[118:119], v1, s[2:3]
	s_add_u32 s2, s2, 0x8000
	s_addc_u32 s3, s3, 0
	global_load_dwordx2 v[120:121], v1, s[2:3]
	s_add_u32 s2, s2, 0x8000
	s_addc_u32 s3, s3, 0
	global_load_dwordx2 v[122:123], v1, s[2:3]
	s_add_u32 s2, s2, 0x8000
	s_addc_u32 s3, s3, 0
	global_load_dwordx2 v[124:125], v1, s[2:3]
	s_add_u32 s2, s2, 0x8000
	s_addc_u32 s3, s3, 0
	global_load_dwordx2 v[126:127], v1, s[2:3]
	s_add_u32 s2, s2, 0x8000
	s_addc_u32 s3, s3, 0
	global_load_dwordx2 v[128:129], v1, s[2:3]
	s_add_u32 s2, s2, 0x8000
	s_addc_u32 s3, s3, 0
	global_load_dwordx2 v[130:131], v1, s[2:3]
	s_add_u32 s2, s2, 0x8000
	s_addc_u32 s3, s3, 0
	global_load_dwordx2 v[132:133], v1, s[2:3]
	s_add_u32 s2, s2, 0x8000
	s_addc_u32 s3, s3, 0
	global_load_dwordx2 v[134:135], v1, s[2:3]
	s_add_u32 s2, s2, 0x8000
	s_addc_u32 s3, s3, 0
	global_load_dwordx2 v[136:137], v1, s[2:3]
	s_add_u32 s2, s2, 0x8000
	s_addc_u32 s3, s3, 0
	global_load_dwordx2 v[138:139], v1, s[2:3]
	s_add_u32 s2, s2, 0x8000
	s_addc_u32 s3, s3, 0
	global_load_dwordx2 v[140:141], v1, s[2:3]
	s_add_u32 s2, s2, 0x8000
	s_addc_u32 s3, s3, 0
	global_load_dwordx2 v[142:143], v1, s[2:3]
	s_add_u32 s2, s2, 0x8000
	s_addc_u32 s3, s3, 0
	global_load_dwordx2 v[144:145], v1, s[2:3]
	s_add_u32 s2, s2, 0x8000
	s_addc_u32 s3, s3, 0
	global_load_dwordx2 v[146:147], v1, s[2:3]
	s_add_u32 s2, s2, 0x8000
	s_addc_u32 s3, s3, 0
	global_load_dwordx2 v[148:149], v1, s[2:3]
	s_add_u32 s2, s2, 0x8000
	s_addc_u32 s3, s3, 0
	global_load_dwordx2 v[150:151], v1, s[2:3]
	s_add_u32 s2, s2, 0x8000
	s_addc_u32 s3, s3, 0
	global_load_dwordx2 v[152:153], v1, s[2:3]
	s_add_u32 s2, s2, 0x8000
	s_addc_u32 s3, s3, 0
	global_load_dwordx2 v[154:155], v1, s[2:3]
	s_add_u32 s2, s2, 0x8000
	s_addc_u32 s3, s3, 0
	s_waitcnt vmcnt(28)
	v_readlane_b32 s12, v2, 0
	v_readlane_b32 s14, v3, 0
	v_cvt_pk_bf16_f32 v20, v4, v5
	v_cvt_pk_bf16_f32 v21, v6, v7
	global_store_dwordx2 v1, v[20:21], s[4:5]
	s_add_u32 s4, s4, 0x8000
	s_addc_u32 s5, s5, 0
	v_add_f32_e32 v13, s12, v12
	v_max_f32_e64 v14, s14, s14
	v_max_f32_e32 v15, v13, v14
	v_sub_f32_e32 v13, v13, v15
	v_sub_f32_e32 v14, s14, v15
	v_mul_f32_e32 v14, 0x3fb8aa3b, v14
	v_mul_f32_e32 v13, 0x3fb8aa3b, v13
	v_exp_f32_e32 v16, v14
	v_exp_f32_e32 v18, v13
	s_waitcnt vmcnt(28)
	v_lshlrev_b32_e32 v24, 16, v100
	v_and_b32_e32 v25, 0xffff0000, v100
	v_lshlrev_b32_e32 v26, 16, v101
	v_and_b32_e32 v27, 0xffff0000, v101
	global_load_dwordx2 v[100:101], v1, s[2:3]
	s_add_u32 s2, s2, 0x8000
	s_addc_u32 s3, s3, 0
	v_pk_mul_f32 v[24:25], v[16:17], v[24:25] op_sel_hi:[0,1]
	v_pk_mul_f32 v[26:27], v[16:17], v[26:27] op_sel_hi:[0,1]
	v_pk_fma_f32 v[4:5], v[4:5], v[18:19], v[24:25] op_sel_hi:[1,0,1]
	v_pk_fma_f32 v[6:7], v[6:7], v[18:19], v[26:27] op_sel_hi:[1,0,1]
	v_mov_b32_e32 v12, v15
	v_readlane_b32 s12, v2, 1
	v_readlane_b32 s14, v3, 1
	v_cvt_pk_bf16_f32 v20, v4, v5
	v_cvt_pk_bf16_f32 v21, v6, v7
	global_store_dwordx2 v1, v[20:21], s[4:5]
	s_add_u32 s4, s4, 0x8000
	s_addc_u32 s5, s5, 0
	v_add_f32_e32 v13, s12, v12
	v_max_f32_e64 v14, s14, s14
	v_max_f32_e32 v15, v13, v14
	v_sub_f32_e32 v13, v13, v15
	v_sub_f32_e32 v14, s14, v15
	v_mul_f32_e32 v14, 0x3fb8aa3b, v14
	v_mul_f32_e32 v13, 0x3fb8aa3b, v13
	v_exp_f32_e32 v16, v14
	v_exp_f32_e32 v18, v13
	s_waitcnt vmcnt(29)
	v_lshlrev_b32_e32 v24, 16, v102
	v_and_b32_e32 v25, 0xffff0000, v102
	v_lshlrev_b32_e32 v26, 16, v103
	v_and_b32_e32 v27, 0xffff0000, v103
	global_load_dwordx2 v[102:103], v1, s[2:3]
	s_add_u32 s2, s2, 0x8000
	s_addc_u32 s3, s3, 0
	v_pk_mul_f32 v[24:25], v[16:17], v[24:25] op_sel_hi:[0,1]
	v_pk_mul_f32 v[26:27], v[16:17], v[26:27] op_sel_hi:[0,1]
	v_pk_fma_f32 v[4:5], v[4:5], v[18:19], v[24:25] op_sel_hi:[1,0,1]
	v_pk_fma_f32 v[6:7], v[6:7], v[18:19], v[26:27] op_sel_hi:[1,0,1]
	v_mov_b32_e32 v12, v15
	v_readlane_b32 s12, v2, 2
	v_readlane_b32 s14, v3, 2
	v_cvt_pk_bf16_f32 v20, v4, v5
	v_cvt_pk_bf16_f32 v21, v6, v7
	global_store_dwordx2 v1, v[20:21], s[4:5]
	s_add_u32 s4, s4, 0x8000
	s_addc_u32 s5, s5, 0
	v_add_f32_e32 v13, s12, v12
	v_max_f32_e64 v14, s14, s14
	v_max_f32_e32 v15, v13, v14
	v_sub_f32_e32 v13, v13, v15
	v_sub_f32_e32 v14, s14, v15
	v_mul_f32_e32 v14, 0x3fb8aa3b, v14
	v_mul_f32_e32 v13, 0x3fb8aa3b, v13
	v_exp_f32_e32 v16, v14
	v_exp_f32_e32 v18, v13
	s_waitcnt vmcnt(30)
	v_lshlrev_b32_e32 v24, 16, v104
	v_and_b32_e32 v25, 0xffff0000, v104
	v_lshlrev_b32_e32 v26, 16, v105
	v_and_b32_e32 v27, 0xffff0000, v105
	global_load_dwordx2 v[104:105], v1, s[2:3]
	s_add_u32 s2, s2, 0x8000
	s_addc_u32 s3, s3, 0
	v_pk_mul_f32 v[24:25], v[16:17], v[24:25] op_sel_hi:[0,1]
	v_pk_mul_f32 v[26:27], v[16:17], v[26:27] op_sel_hi:[0,1]
	v_pk_fma_f32 v[4:5], v[4:5], v[18:19], v[24:25] op_sel_hi:[1,0,1]
	v_pk_fma_f32 v[6:7], v[6:7], v[18:19], v[26:27] op_sel_hi:[1,0,1]
	v_mov_b32_e32 v12, v15
	v_readlane_b32 s12, v2, 3
	v_readlane_b32 s14, v3, 3
	v_cvt_pk_bf16_f32 v20, v4, v5
	v_cvt_pk_bf16_f32 v21, v6, v7
	global_store_dwordx2 v1, v[20:21], s[4:5]
	s_add_u32 s4, s4, 0x8000
	s_addc_u32 s5, s5, 0
	v_add_f32_e32 v13, s12, v12
	v_max_f32_e64 v14, s14, s14
	v_max_f32_e32 v15, v13, v14
	v_sub_f32_e32 v13, v13, v15
	v_sub_f32_e32 v14, s14, v15
	v_mul_f32_e32 v14, 0x3fb8aa3b, v14
	v_mul_f32_e32 v13, 0x3fb8aa3b, v13
	v_exp_f32_e32 v16, v14
	v_exp_f32_e32 v18, v13
	s_waitcnt vmcnt(31)
	v_lshlrev_b32_e32 v24, 16, v106
	v_and_b32_e32 v25, 0xffff0000, v106
	v_lshlrev_b32_e32 v26, 16, v107
	v_and_b32_e32 v27, 0xffff0000, v107
	global_load_dwordx2 v[106:107], v1, s[2:3]
	s_add_u32 s2, s2, 0x8000
	s_addc_u32 s3, s3, 0
	v_pk_mul_f32 v[24:25], v[16:17], v[24:25] op_sel_hi:[0,1]
	v_pk_mul_f32 v[26:27], v[16:17], v[26:27] op_sel_hi:[0,1]
	v_pk_fma_f32 v[4:5], v[4:5], v[18:19], v[24:25] op_sel_hi:[1,0,1]
	v_pk_fma_f32 v[6:7], v[6:7], v[18:19], v[26:27] op_sel_hi:[1,0,1]
	v_mov_b32_e32 v12, v15
	v_readlane_b32 s12, v2, 4
	v_readlane_b32 s14, v3, 4
	v_cvt_pk_bf16_f32 v20, v4, v5
	v_cvt_pk_bf16_f32 v21, v6, v7
	global_store_dwordx2 v1, v[20:21], s[4:5]
	s_add_u32 s4, s4, 0x8000
	s_addc_u32 s5, s5, 0
	v_add_f32_e32 v13, s12, v12
	v_max_f32_e64 v14, s14, s14
	v_max_f32_e32 v15, v13, v14
	v_sub_f32_e32 v13, v13, v15
	v_sub_f32_e32 v14, s14, v15
	v_mul_f32_e32 v14, 0x3fb8aa3b, v14
	v_mul_f32_e32 v13, 0x3fb8aa3b, v13
	v_exp_f32_e32 v16, v14
	v_exp_f32_e32 v18, v13
	s_waitcnt vmcnt(32)
	v_lshlrev_b32_e32 v24, 16, v108
	v_and_b32_e32 v25, 0xffff0000, v108
	v_lshlrev_b32_e32 v26, 16, v109
	v_and_b32_e32 v27, 0xffff0000, v109
	global_load_dwordx2 v[108:109], v1, s[2:3]
	s_add_u32 s2, s2, 0x8000
	s_addc_u32 s3, s3, 0
	v_pk_mul_f32 v[24:25], v[16:17], v[24:25] op_sel_hi:[0,1]
	v_pk_mul_f32 v[26:27], v[16:17], v[26:27] op_sel_hi:[0,1]
	v_pk_fma_f32 v[4:5], v[4:5], v[18:19], v[24:25] op_sel_hi:[1,0,1]
	v_pk_fma_f32 v[6:7], v[6:7], v[18:19], v[26:27] op_sel_hi:[1,0,1]
	v_mov_b32_e32 v12, v15
	v_readlane_b32 s12, v2, 5
	v_readlane_b32 s14, v3, 5
	v_cvt_pk_bf16_f32 v20, v4, v5
	v_cvt_pk_bf16_f32 v21, v6, v7
	global_store_dwordx2 v1, v[20:21], s[4:5]
	s_add_u32 s4, s4, 0x8000
	s_addc_u32 s5, s5, 0
	v_add_f32_e32 v13, s12, v12
	v_max_f32_e64 v14, s14, s14
	v_max_f32_e32 v15, v13, v14
	v_sub_f32_e32 v13, v13, v15
	v_sub_f32_e32 v14, s14, v15
	v_mul_f32_e32 v14, 0x3fb8aa3b, v14
	v_mul_f32_e32 v13, 0x3fb8aa3b, v13
	v_exp_f32_e32 v16, v14
	v_exp_f32_e32 v18, v13
	s_waitcnt vmcnt(33)
	v_lshlrev_b32_e32 v24, 16, v110
	v_and_b32_e32 v25, 0xffff0000, v110
	v_lshlrev_b32_e32 v26, 16, v111
	v_and_b32_e32 v27, 0xffff0000, v111
	global_load_dwordx2 v[110:111], v1, s[2:3]
	s_add_u32 s2, s2, 0x8000
	s_addc_u32 s3, s3, 0
	v_pk_mul_f32 v[24:25], v[16:17], v[24:25] op_sel_hi:[0,1]
	v_pk_mul_f32 v[26:27], v[16:17], v[26:27] op_sel_hi:[0,1]
	v_pk_fma_f32 v[4:5], v[4:5], v[18:19], v[24:25] op_sel_hi:[1,0,1]
	v_pk_fma_f32 v[6:7], v[6:7], v[18:19], v[26:27] op_sel_hi:[1,0,1]
	v_mov_b32_e32 v12, v15
	v_readlane_b32 s12, v2, 6
	v_readlane_b32 s14, v3, 6
	v_cvt_pk_bf16_f32 v20, v4, v5
	v_cvt_pk_bf16_f32 v21, v6, v7
	global_store_dwordx2 v1, v[20:21], s[4:5]
	s_add_u32 s4, s4, 0x8000
	s_addc_u32 s5, s5, 0
	v_add_f32_e32 v13, s12, v12
	v_max_f32_e64 v14, s14, s14
	v_max_f32_e32 v15, v13, v14
	v_sub_f32_e32 v13, v13, v15
	v_sub_f32_e32 v14, s14, v15
	v_mul_f32_e32 v14, 0x3fb8aa3b, v14
	v_mul_f32_e32 v13, 0x3fb8aa3b, v13
	v_exp_f32_e32 v16, v14
	v_exp_f32_e32 v18, v13
	s_waitcnt vmcnt(34)
	v_lshlrev_b32_e32 v24, 16, v112
	v_and_b32_e32 v25, 0xffff0000, v112
	v_lshlrev_b32_e32 v26, 16, v113
	v_and_b32_e32 v27, 0xffff0000, v113
	global_load_dwordx2 v[112:113], v1, s[2:3]
	s_add_u32 s2, s2, 0x8000
	s_addc_u32 s3, s3, 0
	v_pk_mul_f32 v[24:25], v[16:17], v[24:25] op_sel_hi:[0,1]
	v_pk_mul_f32 v[26:27], v[16:17], v[26:27] op_sel_hi:[0,1]
	v_pk_fma_f32 v[4:5], v[4:5], v[18:19], v[24:25] op_sel_hi:[1,0,1]
	v_pk_fma_f32 v[6:7], v[6:7], v[18:19], v[26:27] op_sel_hi:[1,0,1]
	v_mov_b32_e32 v12, v15
	v_readlane_b32 s12, v2, 7
	v_readlane_b32 s14, v3, 7
	v_cvt_pk_bf16_f32 v20, v4, v5
	v_cvt_pk_bf16_f32 v21, v6, v7
	global_store_dwordx2 v1, v[20:21], s[4:5]
	s_add_u32 s4, s4, 0x8000
	s_addc_u32 s5, s5, 0
	v_add_f32_e32 v13, s12, v12
	v_max_f32_e64 v14, s14, s14
	v_max_f32_e32 v15, v13, v14
	v_sub_f32_e32 v13, v13, v15
	v_sub_f32_e32 v14, s14, v15
	v_mul_f32_e32 v14, 0x3fb8aa3b, v14
	v_mul_f32_e32 v13, 0x3fb8aa3b, v13
	v_exp_f32_e32 v16, v14
	v_exp_f32_e32 v18, v13
	s_waitcnt vmcnt(35)
	v_lshlrev_b32_e32 v24, 16, v114
	v_and_b32_e32 v25, 0xffff0000, v114
	v_lshlrev_b32_e32 v26, 16, v115
	v_and_b32_e32 v27, 0xffff0000, v115
	global_load_dwordx2 v[114:115], v1, s[2:3]
	s_add_u32 s2, s2, 0x8000
	s_addc_u32 s3, s3, 0
	v_pk_mul_f32 v[24:25], v[16:17], v[24:25] op_sel_hi:[0,1]
	v_pk_mul_f32 v[26:27], v[16:17], v[26:27] op_sel_hi:[0,1]
	v_pk_fma_f32 v[4:5], v[4:5], v[18:19], v[24:25] op_sel_hi:[1,0,1]
	v_pk_fma_f32 v[6:7], v[6:7], v[18:19], v[26:27] op_sel_hi:[1,0,1]
	v_mov_b32_e32 v12, v15
	v_readlane_b32 s12, v2, 8
	v_readlane_b32 s14, v3, 8
	v_cvt_pk_bf16_f32 v20, v4, v5
	v_cvt_pk_bf16_f32 v21, v6, v7
	global_store_dwordx2 v1, v[20:21], s[4:5]
	s_add_u32 s4, s4, 0x8000
	s_addc_u32 s5, s5, 0
	v_add_f32_e32 v13, s12, v12
	v_max_f32_e64 v14, s14, s14
	v_max_f32_e32 v15, v13, v14
	v_sub_f32_e32 v13, v13, v15
	v_sub_f32_e32 v14, s14, v15
	v_mul_f32_e32 v14, 0x3fb8aa3b, v14
	v_mul_f32_e32 v13, 0x3fb8aa3b, v13
	v_exp_f32_e32 v16, v14
	v_exp_f32_e32 v18, v13
	s_waitcnt vmcnt(36)
	v_lshlrev_b32_e32 v24, 16, v116
	v_and_b32_e32 v25, 0xffff0000, v116
	v_lshlrev_b32_e32 v26, 16, v117
	v_and_b32_e32 v27, 0xffff0000, v117
	global_load_dwordx2 v[116:117], v1, s[2:3]
	s_add_u32 s2, s2, 0x8000
	s_addc_u32 s3, s3, 0
	v_pk_mul_f32 v[24:25], v[16:17], v[24:25] op_sel_hi:[0,1]
	v_pk_mul_f32 v[26:27], v[16:17], v[26:27] op_sel_hi:[0,1]
	v_pk_fma_f32 v[4:5], v[4:5], v[18:19], v[24:25] op_sel_hi:[1,0,1]
	v_pk_fma_f32 v[6:7], v[6:7], v[18:19], v[26:27] op_sel_hi:[1,0,1]
	v_mov_b32_e32 v12, v15
	v_readlane_b32 s12, v2, 9
	v_readlane_b32 s14, v3, 9
	v_cvt_pk_bf16_f32 v20, v4, v5
	v_cvt_pk_bf16_f32 v21, v6, v7
	global_store_dwordx2 v1, v[20:21], s[4:5]
	s_add_u32 s4, s4, 0x8000
	s_addc_u32 s5, s5, 0
	v_add_f32_e32 v13, s12, v12
	v_max_f32_e64 v14, s14, s14
	v_max_f32_e32 v15, v13, v14
	v_sub_f32_e32 v13, v13, v15
	v_sub_f32_e32 v14, s14, v15
	v_mul_f32_e32 v14, 0x3fb8aa3b, v14
	v_mul_f32_e32 v13, 0x3fb8aa3b, v13
	v_exp_f32_e32 v16, v14
	v_exp_f32_e32 v18, v13
	s_waitcnt vmcnt(37)
	v_lshlrev_b32_e32 v24, 16, v118
	v_and_b32_e32 v25, 0xffff0000, v118
	v_lshlrev_b32_e32 v26, 16, v119
	v_and_b32_e32 v27, 0xffff0000, v119
	global_load_dwordx2 v[118:119], v1, s[2:3]
	s_add_u32 s2, s2, 0x8000
	s_addc_u32 s3, s3, 0
	v_pk_mul_f32 v[24:25], v[16:17], v[24:25] op_sel_hi:[0,1]
	v_pk_mul_f32 v[26:27], v[16:17], v[26:27] op_sel_hi:[0,1]
	v_pk_fma_f32 v[4:5], v[4:5], v[18:19], v[24:25] op_sel_hi:[1,0,1]
	v_pk_fma_f32 v[6:7], v[6:7], v[18:19], v[26:27] op_sel_hi:[1,0,1]
	v_mov_b32_e32 v12, v15
	v_readlane_b32 s12, v2, 10
	v_readlane_b32 s14, v3, 10
	v_cvt_pk_bf16_f32 v20, v4, v5
	v_cvt_pk_bf16_f32 v21, v6, v7
	global_store_dwordx2 v1, v[20:21], s[4:5]
	s_add_u32 s4, s4, 0x8000
	s_addc_u32 s5, s5, 0
	v_add_f32_e32 v13, s12, v12
	v_max_f32_e64 v14, s14, s14
	v_max_f32_e32 v15, v13, v14
	v_sub_f32_e32 v13, v13, v15
	v_sub_f32_e32 v14, s14, v15
	v_mul_f32_e32 v14, 0x3fb8aa3b, v14
	v_mul_f32_e32 v13, 0x3fb8aa3b, v13
	v_exp_f32_e32 v16, v14
	v_exp_f32_e32 v18, v13
	s_waitcnt vmcnt(38)
	v_lshlrev_b32_e32 v24, 16, v120
	v_and_b32_e32 v25, 0xffff0000, v120
	v_lshlrev_b32_e32 v26, 16, v121
	v_and_b32_e32 v27, 0xffff0000, v121
	global_load_dwordx2 v[120:121], v1, s[2:3]
	s_add_u32 s2, s2, 0x8000
	s_addc_u32 s3, s3, 0
	v_pk_mul_f32 v[24:25], v[16:17], v[24:25] op_sel_hi:[0,1]
	v_pk_mul_f32 v[26:27], v[16:17], v[26:27] op_sel_hi:[0,1]
	v_pk_fma_f32 v[4:5], v[4:5], v[18:19], v[24:25] op_sel_hi:[1,0,1]
	v_pk_fma_f32 v[6:7], v[6:7], v[18:19], v[26:27] op_sel_hi:[1,0,1]
	v_mov_b32_e32 v12, v15
	v_readlane_b32 s12, v2, 11
	v_readlane_b32 s14, v3, 11
	v_cvt_pk_bf16_f32 v20, v4, v5
	v_cvt_pk_bf16_f32 v21, v6, v7
	global_store_dwordx2 v1, v[20:21], s[4:5]
	s_add_u32 s4, s4, 0x8000
	s_addc_u32 s5, s5, 0
	v_add_f32_e32 v13, s12, v12
	v_max_f32_e64 v14, s14, s14
	v_max_f32_e32 v15, v13, v14
	v_sub_f32_e32 v13, v13, v15
	v_sub_f32_e32 v14, s14, v15
	v_mul_f32_e32 v14, 0x3fb8aa3b, v14
	v_mul_f32_e32 v13, 0x3fb8aa3b, v13
	v_exp_f32_e32 v16, v14
	v_exp_f32_e32 v18, v13
	s_waitcnt vmcnt(39)
	v_lshlrev_b32_e32 v24, 16, v122
	v_and_b32_e32 v25, 0xffff0000, v122
	v_lshlrev_b32_e32 v26, 16, v123
	v_and_b32_e32 v27, 0xffff0000, v123
	global_load_dwordx2 v[122:123], v1, s[2:3]
	s_add_u32 s2, s2, 0x8000
	s_addc_u32 s3, s3, 0
	v_pk_mul_f32 v[24:25], v[16:17], v[24:25] op_sel_hi:[0,1]
	v_pk_mul_f32 v[26:27], v[16:17], v[26:27] op_sel_hi:[0,1]
	v_pk_fma_f32 v[4:5], v[4:5], v[18:19], v[24:25] op_sel_hi:[1,0,1]
	v_pk_fma_f32 v[6:7], v[6:7], v[18:19], v[26:27] op_sel_hi:[1,0,1]
	v_mov_b32_e32 v12, v15
	v_readlane_b32 s12, v2, 12
	v_readlane_b32 s14, v3, 12
	v_cvt_pk_bf16_f32 v20, v4, v5
	v_cvt_pk_bf16_f32 v21, v6, v7
	global_store_dwordx2 v1, v[20:21], s[4:5]
	s_add_u32 s4, s4, 0x8000
	s_addc_u32 s5, s5, 0
	v_add_f32_e32 v13, s12, v12
	v_max_f32_e64 v14, s14, s14
	v_max_f32_e32 v15, v13, v14
	v_sub_f32_e32 v13, v13, v15
	v_sub_f32_e32 v14, s14, v15
	v_mul_f32_e32 v14, 0x3fb8aa3b, v14
	v_mul_f32_e32 v13, 0x3fb8aa3b, v13
	v_exp_f32_e32 v16, v14
	v_exp_f32_e32 v18, v13
	s_waitcnt vmcnt(40)
	v_lshlrev_b32_e32 v24, 16, v124
	v_and_b32_e32 v25, 0xffff0000, v124
	v_lshlrev_b32_e32 v26, 16, v125
	v_and_b32_e32 v27, 0xffff0000, v125
	global_load_dwordx2 v[124:125], v1, s[2:3]
	s_add_u32 s2, s2, 0x8000
	s_addc_u32 s3, s3, 0
	v_pk_mul_f32 v[24:25], v[16:17], v[24:25] op_sel_hi:[0,1]
	v_pk_mul_f32 v[26:27], v[16:17], v[26:27] op_sel_hi:[0,1]
	v_pk_fma_f32 v[4:5], v[4:5], v[18:19], v[24:25] op_sel_hi:[1,0,1]
	v_pk_fma_f32 v[6:7], v[6:7], v[18:19], v[26:27] op_sel_hi:[1,0,1]
	v_mov_b32_e32 v12, v15
	v_readlane_b32 s12, v2, 13
	v_readlane_b32 s14, v3, 13
	v_cvt_pk_bf16_f32 v20, v4, v5
	v_cvt_pk_bf16_f32 v21, v6, v7
	global_store_dwordx2 v1, v[20:21], s[4:5]
	s_add_u32 s4, s4, 0x8000
	s_addc_u32 s5, s5, 0
	v_add_f32_e32 v13, s12, v12
	v_max_f32_e64 v14, s14, s14
	v_max_f32_e32 v15, v13, v14
	v_sub_f32_e32 v13, v13, v15
	v_sub_f32_e32 v14, s14, v15
	v_mul_f32_e32 v14, 0x3fb8aa3b, v14
	v_mul_f32_e32 v13, 0x3fb8aa3b, v13
	v_exp_f32_e32 v16, v14
	v_exp_f32_e32 v18, v13
	s_waitcnt vmcnt(41)
	v_lshlrev_b32_e32 v24, 16, v126
	v_and_b32_e32 v25, 0xffff0000, v126
	v_lshlrev_b32_e32 v26, 16, v127
	v_and_b32_e32 v27, 0xffff0000, v127
	global_load_dwordx2 v[126:127], v1, s[2:3]
	s_add_u32 s2, s2, 0x8000
	s_addc_u32 s3, s3, 0
	v_pk_mul_f32 v[24:25], v[16:17], v[24:25] op_sel_hi:[0,1]
	v_pk_mul_f32 v[26:27], v[16:17], v[26:27] op_sel_hi:[0,1]
	v_pk_fma_f32 v[4:5], v[4:5], v[18:19], v[24:25] op_sel_hi:[1,0,1]
	v_pk_fma_f32 v[6:7], v[6:7], v[18:19], v[26:27] op_sel_hi:[1,0,1]
	v_mov_b32_e32 v12, v15
	v_readlane_b32 s12, v2, 14
	v_readlane_b32 s14, v3, 14
	v_cvt_pk_bf16_f32 v20, v4, v5
	v_cvt_pk_bf16_f32 v21, v6, v7
	global_store_dwordx2 v1, v[20:21], s[4:5]
	s_add_u32 s4, s4, 0x8000
	s_addc_u32 s5, s5, 0
	v_add_f32_e32 v13, s12, v12
	v_max_f32_e64 v14, s14, s14
	v_max_f32_e32 v15, v13, v14
	v_sub_f32_e32 v13, v13, v15
	v_sub_f32_e32 v14, s14, v15
	v_mul_f32_e32 v14, 0x3fb8aa3b, v14
	v_mul_f32_e32 v13, 0x3fb8aa3b, v13
	v_exp_f32_e32 v16, v14
	v_exp_f32_e32 v18, v13
	s_waitcnt vmcnt(42)
	v_lshlrev_b32_e32 v24, 16, v128
	v_and_b32_e32 v25, 0xffff0000, v128
	v_lshlrev_b32_e32 v26, 16, v129
	v_and_b32_e32 v27, 0xffff0000, v129
	global_load_dwordx2 v[128:129], v1, s[2:3]
	s_add_u32 s2, s2, 0x8000
	s_addc_u32 s3, s3, 0
	v_pk_mul_f32 v[24:25], v[16:17], v[24:25] op_sel_hi:[0,1]
	v_pk_mul_f32 v[26:27], v[16:17], v[26:27] op_sel_hi:[0,1]
	v_pk_fma_f32 v[4:5], v[4:5], v[18:19], v[24:25] op_sel_hi:[1,0,1]
	v_pk_fma_f32 v[6:7], v[6:7], v[18:19], v[26:27] op_sel_hi:[1,0,1]
	v_mov_b32_e32 v12, v15
	v_readlane_b32 s12, v2, 15
	v_readlane_b32 s14, v3, 15
	v_cvt_pk_bf16_f32 v20, v4, v5
	v_cvt_pk_bf16_f32 v21, v6, v7
	global_store_dwordx2 v1, v[20:21], s[4:5]
	s_add_u32 s4, s4, 0x8000
	s_addc_u32 s5, s5, 0
	v_add_f32_e32 v13, s12, v12
	v_max_f32_e64 v14, s14, s14
	v_max_f32_e32 v15, v13, v14
	v_sub_f32_e32 v13, v13, v15
	v_sub_f32_e32 v14, s14, v15
	v_mul_f32_e32 v14, 0x3fb8aa3b, v14
	v_mul_f32_e32 v13, 0x3fb8aa3b, v13
	v_exp_f32_e32 v16, v14
	v_exp_f32_e32 v18, v13
	s_waitcnt vmcnt(43)
	v_lshlrev_b32_e32 v24, 16, v130
	v_and_b32_e32 v25, 0xffff0000, v130
	v_lshlrev_b32_e32 v26, 16, v131
	v_and_b32_e32 v27, 0xffff0000, v131
	global_load_dwordx2 v[130:131], v1, s[2:3]
	s_add_u32 s2, s2, 0x8000
	s_addc_u32 s3, s3, 0
	v_pk_mul_f32 v[24:25], v[16:17], v[24:25] op_sel_hi:[0,1]
	v_pk_mul_f32 v[26:27], v[16:17], v[26:27] op_sel_hi:[0,1]
	v_pk_fma_f32 v[4:5], v[4:5], v[18:19], v[24:25] op_sel_hi:[1,0,1]
	v_pk_fma_f32 v[6:7], v[6:7], v[18:19], v[26:27] op_sel_hi:[1,0,1]
	v_mov_b32_e32 v12, v15
	v_readlane_b32 s12, v2, 16
	v_readlane_b32 s14, v3, 16
	v_cvt_pk_bf16_f32 v20, v4, v5
	v_cvt_pk_bf16_f32 v21, v6, v7
	global_store_dwordx2 v1, v[20:21], s[4:5]
	s_add_u32 s4, s4, 0x8000
	s_addc_u32 s5, s5, 0
	v_add_f32_e32 v13, s12, v12
	v_max_f32_e64 v14, s14, s14
	v_max_f32_e32 v15, v13, v14
	v_sub_f32_e32 v13, v13, v15
	v_sub_f32_e32 v14, s14, v15
	v_mul_f32_e32 v14, 0x3fb8aa3b, v14
	v_mul_f32_e32 v13, 0x3fb8aa3b, v13
	v_exp_f32_e32 v16, v14
	v_exp_f32_e32 v18, v13
	s_waitcnt vmcnt(44)
	v_lshlrev_b32_e32 v24, 16, v132
	v_and_b32_e32 v25, 0xffff0000, v132
	v_lshlrev_b32_e32 v26, 16, v133
	v_and_b32_e32 v27, 0xffff0000, v133
	global_load_dwordx2 v[132:133], v1, s[2:3]
	s_add_u32 s2, s2, 0x8000
	s_addc_u32 s3, s3, 0
	v_pk_mul_f32 v[24:25], v[16:17], v[24:25] op_sel_hi:[0,1]
	v_pk_mul_f32 v[26:27], v[16:17], v[26:27] op_sel_hi:[0,1]
	v_pk_fma_f32 v[4:5], v[4:5], v[18:19], v[24:25] op_sel_hi:[1,0,1]
	v_pk_fma_f32 v[6:7], v[6:7], v[18:19], v[26:27] op_sel_hi:[1,0,1]
	v_mov_b32_e32 v12, v15
	v_readlane_b32 s12, v2, 17
	v_readlane_b32 s14, v3, 17
	v_cvt_pk_bf16_f32 v20, v4, v5
	v_cvt_pk_bf16_f32 v21, v6, v7
	global_store_dwordx2 v1, v[20:21], s[4:5]
	s_add_u32 s4, s4, 0x8000
	s_addc_u32 s5, s5, 0
	v_add_f32_e32 v13, s12, v12
	v_max_f32_e64 v14, s14, s14
	v_max_f32_e32 v15, v13, v14
	v_sub_f32_e32 v13, v13, v15
	v_sub_f32_e32 v14, s14, v15
	v_mul_f32_e32 v14, 0x3fb8aa3b, v14
	v_mul_f32_e32 v13, 0x3fb8aa3b, v13
	v_exp_f32_e32 v16, v14
	v_exp_f32_e32 v18, v13
	s_waitcnt vmcnt(45)
	v_lshlrev_b32_e32 v24, 16, v134
	v_and_b32_e32 v25, 0xffff0000, v134
	v_lshlrev_b32_e32 v26, 16, v135
	v_and_b32_e32 v27, 0xffff0000, v135
	global_load_dwordx2 v[134:135], v1, s[2:3]
	s_add_u32 s2, s2, 0x8000
	s_addc_u32 s3, s3, 0
	v_pk_mul_f32 v[24:25], v[16:17], v[24:25] op_sel_hi:[0,1]
	v_pk_mul_f32 v[26:27], v[16:17], v[26:27] op_sel_hi:[0,1]
	v_pk_fma_f32 v[4:5], v[4:5], v[18:19], v[24:25] op_sel_hi:[1,0,1]
	v_pk_fma_f32 v[6:7], v[6:7], v[18:19], v[26:27] op_sel_hi:[1,0,1]
	v_mov_b32_e32 v12, v15
	v_readlane_b32 s12, v2, 18
	v_readlane_b32 s14, v3, 18
	v_cvt_pk_bf16_f32 v20, v4, v5
	v_cvt_pk_bf16_f32 v21, v6, v7
	global_store_dwordx2 v1, v[20:21], s[4:5]
	s_add_u32 s4, s4, 0x8000
	s_addc_u32 s5, s5, 0
	v_add_f32_e32 v13, s12, v12
	v_max_f32_e64 v14, s14, s14
	v_max_f32_e32 v15, v13, v14
	v_sub_f32_e32 v13, v13, v15
	v_sub_f32_e32 v14, s14, v15
	v_mul_f32_e32 v14, 0x3fb8aa3b, v14
	v_mul_f32_e32 v13, 0x3fb8aa3b, v13
	v_exp_f32_e32 v16, v14
	v_exp_f32_e32 v18, v13
	s_waitcnt vmcnt(46)
	v_lshlrev_b32_e32 v24, 16, v136
	v_and_b32_e32 v25, 0xffff0000, v136
	v_lshlrev_b32_e32 v26, 16, v137
	v_and_b32_e32 v27, 0xffff0000, v137
	global_load_dwordx2 v[136:137], v1, s[2:3]
	s_add_u32 s2, s2, 0x8000
	s_addc_u32 s3, s3, 0
	v_pk_mul_f32 v[24:25], v[16:17], v[24:25] op_sel_hi:[0,1]
	v_pk_mul_f32 v[26:27], v[16:17], v[26:27] op_sel_hi:[0,1]
	v_pk_fma_f32 v[4:5], v[4:5], v[18:19], v[24:25] op_sel_hi:[1,0,1]
	v_pk_fma_f32 v[6:7], v[6:7], v[18:19], v[26:27] op_sel_hi:[1,0,1]
	v_mov_b32_e32 v12, v15
	v_readlane_b32 s12, v2, 19
	v_readlane_b32 s14, v3, 19
	v_cvt_pk_bf16_f32 v20, v4, v5
	v_cvt_pk_bf16_f32 v21, v6, v7
	global_store_dwordx2 v1, v[20:21], s[4:5]
	s_add_u32 s4, s4, 0x8000
	s_addc_u32 s5, s5, 0
	v_add_f32_e32 v13, s12, v12
	v_max_f32_e64 v14, s14, s14
	v_max_f32_e32 v15, v13, v14
	v_sub_f32_e32 v13, v13, v15
	v_sub_f32_e32 v14, s14, v15
	v_mul_f32_e32 v14, 0x3fb8aa3b, v14
	v_mul_f32_e32 v13, 0x3fb8aa3b, v13
	v_exp_f32_e32 v16, v14
	v_exp_f32_e32 v18, v13
	s_waitcnt vmcnt(47)
	v_lshlrev_b32_e32 v24, 16, v138
	v_and_b32_e32 v25, 0xffff0000, v138
	v_lshlrev_b32_e32 v26, 16, v139
	v_and_b32_e32 v27, 0xffff0000, v139
	global_load_dwordx2 v[138:139], v1, s[2:3]
	s_add_u32 s2, s2, 0x8000
	s_addc_u32 s3, s3, 0
	v_pk_mul_f32 v[24:25], v[16:17], v[24:25] op_sel_hi:[0,1]
	v_pk_mul_f32 v[26:27], v[16:17], v[26:27] op_sel_hi:[0,1]
	v_pk_fma_f32 v[4:5], v[4:5], v[18:19], v[24:25] op_sel_hi:[1,0,1]
	v_pk_fma_f32 v[6:7], v[6:7], v[18:19], v[26:27] op_sel_hi:[1,0,1]
	v_mov_b32_e32 v12, v15
	v_readlane_b32 s12, v2, 20
	v_readlane_b32 s14, v3, 20
	v_cvt_pk_bf16_f32 v20, v4, v5
	v_cvt_pk_bf16_f32 v21, v6, v7
	global_store_dwordx2 v1, v[20:21], s[4:5]
	s_add_u32 s4, s4, 0x8000
	s_addc_u32 s5, s5, 0
	v_add_f32_e32 v13, s12, v12
	v_max_f32_e64 v14, s14, s14
	v_max_f32_e32 v15, v13, v14
	v_sub_f32_e32 v13, v13, v15
	v_sub_f32_e32 v14, s14, v15
	v_mul_f32_e32 v14, 0x3fb8aa3b, v14
	v_mul_f32_e32 v13, 0x3fb8aa3b, v13
	v_exp_f32_e32 v16, v14
	v_exp_f32_e32 v18, v13
	s_waitcnt vmcnt(48)
	v_lshlrev_b32_e32 v24, 16, v140
	v_and_b32_e32 v25, 0xffff0000, v140
	v_lshlrev_b32_e32 v26, 16, v141
	v_and_b32_e32 v27, 0xffff0000, v141
	global_load_dwordx2 v[140:141], v1, s[2:3]
	s_add_u32 s2, s2, 0x8000
	s_addc_u32 s3, s3, 0
	v_pk_mul_f32 v[24:25], v[16:17], v[24:25] op_sel_hi:[0,1]
	v_pk_mul_f32 v[26:27], v[16:17], v[26:27] op_sel_hi:[0,1]
	v_pk_fma_f32 v[4:5], v[4:5], v[18:19], v[24:25] op_sel_hi:[1,0,1]
	v_pk_fma_f32 v[6:7], v[6:7], v[18:19], v[26:27] op_sel_hi:[1,0,1]
	v_mov_b32_e32 v12, v15
	v_readlane_b32 s12, v2, 21
	v_readlane_b32 s14, v3, 21
	v_cvt_pk_bf16_f32 v20, v4, v5
	v_cvt_pk_bf16_f32 v21, v6, v7
	global_store_dwordx2 v1, v[20:21], s[4:5]
	s_add_u32 s4, s4, 0x8000
	s_addc_u32 s5, s5, 0
	v_add_f32_e32 v13, s12, v12
	v_max_f32_e64 v14, s14, s14
	v_max_f32_e32 v15, v13, v14
	v_sub_f32_e32 v13, v13, v15
	v_sub_f32_e32 v14, s14, v15
	v_mul_f32_e32 v14, 0x3fb8aa3b, v14
	v_mul_f32_e32 v13, 0x3fb8aa3b, v13
	v_exp_f32_e32 v16, v14
	v_exp_f32_e32 v18, v13
	s_waitcnt vmcnt(49)
	v_lshlrev_b32_e32 v24, 16, v142
	v_and_b32_e32 v25, 0xffff0000, v142
	v_lshlrev_b32_e32 v26, 16, v143
	v_and_b32_e32 v27, 0xffff0000, v143
	global_load_dwordx2 v[142:143], v1, s[2:3]
	s_add_u32 s2, s2, 0x8000
	s_addc_u32 s3, s3, 0
	v_pk_mul_f32 v[24:25], v[16:17], v[24:25] op_sel_hi:[0,1]
	v_pk_mul_f32 v[26:27], v[16:17], v[26:27] op_sel_hi:[0,1]
	v_pk_fma_f32 v[4:5], v[4:5], v[18:19], v[24:25] op_sel_hi:[1,0,1]
	v_pk_fma_f32 v[6:7], v[6:7], v[18:19], v[26:27] op_sel_hi:[1,0,1]
	v_mov_b32_e32 v12, v15
	v_readlane_b32 s12, v2, 22
	v_readlane_b32 s14, v3, 22
	v_cvt_pk_bf16_f32 v20, v4, v5
	v_cvt_pk_bf16_f32 v21, v6, v7
	global_store_dwordx2 v1, v[20:21], s[4:5]
	s_add_u32 s4, s4, 0x8000
	s_addc_u32 s5, s5, 0
	v_add_f32_e32 v13, s12, v12
	v_max_f32_e64 v14, s14, s14
	v_max_f32_e32 v15, v13, v14
	v_sub_f32_e32 v13, v13, v15
	v_sub_f32_e32 v14, s14, v15
	v_mul_f32_e32 v14, 0x3fb8aa3b, v14
	v_mul_f32_e32 v13, 0x3fb8aa3b, v13
	v_exp_f32_e32 v16, v14
	v_exp_f32_e32 v18, v13
	s_waitcnt vmcnt(50)
	v_lshlrev_b32_e32 v24, 16, v144
	v_and_b32_e32 v25, 0xffff0000, v144
	v_lshlrev_b32_e32 v26, 16, v145
	v_and_b32_e32 v27, 0xffff0000, v145
	global_load_dwordx2 v[144:145], v1, s[2:3]
	s_add_u32 s2, s2, 0x8000
	s_addc_u32 s3, s3, 0
	v_pk_mul_f32 v[24:25], v[16:17], v[24:25] op_sel_hi:[0,1]
	v_pk_mul_f32 v[26:27], v[16:17], v[26:27] op_sel_hi:[0,1]
	v_pk_fma_f32 v[4:5], v[4:5], v[18:19], v[24:25] op_sel_hi:[1,0,1]
	v_pk_fma_f32 v[6:7], v[6:7], v[18:19], v[26:27] op_sel_hi:[1,0,1]
	v_mov_b32_e32 v12, v15
	v_readlane_b32 s12, v2, 23
	v_readlane_b32 s14, v3, 23
	v_cvt_pk_bf16_f32 v20, v4, v5
	v_cvt_pk_bf16_f32 v21, v6, v7
	global_store_dwordx2 v1, v[20:21], s[4:5]
	s_add_u32 s4, s4, 0x8000
	s_addc_u32 s5, s5, 0
	v_add_f32_e32 v13, s12, v12
	v_max_f32_e64 v14, s14, s14
	v_max_f32_e32 v15, v13, v14
	v_sub_f32_e32 v13, v13, v15
	v_sub_f32_e32 v14, s14, v15
	v_mul_f32_e32 v14, 0x3fb8aa3b, v14
	v_mul_f32_e32 v13, 0x3fb8aa3b, v13
	v_exp_f32_e32 v16, v14
	v_exp_f32_e32 v18, v13
	s_waitcnt vmcnt(51)
	v_lshlrev_b32_e32 v24, 16, v146
	v_and_b32_e32 v25, 0xffff0000, v146
	v_lshlrev_b32_e32 v26, 16, v147
	v_and_b32_e32 v27, 0xffff0000, v147
	global_load_dwordx2 v[146:147], v1, s[2:3]
	s_add_u32 s2, s2, 0x8000
	s_addc_u32 s3, s3, 0
	v_pk_mul_f32 v[24:25], v[16:17], v[24:25] op_sel_hi:[0,1]
	v_pk_mul_f32 v[26:27], v[16:17], v[26:27] op_sel_hi:[0,1]
	v_pk_fma_f32 v[4:5], v[4:5], v[18:19], v[24:25] op_sel_hi:[1,0,1]
	v_pk_fma_f32 v[6:7], v[6:7], v[18:19], v[26:27] op_sel_hi:[1,0,1]
	v_mov_b32_e32 v12, v15
	v_readlane_b32 s12, v2, 24
	v_readlane_b32 s14, v3, 24
	v_cvt_pk_bf16_f32 v20, v4, v5
	v_cvt_pk_bf16_f32 v21, v6, v7
	global_store_dwordx2 v1, v[20:21], s[4:5]
	s_add_u32 s4, s4, 0x8000
	s_addc_u32 s5, s5, 0
	v_add_f32_e32 v13, s12, v12
	v_max_f32_e64 v14, s14, s14
	v_max_f32_e32 v15, v13, v14
	v_sub_f32_e32 v13, v13, v15
	v_sub_f32_e32 v14, s14, v15
	v_mul_f32_e32 v14, 0x3fb8aa3b, v14
	v_mul_f32_e32 v13, 0x3fb8aa3b, v13
	v_exp_f32_e32 v16, v14
	v_exp_f32_e32 v18, v13
	s_waitcnt vmcnt(52)
	v_lshlrev_b32_e32 v24, 16, v148
	v_and_b32_e32 v25, 0xffff0000, v148
	v_lshlrev_b32_e32 v26, 16, v149
	v_and_b32_e32 v27, 0xffff0000, v149
	global_load_dwordx2 v[148:149], v1, s[2:3]
	s_add_u32 s2, s2, 0x8000
	s_addc_u32 s3, s3, 0
	v_pk_mul_f32 v[24:25], v[16:17], v[24:25] op_sel_hi:[0,1]
	v_pk_mul_f32 v[26:27], v[16:17], v[26:27] op_sel_hi:[0,1]
	v_pk_fma_f32 v[4:5], v[4:5], v[18:19], v[24:25] op_sel_hi:[1,0,1]
	v_pk_fma_f32 v[6:7], v[6:7], v[18:19], v[26:27] op_sel_hi:[1,0,1]
	v_mov_b32_e32 v12, v15
	v_readlane_b32 s12, v2, 25
	v_readlane_b32 s14, v3, 25
	v_cvt_pk_bf16_f32 v20, v4, v5
	v_cvt_pk_bf16_f32 v21, v6, v7
	global_store_dwordx2 v1, v[20:21], s[4:5]
	s_add_u32 s4, s4, 0x8000
	s_addc_u32 s5, s5, 0
	v_add_f32_e32 v13, s12, v12
	v_max_f32_e64 v14, s14, s14
	v_max_f32_e32 v15, v13, v14
	v_sub_f32_e32 v13, v13, v15
	v_sub_f32_e32 v14, s14, v15
	v_mul_f32_e32 v14, 0x3fb8aa3b, v14
	v_mul_f32_e32 v13, 0x3fb8aa3b, v13
	v_exp_f32_e32 v16, v14
	v_exp_f32_e32 v18, v13
	s_waitcnt vmcnt(53)
	v_lshlrev_b32_e32 v24, 16, v150
	v_and_b32_e32 v25, 0xffff0000, v150
	v_lshlrev_b32_e32 v26, 16, v151
	v_and_b32_e32 v27, 0xffff0000, v151
	global_load_dwordx2 v[150:151], v1, s[2:3]
	s_add_u32 s2, s2, 0x8000
	s_addc_u32 s3, s3, 0
	v_pk_mul_f32 v[24:25], v[16:17], v[24:25] op_sel_hi:[0,1]
	v_pk_mul_f32 v[26:27], v[16:17], v[26:27] op_sel_hi:[0,1]
	v_pk_fma_f32 v[4:5], v[4:5], v[18:19], v[24:25] op_sel_hi:[1,0,1]
	v_pk_fma_f32 v[6:7], v[6:7], v[18:19], v[26:27] op_sel_hi:[1,0,1]
	v_mov_b32_e32 v12, v15
	v_readlane_b32 s12, v2, 26
	v_readlane_b32 s14, v3, 26
	v_cvt_pk_bf16_f32 v20, v4, v5
	v_cvt_pk_bf16_f32 v21, v6, v7
	global_store_dwordx2 v1, v[20:21], s[4:5]
	s_add_u32 s4, s4, 0x8000
	s_addc_u32 s5, s5, 0
	v_add_f32_e32 v13, s12, v12
	v_max_f32_e64 v14, s14, s14
	v_max_f32_e32 v15, v13, v14
	v_sub_f32_e32 v13, v13, v15
	v_sub_f32_e32 v14, s14, v15
	v_mul_f32_e32 v14, 0x3fb8aa3b, v14
	v_mul_f32_e32 v13, 0x3fb8aa3b, v13
	v_exp_f32_e32 v16, v14
	v_exp_f32_e32 v18, v13
	s_waitcnt vmcnt(54)
	v_lshlrev_b32_e32 v24, 16, v152
	v_and_b32_e32 v25, 0xffff0000, v152
	v_lshlrev_b32_e32 v26, 16, v153
	v_and_b32_e32 v27, 0xffff0000, v153
	global_load_dwordx2 v[152:153], v1, s[2:3]
	s_add_u32 s2, s2, 0x8000
	s_addc_u32 s3, s3, 0
	v_pk_mul_f32 v[24:25], v[16:17], v[24:25] op_sel_hi:[0,1]
	v_pk_mul_f32 v[26:27], v[16:17], v[26:27] op_sel_hi:[0,1]
	v_pk_fma_f32 v[4:5], v[4:5], v[18:19], v[24:25] op_sel_hi:[1,0,1]
	v_pk_fma_f32 v[6:7], v[6:7], v[18:19], v[26:27] op_sel_hi:[1,0,1]
	v_mov_b32_e32 v12, v15
	v_readlane_b32 s12, v2, 27
	v_readlane_b32 s14, v3, 27
	v_cvt_pk_bf16_f32 v20, v4, v5
	v_cvt_pk_bf16_f32 v21, v6, v7
	global_store_dwordx2 v1, v[20:21], s[4:5]
	s_add_u32 s4, s4, 0x8000
	s_addc_u32 s5, s5, 0
	v_add_f32_e32 v13, s12, v12
	v_max_f32_e64 v14, s14, s14
	v_max_f32_e32 v15, v13, v14
	v_sub_f32_e32 v13, v13, v15
	v_sub_f32_e32 v14, s14, v15
	v_mul_f32_e32 v14, 0x3fb8aa3b, v14
	v_mul_f32_e32 v13, 0x3fb8aa3b, v13
	v_exp_f32_e32 v16, v14
	v_exp_f32_e32 v18, v13
	s_waitcnt vmcnt(55)
	v_lshlrev_b32_e32 v24, 16, v154
	v_and_b32_e32 v25, 0xffff0000, v154
	v_lshlrev_b32_e32 v26, 16, v155
	v_and_b32_e32 v27, 0xffff0000, v155
	global_load_dwordx2 v[154:155], v1, s[2:3]
	s_add_u32 s2, s2, 0x8000
	s_addc_u32 s3, s3, 0
	v_pk_mul_f32 v[24:25], v[16:17], v[24:25] op_sel_hi:[0,1]
	v_pk_mul_f32 v[26:27], v[16:17], v[26:27] op_sel_hi:[0,1]
	v_pk_fma_f32 v[4:5], v[4:5], v[18:19], v[24:25] op_sel_hi:[1,0,1]
	v_pk_fma_f32 v[6:7], v[6:7], v[18:19], v[26:27] op_sel_hi:[1,0,1]
	v_mov_b32_e32 v12, v15
	v_readlane_b32 s12, v2, 28
	v_readlane_b32 s14, v3, 28
	v_cvt_pk_bf16_f32 v20, v4, v5
	v_cvt_pk_bf16_f32 v21, v6, v7
	global_store_dwordx2 v1, v[20:21], s[4:5]
	s_add_u32 s4, s4, 0x8000
	s_addc_u32 s5, s5, 0
	v_add_f32_e32 v13, s12, v12
	v_max_f32_e64 v14, s14, s14
	v_max_f32_e32 v15, v13, v14
	v_sub_f32_e32 v13, v13, v15
	v_sub_f32_e32 v14, s14, v15
	v_mul_f32_e32 v14, 0x3fb8aa3b, v14
	v_mul_f32_e32 v13, 0x3fb8aa3b, v13
	v_exp_f32_e32 v16, v14
	v_exp_f32_e32 v18, v13
	s_waitcnt vmcnt(55)
	v_lshlrev_b32_e32 v24, 16, v100
	v_and_b32_e32 v25, 0xffff0000, v100
	v_lshlrev_b32_e32 v26, 16, v101
	v_and_b32_e32 v27, 0xffff0000, v101
	global_load_dwordx2 v[100:101], v1, s[2:3]
	s_add_u32 s2, s2, 0x8000
	s_addc_u32 s3, s3, 0
	v_pk_mul_f32 v[24:25], v[16:17], v[24:25] op_sel_hi:[0,1]
	v_pk_mul_f32 v[26:27], v[16:17], v[26:27] op_sel_hi:[0,1]
	v_pk_fma_f32 v[4:5], v[4:5], v[18:19], v[24:25] op_sel_hi:[1,0,1]
	v_pk_fma_f32 v[6:7], v[6:7], v[18:19], v[26:27] op_sel_hi:[1,0,1]
	v_mov_b32_e32 v12, v15
	v_readlane_b32 s12, v2, 29
	v_readlane_b32 s14, v3, 29
	v_cvt_pk_bf16_f32 v20, v4, v5
	v_cvt_pk_bf16_f32 v21, v6, v7
	global_store_dwordx2 v1, v[20:21], s[4:5]
	s_add_u32 s4, s4, 0x8000
	s_addc_u32 s5, s5, 0
	v_add_f32_e32 v13, s12, v12
	v_max_f32_e64 v14, s14, s14
	v_max_f32_e32 v15, v13, v14
	v_sub_f32_e32 v13, v13, v15
	v_sub_f32_e32 v14, s14, v15
	v_mul_f32_e32 v14, 0x3fb8aa3b, v14
	v_mul_f32_e32 v13, 0x3fb8aa3b, v13
	v_exp_f32_e32 v16, v14
	v_exp_f32_e32 v18, v13
	s_waitcnt vmcnt(55)
	v_lshlrev_b32_e32 v24, 16, v102
	v_and_b32_e32 v25, 0xffff0000, v102
	v_lshlrev_b32_e32 v26, 16, v103
	v_and_b32_e32 v27, 0xffff0000, v103
	global_load_dwordx2 v[102:103], v1, s[2:3]
	s_add_u32 s2, s2, 0x8000
	s_addc_u32 s3, s3, 0
	v_pk_mul_f32 v[24:25], v[16:17], v[24:25] op_sel_hi:[0,1]
	v_pk_mul_f32 v[26:27], v[16:17], v[26:27] op_sel_hi:[0,1]
	v_pk_fma_f32 v[4:5], v[4:5], v[18:19], v[24:25] op_sel_hi:[1,0,1]
	v_pk_fma_f32 v[6:7], v[6:7], v[18:19], v[26:27] op_sel_hi:[1,0,1]
	v_mov_b32_e32 v12, v15
	v_readlane_b32 s12, v2, 30
	v_readlane_b32 s14, v3, 30
	v_cvt_pk_bf16_f32 v20, v4, v5
	v_cvt_pk_bf16_f32 v21, v6, v7
	global_store_dwordx2 v1, v[20:21], s[4:5]
	s_add_u32 s4, s4, 0x8000
	s_addc_u32 s5, s5, 0
	v_add_f32_e32 v13, s12, v12
	v_max_f32_e64 v14, s14, s14
	v_max_f32_e32 v15, v13, v14
	v_sub_f32_e32 v13, v13, v15
	v_sub_f32_e32 v14, s14, v15
	v_mul_f32_e32 v14, 0x3fb8aa3b, v14
	v_mul_f32_e32 v13, 0x3fb8aa3b, v13
	v_exp_f32_e32 v16, v14
	v_exp_f32_e32 v18, v13
	s_waitcnt vmcnt(55)
	v_lshlrev_b32_e32 v24, 16, v104
	v_and_b32_e32 v25, 0xffff0000, v104
	v_lshlrev_b32_e32 v26, 16, v105
	v_and_b32_e32 v27, 0xffff0000, v105
	global_load_dwordx2 v[104:105], v1, s[2:3]
	s_add_u32 s2, s2, 0x8000
	s_addc_u32 s3, s3, 0
	v_pk_mul_f32 v[24:25], v[16:17], v[24:25] op_sel_hi:[0,1]
	v_pk_mul_f32 v[26:27], v[16:17], v[26:27] op_sel_hi:[0,1]
	v_pk_fma_f32 v[4:5], v[4:5], v[18:19], v[24:25] op_sel_hi:[1,0,1]
	v_pk_fma_f32 v[6:7], v[6:7], v[18:19], v[26:27] op_sel_hi:[1,0,1]
	v_mov_b32_e32 v12, v15
	v_readlane_b32 s12, v2, 31
	v_readlane_b32 s14, v3, 31
	v_cvt_pk_bf16_f32 v20, v4, v5
	v_cvt_pk_bf16_f32 v21, v6, v7
	global_store_dwordx2 v1, v[20:21], s[4:5]
	s_add_u32 s4, s4, 0x8000
	s_addc_u32 s5, s5, 0
	v_add_f32_e32 v13, s12, v12
	v_max_f32_e64 v14, s14, s14
	v_max_f32_e32 v15, v13, v14
	v_sub_f32_e32 v13, v13, v15
	v_sub_f32_e32 v14, s14, v15
	v_mul_f32_e32 v14, 0x3fb8aa3b, v14
	v_mul_f32_e32 v13, 0x3fb8aa3b, v13
	v_exp_f32_e32 v16, v14
	v_exp_f32_e32 v18, v13
	s_waitcnt vmcnt(55)
	v_lshlrev_b32_e32 v24, 16, v106
	v_and_b32_e32 v25, 0xffff0000, v106
	v_lshlrev_b32_e32 v26, 16, v107
	v_and_b32_e32 v27, 0xffff0000, v107
	global_load_dwordx2 v[106:107], v1, s[2:3]
	s_add_u32 s2, s2, 0x8000
	s_addc_u32 s3, s3, 0
	v_pk_mul_f32 v[24:25], v[16:17], v[24:25] op_sel_hi:[0,1]
	v_pk_mul_f32 v[26:27], v[16:17], v[26:27] op_sel_hi:[0,1]
	v_pk_fma_f32 v[4:5], v[4:5], v[18:19], v[24:25] op_sel_hi:[1,0,1]
	v_pk_fma_f32 v[6:7], v[6:7], v[18:19], v[26:27] op_sel_hi:[1,0,1]
	v_mov_b32_e32 v12, v15
	v_readlane_b32 s12, v2, 32
	v_readlane_b32 s14, v3, 32
	v_cvt_pk_bf16_f32 v20, v4, v5
	v_cvt_pk_bf16_f32 v21, v6, v7
	global_store_dwordx2 v1, v[20:21], s[4:5]
	s_add_u32 s4, s4, 0x8000
	s_addc_u32 s5, s5, 0
	v_add_f32_e32 v13, s12, v12
	v_max_f32_e64 v14, s14, s14
	v_max_f32_e32 v15, v13, v14
	v_sub_f32_e32 v13, v13, v15
	v_sub_f32_e32 v14, s14, v15
	v_mul_f32_e32 v14, 0x3fb8aa3b, v14
	v_mul_f32_e32 v13, 0x3fb8aa3b, v13
	v_exp_f32_e32 v16, v14
	v_exp_f32_e32 v18, v13
	s_waitcnt vmcnt(55)
	v_lshlrev_b32_e32 v24, 16, v108
	v_and_b32_e32 v25, 0xffff0000, v108
	v_lshlrev_b32_e32 v26, 16, v109
	v_and_b32_e32 v27, 0xffff0000, v109
	global_load_dwordx2 v[108:109], v1, s[2:3]
	s_add_u32 s2, s2, 0x8000
	s_addc_u32 s3, s3, 0
	v_pk_mul_f32 v[24:25], v[16:17], v[24:25] op_sel_hi:[0,1]
	v_pk_mul_f32 v[26:27], v[16:17], v[26:27] op_sel_hi:[0,1]
	v_pk_fma_f32 v[4:5], v[4:5], v[18:19], v[24:25] op_sel_hi:[1,0,1]
	v_pk_fma_f32 v[6:7], v[6:7], v[18:19], v[26:27] op_sel_hi:[1,0,1]
	v_mov_b32_e32 v12, v15
	v_readlane_b32 s12, v2, 33
	v_readlane_b32 s14, v3, 33
	v_cvt_pk_bf16_f32 v20, v4, v5
	v_cvt_pk_bf16_f32 v21, v6, v7
	global_store_dwordx2 v1, v[20:21], s[4:5]
	s_add_u32 s4, s4, 0x8000
	s_addc_u32 s5, s5, 0
	v_add_f32_e32 v13, s12, v12
	v_max_f32_e64 v14, s14, s14
	v_max_f32_e32 v15, v13, v14
	v_sub_f32_e32 v13, v13, v15
	v_sub_f32_e32 v14, s14, v15
	v_mul_f32_e32 v14, 0x3fb8aa3b, v14
	v_mul_f32_e32 v13, 0x3fb8aa3b, v13
	v_exp_f32_e32 v16, v14
	v_exp_f32_e32 v18, v13
	s_waitcnt vmcnt(55)
	v_lshlrev_b32_e32 v24, 16, v110
	v_and_b32_e32 v25, 0xffff0000, v110
	v_lshlrev_b32_e32 v26, 16, v111
	v_and_b32_e32 v27, 0xffff0000, v111
	global_load_dwordx2 v[110:111], v1, s[2:3]
	s_add_u32 s2, s2, 0x8000
	s_addc_u32 s3, s3, 0
	v_pk_mul_f32 v[24:25], v[16:17], v[24:25] op_sel_hi:[0,1]
	v_pk_mul_f32 v[26:27], v[16:17], v[26:27] op_sel_hi:[0,1]
	v_pk_fma_f32 v[4:5], v[4:5], v[18:19], v[24:25] op_sel_hi:[1,0,1]
	v_pk_fma_f32 v[6:7], v[6:7], v[18:19], v[26:27] op_sel_hi:[1,0,1]
	v_mov_b32_e32 v12, v15
	v_readlane_b32 s12, v2, 34
	v_readlane_b32 s14, v3, 34
	v_cvt_pk_bf16_f32 v20, v4, v5
	v_cvt_pk_bf16_f32 v21, v6, v7
	global_store_dwordx2 v1, v[20:21], s[4:5]
	s_add_u32 s4, s4, 0x8000
	s_addc_u32 s5, s5, 0
	v_add_f32_e32 v13, s12, v12
	v_max_f32_e64 v14, s14, s14
	v_max_f32_e32 v15, v13, v14
	v_sub_f32_e32 v13, v13, v15
	v_sub_f32_e32 v14, s14, v15
	v_mul_f32_e32 v14, 0x3fb8aa3b, v14
	v_mul_f32_e32 v13, 0x3fb8aa3b, v13
	v_exp_f32_e32 v16, v14
	v_exp_f32_e32 v18, v13
	s_waitcnt vmcnt(55)
	v_lshlrev_b32_e32 v24, 16, v112
	v_and_b32_e32 v25, 0xffff0000, v112
	v_lshlrev_b32_e32 v26, 16, v113
	v_and_b32_e32 v27, 0xffff0000, v113
	global_load_dwordx2 v[112:113], v1, s[2:3]
	s_add_u32 s2, s2, 0x8000
	s_addc_u32 s3, s3, 0
	v_pk_mul_f32 v[24:25], v[16:17], v[24:25] op_sel_hi:[0,1]
	v_pk_mul_f32 v[26:27], v[16:17], v[26:27] op_sel_hi:[0,1]
	v_pk_fma_f32 v[4:5], v[4:5], v[18:19], v[24:25] op_sel_hi:[1,0,1]
	v_pk_fma_f32 v[6:7], v[6:7], v[18:19], v[26:27] op_sel_hi:[1,0,1]
	v_mov_b32_e32 v12, v15
	v_readlane_b32 s12, v2, 35
	v_readlane_b32 s14, v3, 35
	v_cvt_pk_bf16_f32 v20, v4, v5
	v_cvt_pk_bf16_f32 v21, v6, v7
	global_store_dwordx2 v1, v[20:21], s[4:5]
	s_add_u32 s4, s4, 0x8000
	s_addc_u32 s5, s5, 0
	v_add_f32_e32 v13, s12, v12
	v_max_f32_e64 v14, s14, s14
	v_max_f32_e32 v15, v13, v14
	v_sub_f32_e32 v13, v13, v15
	v_sub_f32_e32 v14, s14, v15
	v_mul_f32_e32 v14, 0x3fb8aa3b, v14
	v_mul_f32_e32 v13, 0x3fb8aa3b, v13
	v_exp_f32_e32 v16, v14
	v_exp_f32_e32 v18, v13
	s_waitcnt vmcnt(55)
	v_lshlrev_b32_e32 v24, 16, v114
	v_and_b32_e32 v25, 0xffff0000, v114
	v_lshlrev_b32_e32 v26, 16, v115
	v_and_b32_e32 v27, 0xffff0000, v115
	global_load_dwordx2 v[114:115], v1, s[2:3]
	s_add_u32 s2, s2, 0x8000
	s_addc_u32 s3, s3, 0
	v_pk_mul_f32 v[24:25], v[16:17], v[24:25] op_sel_hi:[0,1]
	v_pk_mul_f32 v[26:27], v[16:17], v[26:27] op_sel_hi:[0,1]
	v_pk_fma_f32 v[4:5], v[4:5], v[18:19], v[24:25] op_sel_hi:[1,0,1]
	v_pk_fma_f32 v[6:7], v[6:7], v[18:19], v[26:27] op_sel_hi:[1,0,1]
	v_mov_b32_e32 v12, v15
	v_readlane_b32 s12, v2, 36
	v_readlane_b32 s14, v3, 36
	v_cvt_pk_bf16_f32 v20, v4, v5
	v_cvt_pk_bf16_f32 v21, v6, v7
	global_store_dwordx2 v1, v[20:21], s[4:5]
	s_add_u32 s4, s4, 0x8000
	s_addc_u32 s5, s5, 0
	v_add_f32_e32 v13, s12, v12
	v_max_f32_e64 v14, s14, s14
	v_max_f32_e32 v15, v13, v14
	v_sub_f32_e32 v13, v13, v15
	v_sub_f32_e32 v14, s14, v15
	v_mul_f32_e32 v14, 0x3fb8aa3b, v14
	v_mul_f32_e32 v13, 0x3fb8aa3b, v13
	v_exp_f32_e32 v16, v14
	v_exp_f32_e32 v18, v13
	s_waitcnt vmcnt(55)
	v_lshlrev_b32_e32 v24, 16, v116
	v_and_b32_e32 v25, 0xffff0000, v116
	v_lshlrev_b32_e32 v26, 16, v117
	v_and_b32_e32 v27, 0xffff0000, v117
	v_pk_mul_f32 v[24:25], v[16:17], v[24:25] op_sel_hi:[0,1]
	v_pk_mul_f32 v[26:27], v[16:17], v[26:27] op_sel_hi:[0,1]
	v_pk_fma_f32 v[4:5], v[4:5], v[18:19], v[24:25] op_sel_hi:[1,0,1]
	v_pk_fma_f32 v[6:7], v[6:7], v[18:19], v[26:27] op_sel_hi:[1,0,1]
	v_mov_b32_e32 v12, v15
	v_readlane_b32 s12, v2, 37
	v_readlane_b32 s14, v3, 37
	v_cvt_pk_bf16_f32 v20, v4, v5
	v_cvt_pk_bf16_f32 v21, v6, v7
	global_store_dwordx2 v1, v[20:21], s[4:5]
	s_add_u32 s4, s4, 0x8000
	s_addc_u32 s5, s5, 0
	v_add_f32_e32 v13, s12, v12
	v_max_f32_e64 v14, s14, s14
	v_max_f32_e32 v15, v13, v14
	v_sub_f32_e32 v13, v13, v15
	v_sub_f32_e32 v14, s14, v15
	v_mul_f32_e32 v14, 0x3fb8aa3b, v14
	v_mul_f32_e32 v13, 0x3fb8aa3b, v13
	v_exp_f32_e32 v16, v14
	v_exp_f32_e32 v18, v13
	s_waitcnt vmcnt(54)
	v_lshlrev_b32_e32 v24, 16, v118
	v_and_b32_e32 v25, 0xffff0000, v118
	v_lshlrev_b32_e32 v26, 16, v119
	v_and_b32_e32 v27, 0xffff0000, v119
	v_pk_mul_f32 v[24:25], v[16:17], v[24:25] op_sel_hi:[0,1]
	v_pk_mul_f32 v[26:27], v[16:17], v[26:27] op_sel_hi:[0,1]
	v_pk_fma_f32 v[4:5], v[4:5], v[18:19], v[24:25] op_sel_hi:[1,0,1]
	v_pk_fma_f32 v[6:7], v[6:7], v[18:19], v[26:27] op_sel_hi:[1,0,1]
	v_mov_b32_e32 v12, v15
	v_readlane_b32 s12, v2, 38
	v_readlane_b32 s14, v3, 38
	v_cvt_pk_bf16_f32 v20, v4, v5
	v_cvt_pk_bf16_f32 v21, v6, v7
	global_store_dwordx2 v1, v[20:21], s[4:5]
	s_add_u32 s4, s4, 0x8000
	s_addc_u32 s5, s5, 0
	v_add_f32_e32 v13, s12, v12
	v_max_f32_e64 v14, s14, s14
	v_max_f32_e32 v15, v13, v14
	v_sub_f32_e32 v13, v13, v15
	v_sub_f32_e32 v14, s14, v15
	v_mul_f32_e32 v14, 0x3fb8aa3b, v14
	v_mul_f32_e32 v13, 0x3fb8aa3b, v13
	v_exp_f32_e32 v16, v14
	v_exp_f32_e32 v18, v13
	s_waitcnt vmcnt(53)
	v_lshlrev_b32_e32 v24, 16, v120
	v_and_b32_e32 v25, 0xffff0000, v120
	v_lshlrev_b32_e32 v26, 16, v121
	v_and_b32_e32 v27, 0xffff0000, v121
	v_pk_mul_f32 v[24:25], v[16:17], v[24:25] op_sel_hi:[0,1]
	v_pk_mul_f32 v[26:27], v[16:17], v[26:27] op_sel_hi:[0,1]
	v_pk_fma_f32 v[4:5], v[4:5], v[18:19], v[24:25] op_sel_hi:[1,0,1]
	v_pk_fma_f32 v[6:7], v[6:7], v[18:19], v[26:27] op_sel_hi:[1,0,1]
	v_mov_b32_e32 v12, v15
	v_readlane_b32 s12, v2, 39
	v_readlane_b32 s14, v3, 39
	v_cvt_pk_bf16_f32 v20, v4, v5
	v_cvt_pk_bf16_f32 v21, v6, v7
	global_store_dwordx2 v1, v[20:21], s[4:5]
	s_add_u32 s4, s4, 0x8000
	s_addc_u32 s5, s5, 0
	v_add_f32_e32 v13, s12, v12
	v_max_f32_e64 v14, s14, s14
	v_max_f32_e32 v15, v13, v14
	v_sub_f32_e32 v13, v13, v15
	v_sub_f32_e32 v14, s14, v15
	v_mul_f32_e32 v14, 0x3fb8aa3b, v14
	v_mul_f32_e32 v13, 0x3fb8aa3b, v13
	v_exp_f32_e32 v16, v14
	v_exp_f32_e32 v18, v13
	s_waitcnt vmcnt(52)
	v_lshlrev_b32_e32 v24, 16, v122
	v_and_b32_e32 v25, 0xffff0000, v122
	v_lshlrev_b32_e32 v26, 16, v123
	v_and_b32_e32 v27, 0xffff0000, v123
	v_pk_mul_f32 v[24:25], v[16:17], v[24:25] op_sel_hi:[0,1]
	v_pk_mul_f32 v[26:27], v[16:17], v[26:27] op_sel_hi:[0,1]
	v_pk_fma_f32 v[4:5], v[4:5], v[18:19], v[24:25] op_sel_hi:[1,0,1]
	v_pk_fma_f32 v[6:7], v[6:7], v[18:19], v[26:27] op_sel_hi:[1,0,1]
	v_mov_b32_e32 v12, v15
	v_readlane_b32 s12, v2, 40
	v_readlane_b32 s14, v3, 40
	v_cvt_pk_bf16_f32 v20, v4, v5
	v_cvt_pk_bf16_f32 v21, v6, v7
	global_store_dwordx2 v1, v[20:21], s[4:5]
	s_add_u32 s4, s4, 0x8000
	s_addc_u32 s5, s5, 0
	v_add_f32_e32 v13, s12, v12
	v_max_f32_e64 v14, s14, s14
	v_max_f32_e32 v15, v13, v14
	v_sub_f32_e32 v13, v13, v15
	v_sub_f32_e32 v14, s14, v15
	v_mul_f32_e32 v14, 0x3fb8aa3b, v14
	v_mul_f32_e32 v13, 0x3fb8aa3b, v13
	v_exp_f32_e32 v16, v14
	v_exp_f32_e32 v18, v13
	s_waitcnt vmcnt(51)
	v_lshlrev_b32_e32 v24, 16, v124
	v_and_b32_e32 v25, 0xffff0000, v124
	v_lshlrev_b32_e32 v26, 16, v125
	v_and_b32_e32 v27, 0xffff0000, v125
	v_pk_mul_f32 v[24:25], v[16:17], v[24:25] op_sel_hi:[0,1]
	v_pk_mul_f32 v[26:27], v[16:17], v[26:27] op_sel_hi:[0,1]
	v_pk_fma_f32 v[4:5], v[4:5], v[18:19], v[24:25] op_sel_hi:[1,0,1]
	v_pk_fma_f32 v[6:7], v[6:7], v[18:19], v[26:27] op_sel_hi:[1,0,1]
	v_mov_b32_e32 v12, v15
	v_readlane_b32 s12, v2, 41
	v_readlane_b32 s14, v3, 41
	v_cvt_pk_bf16_f32 v20, v4, v5
	v_cvt_pk_bf16_f32 v21, v6, v7
	global_store_dwordx2 v1, v[20:21], s[4:5]
	s_add_u32 s4, s4, 0x8000
	s_addc_u32 s5, s5, 0
	v_add_f32_e32 v13, s12, v12
	v_max_f32_e64 v14, s14, s14
	v_max_f32_e32 v15, v13, v14
	v_sub_f32_e32 v13, v13, v15
	v_sub_f32_e32 v14, s14, v15
	v_mul_f32_e32 v14, 0x3fb8aa3b, v14
	v_mul_f32_e32 v13, 0x3fb8aa3b, v13
	v_exp_f32_e32 v16, v14
	v_exp_f32_e32 v18, v13
	s_waitcnt vmcnt(50)
	v_lshlrev_b32_e32 v24, 16, v126
	v_and_b32_e32 v25, 0xffff0000, v126
	v_lshlrev_b32_e32 v26, 16, v127
	v_and_b32_e32 v27, 0xffff0000, v127
	v_pk_mul_f32 v[24:25], v[16:17], v[24:25] op_sel_hi:[0,1]
	v_pk_mul_f32 v[26:27], v[16:17], v[26:27] op_sel_hi:[0,1]
	v_pk_fma_f32 v[4:5], v[4:5], v[18:19], v[24:25] op_sel_hi:[1,0,1]
	v_pk_fma_f32 v[6:7], v[6:7], v[18:19], v[26:27] op_sel_hi:[1,0,1]
	v_mov_b32_e32 v12, v15
	v_readlane_b32 s12, v2, 42
	v_readlane_b32 s14, v3, 42
	v_cvt_pk_bf16_f32 v20, v4, v5
	v_cvt_pk_bf16_f32 v21, v6, v7
	global_store_dwordx2 v1, v[20:21], s[4:5]
	s_add_u32 s4, s4, 0x8000
	s_addc_u32 s5, s5, 0
	v_add_f32_e32 v13, s12, v12
	v_max_f32_e64 v14, s14, s14
	v_max_f32_e32 v15, v13, v14
	v_sub_f32_e32 v13, v13, v15
	v_sub_f32_e32 v14, s14, v15
	v_mul_f32_e32 v14, 0x3fb8aa3b, v14
	v_mul_f32_e32 v13, 0x3fb8aa3b, v13
	v_exp_f32_e32 v16, v14
	v_exp_f32_e32 v18, v13
	s_waitcnt vmcnt(49)
	v_lshlrev_b32_e32 v24, 16, v128
	v_and_b32_e32 v25, 0xffff0000, v128
	v_lshlrev_b32_e32 v26, 16, v129
	v_and_b32_e32 v27, 0xffff0000, v129
	v_pk_mul_f32 v[24:25], v[16:17], v[24:25] op_sel_hi:[0,1]
	v_pk_mul_f32 v[26:27], v[16:17], v[26:27] op_sel_hi:[0,1]
	v_pk_fma_f32 v[4:5], v[4:5], v[18:19], v[24:25] op_sel_hi:[1,0,1]
	v_pk_fma_f32 v[6:7], v[6:7], v[18:19], v[26:27] op_sel_hi:[1,0,1]
	v_mov_b32_e32 v12, v15
	v_readlane_b32 s12, v2, 43
	v_readlane_b32 s14, v3, 43
	v_cvt_pk_bf16_f32 v20, v4, v5
	v_cvt_pk_bf16_f32 v21, v6, v7
	global_store_dwordx2 v1, v[20:21], s[4:5]
	s_add_u32 s4, s4, 0x8000
	s_addc_u32 s5, s5, 0
	v_add_f32_e32 v13, s12, v12
	v_max_f32_e64 v14, s14, s14
	v_max_f32_e32 v15, v13, v14
	v_sub_f32_e32 v13, v13, v15
	v_sub_f32_e32 v14, s14, v15
	v_mul_f32_e32 v14, 0x3fb8aa3b, v14
	v_mul_f32_e32 v13, 0x3fb8aa3b, v13
	v_exp_f32_e32 v16, v14
	v_exp_f32_e32 v18, v13
	s_waitcnt vmcnt(48)
	v_lshlrev_b32_e32 v24, 16, v130
	v_and_b32_e32 v25, 0xffff0000, v130
	v_lshlrev_b32_e32 v26, 16, v131
	v_and_b32_e32 v27, 0xffff0000, v131
	v_pk_mul_f32 v[24:25], v[16:17], v[24:25] op_sel_hi:[0,1]
	v_pk_mul_f32 v[26:27], v[16:17], v[26:27] op_sel_hi:[0,1]
	v_pk_fma_f32 v[4:5], v[4:5], v[18:19], v[24:25] op_sel_hi:[1,0,1]
	v_pk_fma_f32 v[6:7], v[6:7], v[18:19], v[26:27] op_sel_hi:[1,0,1]
	v_mov_b32_e32 v12, v15
	v_readlane_b32 s12, v2, 44
	v_readlane_b32 s14, v3, 44
	v_cvt_pk_bf16_f32 v20, v4, v5
	v_cvt_pk_bf16_f32 v21, v6, v7
	global_store_dwordx2 v1, v[20:21], s[4:5]
	s_add_u32 s4, s4, 0x8000
	s_addc_u32 s5, s5, 0
	v_add_f32_e32 v13, s12, v12
	v_max_f32_e64 v14, s14, s14
	v_max_f32_e32 v15, v13, v14
	v_sub_f32_e32 v13, v13, v15
	v_sub_f32_e32 v14, s14, v15
	v_mul_f32_e32 v14, 0x3fb8aa3b, v14
	v_mul_f32_e32 v13, 0x3fb8aa3b, v13
	v_exp_f32_e32 v16, v14
	v_exp_f32_e32 v18, v13
	s_waitcnt vmcnt(47)
	v_lshlrev_b32_e32 v24, 16, v132
	v_and_b32_e32 v25, 0xffff0000, v132
	v_lshlrev_b32_e32 v26, 16, v133
	v_and_b32_e32 v27, 0xffff0000, v133
	v_pk_mul_f32 v[24:25], v[16:17], v[24:25] op_sel_hi:[0,1]
	v_pk_mul_f32 v[26:27], v[16:17], v[26:27] op_sel_hi:[0,1]
	v_pk_fma_f32 v[4:5], v[4:5], v[18:19], v[24:25] op_sel_hi:[1,0,1]
	v_pk_fma_f32 v[6:7], v[6:7], v[18:19], v[26:27] op_sel_hi:[1,0,1]
	v_mov_b32_e32 v12, v15
	v_readlane_b32 s12, v2, 45
	v_readlane_b32 s14, v3, 45
	v_cvt_pk_bf16_f32 v20, v4, v5
	v_cvt_pk_bf16_f32 v21, v6, v7
	global_store_dwordx2 v1, v[20:21], s[4:5]
	s_add_u32 s4, s4, 0x8000
	s_addc_u32 s5, s5, 0
	v_add_f32_e32 v13, s12, v12
	v_max_f32_e64 v14, s14, s14
	v_max_f32_e32 v15, v13, v14
	v_sub_f32_e32 v13, v13, v15
	v_sub_f32_e32 v14, s14, v15
	v_mul_f32_e32 v14, 0x3fb8aa3b, v14
	v_mul_f32_e32 v13, 0x3fb8aa3b, v13
	v_exp_f32_e32 v16, v14
	v_exp_f32_e32 v18, v13
	s_waitcnt vmcnt(46)
	v_lshlrev_b32_e32 v24, 16, v134
	v_and_b32_e32 v25, 0xffff0000, v134
	v_lshlrev_b32_e32 v26, 16, v135
	v_and_b32_e32 v27, 0xffff0000, v135
	v_pk_mul_f32 v[24:25], v[16:17], v[24:25] op_sel_hi:[0,1]
	v_pk_mul_f32 v[26:27], v[16:17], v[26:27] op_sel_hi:[0,1]
	v_pk_fma_f32 v[4:5], v[4:5], v[18:19], v[24:25] op_sel_hi:[1,0,1]
	v_pk_fma_f32 v[6:7], v[6:7], v[18:19], v[26:27] op_sel_hi:[1,0,1]
	v_mov_b32_e32 v12, v15
	v_readlane_b32 s12, v2, 46
	v_readlane_b32 s14, v3, 46
	v_cvt_pk_bf16_f32 v20, v4, v5
	v_cvt_pk_bf16_f32 v21, v6, v7
	global_store_dwordx2 v1, v[20:21], s[4:5]
	s_add_u32 s4, s4, 0x8000
	s_addc_u32 s5, s5, 0
	v_add_f32_e32 v13, s12, v12
	v_max_f32_e64 v14, s14, s14
	v_max_f32_e32 v15, v13, v14
	v_sub_f32_e32 v13, v13, v15
	v_sub_f32_e32 v14, s14, v15
	v_mul_f32_e32 v14, 0x3fb8aa3b, v14
	v_mul_f32_e32 v13, 0x3fb8aa3b, v13
	v_exp_f32_e32 v16, v14
	v_exp_f32_e32 v18, v13
	s_waitcnt vmcnt(45)
	v_lshlrev_b32_e32 v24, 16, v136
	v_and_b32_e32 v25, 0xffff0000, v136
	v_lshlrev_b32_e32 v26, 16, v137
	v_and_b32_e32 v27, 0xffff0000, v137
	v_pk_mul_f32 v[24:25], v[16:17], v[24:25] op_sel_hi:[0,1]
	v_pk_mul_f32 v[26:27], v[16:17], v[26:27] op_sel_hi:[0,1]
	v_pk_fma_f32 v[4:5], v[4:5], v[18:19], v[24:25] op_sel_hi:[1,0,1]
	v_pk_fma_f32 v[6:7], v[6:7], v[18:19], v[26:27] op_sel_hi:[1,0,1]
	v_mov_b32_e32 v12, v15
	v_readlane_b32 s12, v2, 47
	v_readlane_b32 s14, v3, 47
	v_cvt_pk_bf16_f32 v20, v4, v5
	v_cvt_pk_bf16_f32 v21, v6, v7
	global_store_dwordx2 v1, v[20:21], s[4:5]
	s_add_u32 s4, s4, 0x8000
	s_addc_u32 s5, s5, 0
	v_add_f32_e32 v13, s12, v12
	v_max_f32_e64 v14, s14, s14
	v_max_f32_e32 v15, v13, v14
	v_sub_f32_e32 v13, v13, v15
	v_sub_f32_e32 v14, s14, v15
	v_mul_f32_e32 v14, 0x3fb8aa3b, v14
	v_mul_f32_e32 v13, 0x3fb8aa3b, v13
	v_exp_f32_e32 v16, v14
	v_exp_f32_e32 v18, v13
	s_waitcnt vmcnt(44)
	v_lshlrev_b32_e32 v24, 16, v138
	v_and_b32_e32 v25, 0xffff0000, v138
	v_lshlrev_b32_e32 v26, 16, v139
	v_and_b32_e32 v27, 0xffff0000, v139
	v_pk_mul_f32 v[24:25], v[16:17], v[24:25] op_sel_hi:[0,1]
	v_pk_mul_f32 v[26:27], v[16:17], v[26:27] op_sel_hi:[0,1]
	v_pk_fma_f32 v[4:5], v[4:5], v[18:19], v[24:25] op_sel_hi:[1,0,1]
	v_pk_fma_f32 v[6:7], v[6:7], v[18:19], v[26:27] op_sel_hi:[1,0,1]
	v_mov_b32_e32 v12, v15
	v_readlane_b32 s12, v2, 48
	v_readlane_b32 s14, v3, 48
	v_cvt_pk_bf16_f32 v20, v4, v5
	v_cvt_pk_bf16_f32 v21, v6, v7
	global_store_dwordx2 v1, v[20:21], s[4:5]
	s_add_u32 s4, s4, 0x8000
	s_addc_u32 s5, s5, 0
	v_add_f32_e32 v13, s12, v12
	v_max_f32_e64 v14, s14, s14
	v_max_f32_e32 v15, v13, v14
	v_sub_f32_e32 v13, v13, v15
	v_sub_f32_e32 v14, s14, v15
	v_mul_f32_e32 v14, 0x3fb8aa3b, v14
	v_mul_f32_e32 v13, 0x3fb8aa3b, v13
	v_exp_f32_e32 v16, v14
	v_exp_f32_e32 v18, v13
	s_waitcnt vmcnt(43)
	v_lshlrev_b32_e32 v24, 16, v140
	v_and_b32_e32 v25, 0xffff0000, v140
	v_lshlrev_b32_e32 v26, 16, v141
	v_and_b32_e32 v27, 0xffff0000, v141
	v_pk_mul_f32 v[24:25], v[16:17], v[24:25] op_sel_hi:[0,1]
	v_pk_mul_f32 v[26:27], v[16:17], v[26:27] op_sel_hi:[0,1]
	v_pk_fma_f32 v[4:5], v[4:5], v[18:19], v[24:25] op_sel_hi:[1,0,1]
	v_pk_fma_f32 v[6:7], v[6:7], v[18:19], v[26:27] op_sel_hi:[1,0,1]
	v_mov_b32_e32 v12, v15
	v_readlane_b32 s12, v2, 49
	v_readlane_b32 s14, v3, 49
	v_cvt_pk_bf16_f32 v20, v4, v5
	v_cvt_pk_bf16_f32 v21, v6, v7
	global_store_dwordx2 v1, v[20:21], s[4:5]
	s_add_u32 s4, s4, 0x8000
	s_addc_u32 s5, s5, 0
	v_add_f32_e32 v13, s12, v12
	v_max_f32_e64 v14, s14, s14
	v_max_f32_e32 v15, v13, v14
	v_sub_f32_e32 v13, v13, v15
	v_sub_f32_e32 v14, s14, v15
	v_mul_f32_e32 v14, 0x3fb8aa3b, v14
	v_mul_f32_e32 v13, 0x3fb8aa3b, v13
	v_exp_f32_e32 v16, v14
	v_exp_f32_e32 v18, v13
	s_waitcnt vmcnt(42)
	v_lshlrev_b32_e32 v24, 16, v142
	v_and_b32_e32 v25, 0xffff0000, v142
	v_lshlrev_b32_e32 v26, 16, v143
	v_and_b32_e32 v27, 0xffff0000, v143
	v_pk_mul_f32 v[24:25], v[16:17], v[24:25] op_sel_hi:[0,1]
	v_pk_mul_f32 v[26:27], v[16:17], v[26:27] op_sel_hi:[0,1]
	v_pk_fma_f32 v[4:5], v[4:5], v[18:19], v[24:25] op_sel_hi:[1,0,1]
	v_pk_fma_f32 v[6:7], v[6:7], v[18:19], v[26:27] op_sel_hi:[1,0,1]
	v_mov_b32_e32 v12, v15
	v_readlane_b32 s12, v2, 50
	v_readlane_b32 s14, v3, 50
	v_cvt_pk_bf16_f32 v20, v4, v5
	v_cvt_pk_bf16_f32 v21, v6, v7
	global_store_dwordx2 v1, v[20:21], s[4:5]
	s_add_u32 s4, s4, 0x8000
	s_addc_u32 s5, s5, 0
	v_add_f32_e32 v13, s12, v12
	v_max_f32_e64 v14, s14, s14
	v_max_f32_e32 v15, v13, v14
	v_sub_f32_e32 v13, v13, v15
	v_sub_f32_e32 v14, s14, v15
	v_mul_f32_e32 v14, 0x3fb8aa3b, v14
	v_mul_f32_e32 v13, 0x3fb8aa3b, v13
	v_exp_f32_e32 v16, v14
	v_exp_f32_e32 v18, v13
	s_waitcnt vmcnt(41)
	v_lshlrev_b32_e32 v24, 16, v144
	v_and_b32_e32 v25, 0xffff0000, v144
	v_lshlrev_b32_e32 v26, 16, v145
	v_and_b32_e32 v27, 0xffff0000, v145
	v_pk_mul_f32 v[24:25], v[16:17], v[24:25] op_sel_hi:[0,1]
	v_pk_mul_f32 v[26:27], v[16:17], v[26:27] op_sel_hi:[0,1]
	v_pk_fma_f32 v[4:5], v[4:5], v[18:19], v[24:25] op_sel_hi:[1,0,1]
	v_pk_fma_f32 v[6:7], v[6:7], v[18:19], v[26:27] op_sel_hi:[1,0,1]
	v_mov_b32_e32 v12, v15
	v_readlane_b32 s12, v2, 51
	v_readlane_b32 s14, v3, 51
	v_cvt_pk_bf16_f32 v20, v4, v5
	v_cvt_pk_bf16_f32 v21, v6, v7
	global_store_dwordx2 v1, v[20:21], s[4:5]
	s_add_u32 s4, s4, 0x8000
	s_addc_u32 s5, s5, 0
	v_add_f32_e32 v13, s12, v12
	v_max_f32_e64 v14, s14, s14
	v_max_f32_e32 v15, v13, v14
	v_sub_f32_e32 v13, v13, v15
	v_sub_f32_e32 v14, s14, v15
	v_mul_f32_e32 v14, 0x3fb8aa3b, v14
	v_mul_f32_e32 v13, 0x3fb8aa3b, v13
	v_exp_f32_e32 v16, v14
	v_exp_f32_e32 v18, v13
	s_waitcnt vmcnt(40)
	v_lshlrev_b32_e32 v24, 16, v146
	v_and_b32_e32 v25, 0xffff0000, v146
	v_lshlrev_b32_e32 v26, 16, v147
	v_and_b32_e32 v27, 0xffff0000, v147
	v_pk_mul_f32 v[24:25], v[16:17], v[24:25] op_sel_hi:[0,1]
	v_pk_mul_f32 v[26:27], v[16:17], v[26:27] op_sel_hi:[0,1]
	v_pk_fma_f32 v[4:5], v[4:5], v[18:19], v[24:25] op_sel_hi:[1,0,1]
	v_pk_fma_f32 v[6:7], v[6:7], v[18:19], v[26:27] op_sel_hi:[1,0,1]
	v_mov_b32_e32 v12, v15
	v_readlane_b32 s12, v2, 52
	v_readlane_b32 s14, v3, 52
	v_cvt_pk_bf16_f32 v20, v4, v5
	v_cvt_pk_bf16_f32 v21, v6, v7
	global_store_dwordx2 v1, v[20:21], s[4:5]
	s_add_u32 s4, s4, 0x8000
	s_addc_u32 s5, s5, 0
	v_add_f32_e32 v13, s12, v12
	v_max_f32_e64 v14, s14, s14
	v_max_f32_e32 v15, v13, v14
	v_sub_f32_e32 v13, v13, v15
	v_sub_f32_e32 v14, s14, v15
	v_mul_f32_e32 v14, 0x3fb8aa3b, v14
	v_mul_f32_e32 v13, 0x3fb8aa3b, v13
	v_exp_f32_e32 v16, v14
	v_exp_f32_e32 v18, v13
	s_waitcnt vmcnt(39)
	v_lshlrev_b32_e32 v24, 16, v148
	v_and_b32_e32 v25, 0xffff0000, v148
	v_lshlrev_b32_e32 v26, 16, v149
	v_and_b32_e32 v27, 0xffff0000, v149
	v_pk_mul_f32 v[24:25], v[16:17], v[24:25] op_sel_hi:[0,1]
	v_pk_mul_f32 v[26:27], v[16:17], v[26:27] op_sel_hi:[0,1]
	v_pk_fma_f32 v[4:5], v[4:5], v[18:19], v[24:25] op_sel_hi:[1,0,1]
	v_pk_fma_f32 v[6:7], v[6:7], v[18:19], v[26:27] op_sel_hi:[1,0,1]
	v_mov_b32_e32 v12, v15
	v_readlane_b32 s12, v2, 53
	v_readlane_b32 s14, v3, 53
	v_cvt_pk_bf16_f32 v20, v4, v5
	v_cvt_pk_bf16_f32 v21, v6, v7
	global_store_dwordx2 v1, v[20:21], s[4:5]
	s_add_u32 s4, s4, 0x8000
	s_addc_u32 s5, s5, 0
	v_add_f32_e32 v13, s12, v12
	v_max_f32_e64 v14, s14, s14
	v_max_f32_e32 v15, v13, v14
	v_sub_f32_e32 v13, v13, v15
	v_sub_f32_e32 v14, s14, v15
	v_mul_f32_e32 v14, 0x3fb8aa3b, v14
	v_mul_f32_e32 v13, 0x3fb8aa3b, v13
	v_exp_f32_e32 v16, v14
	v_exp_f32_e32 v18, v13
	s_waitcnt vmcnt(38)
	v_lshlrev_b32_e32 v24, 16, v150
	v_and_b32_e32 v25, 0xffff0000, v150
	v_lshlrev_b32_e32 v26, 16, v151
	v_and_b32_e32 v27, 0xffff0000, v151
	v_pk_mul_f32 v[24:25], v[16:17], v[24:25] op_sel_hi:[0,1]
	v_pk_mul_f32 v[26:27], v[16:17], v[26:27] op_sel_hi:[0,1]
	v_pk_fma_f32 v[4:5], v[4:5], v[18:19], v[24:25] op_sel_hi:[1,0,1]
	v_pk_fma_f32 v[6:7], v[6:7], v[18:19], v[26:27] op_sel_hi:[1,0,1]
	v_mov_b32_e32 v12, v15
	v_readlane_b32 s12, v2, 54
	v_readlane_b32 s14, v3, 54
	v_cvt_pk_bf16_f32 v20, v4, v5
	v_cvt_pk_bf16_f32 v21, v6, v7
	global_store_dwordx2 v1, v[20:21], s[4:5]
	s_add_u32 s4, s4, 0x8000
	s_addc_u32 s5, s5, 0
	v_add_f32_e32 v13, s12, v12
	v_max_f32_e64 v14, s14, s14
	v_max_f32_e32 v15, v13, v14
	v_sub_f32_e32 v13, v13, v15
	v_sub_f32_e32 v14, s14, v15
	v_mul_f32_e32 v14, 0x3fb8aa3b, v14
	v_mul_f32_e32 v13, 0x3fb8aa3b, v13
	v_exp_f32_e32 v16, v14
	v_exp_f32_e32 v18, v13
	s_waitcnt vmcnt(37)
	v_lshlrev_b32_e32 v24, 16, v152
	v_and_b32_e32 v25, 0xffff0000, v152
	v_lshlrev_b32_e32 v26, 16, v153
	v_and_b32_e32 v27, 0xffff0000, v153
	v_pk_mul_f32 v[24:25], v[16:17], v[24:25] op_sel_hi:[0,1]
	v_pk_mul_f32 v[26:27], v[16:17], v[26:27] op_sel_hi:[0,1]
	v_pk_fma_f32 v[4:5], v[4:5], v[18:19], v[24:25] op_sel_hi:[1,0,1]
	v_pk_fma_f32 v[6:7], v[6:7], v[18:19], v[26:27] op_sel_hi:[1,0,1]
	v_mov_b32_e32 v12, v15
	v_readlane_b32 s12, v2, 55
	v_readlane_b32 s14, v3, 55
	v_cvt_pk_bf16_f32 v20, v4, v5
	v_cvt_pk_bf16_f32 v21, v6, v7
	global_store_dwordx2 v1, v[20:21], s[4:5]
	s_add_u32 s4, s4, 0x8000
	s_addc_u32 s5, s5, 0
	v_add_f32_e32 v13, s12, v12
	v_max_f32_e64 v14, s14, s14
	v_max_f32_e32 v15, v13, v14
	v_sub_f32_e32 v13, v13, v15
	v_sub_f32_e32 v14, s14, v15
	v_mul_f32_e32 v14, 0x3fb8aa3b, v14
	v_mul_f32_e32 v13, 0x3fb8aa3b, v13
	v_exp_f32_e32 v16, v14
	v_exp_f32_e32 v18, v13
	s_waitcnt vmcnt(36)
	v_lshlrev_b32_e32 v24, 16, v154
	v_and_b32_e32 v25, 0xffff0000, v154
	v_lshlrev_b32_e32 v26, 16, v155
	v_and_b32_e32 v27, 0xffff0000, v155
	v_pk_mul_f32 v[24:25], v[16:17], v[24:25] op_sel_hi:[0,1]
	v_pk_mul_f32 v[26:27], v[16:17], v[26:27] op_sel_hi:[0,1]
	v_pk_fma_f32 v[4:5], v[4:5], v[18:19], v[24:25] op_sel_hi:[1,0,1]
	v_pk_fma_f32 v[6:7], v[6:7], v[18:19], v[26:27] op_sel_hi:[1,0,1]
	v_mov_b32_e32 v12, v15
	v_readlane_b32 s12, v2, 56
	v_readlane_b32 s14, v3, 56
	v_cvt_pk_bf16_f32 v20, v4, v5
	v_cvt_pk_bf16_f32 v21, v6, v7
	global_store_dwordx2 v1, v[20:21], s[4:5]
	s_add_u32 s4, s4, 0x8000
	s_addc_u32 s5, s5, 0
	v_add_f32_e32 v13, s12, v12
	v_max_f32_e64 v14, s14, s14
	v_max_f32_e32 v15, v13, v14
	v_sub_f32_e32 v13, v13, v15
	v_sub_f32_e32 v14, s14, v15
	v_mul_f32_e32 v14, 0x3fb8aa3b, v14
	v_mul_f32_e32 v13, 0x3fb8aa3b, v13
	v_exp_f32_e32 v16, v14
	v_exp_f32_e32 v18, v13
	s_waitcnt vmcnt(35)
	v_lshlrev_b32_e32 v24, 16, v100
	v_and_b32_e32 v25, 0xffff0000, v100
	v_lshlrev_b32_e32 v26, 16, v101
	v_and_b32_e32 v27, 0xffff0000, v101
	v_pk_mul_f32 v[24:25], v[16:17], v[24:25] op_sel_hi:[0,1]
	v_pk_mul_f32 v[26:27], v[16:17], v[26:27] op_sel_hi:[0,1]
	v_pk_fma_f32 v[4:5], v[4:5], v[18:19], v[24:25] op_sel_hi:[1,0,1]
	v_pk_fma_f32 v[6:7], v[6:7], v[18:19], v[26:27] op_sel_hi:[1,0,1]
	v_mov_b32_e32 v12, v15
	v_readlane_b32 s12, v2, 57
	v_readlane_b32 s14, v3, 57
	v_cvt_pk_bf16_f32 v20, v4, v5
	v_cvt_pk_bf16_f32 v21, v6, v7
	global_store_dwordx2 v1, v[20:21], s[4:5]
	s_add_u32 s4, s4, 0x8000
	s_addc_u32 s5, s5, 0
	v_add_f32_e32 v13, s12, v12
	v_max_f32_e64 v14, s14, s14
	v_max_f32_e32 v15, v13, v14
	v_sub_f32_e32 v13, v13, v15
	v_sub_f32_e32 v14, s14, v15
	v_mul_f32_e32 v14, 0x3fb8aa3b, v14
	v_mul_f32_e32 v13, 0x3fb8aa3b, v13
	v_exp_f32_e32 v16, v14
	v_exp_f32_e32 v18, v13
	s_waitcnt vmcnt(34)
	v_lshlrev_b32_e32 v24, 16, v102
	v_and_b32_e32 v25, 0xffff0000, v102
	v_lshlrev_b32_e32 v26, 16, v103
	v_and_b32_e32 v27, 0xffff0000, v103
	v_pk_mul_f32 v[24:25], v[16:17], v[24:25] op_sel_hi:[0,1]
	v_pk_mul_f32 v[26:27], v[16:17], v[26:27] op_sel_hi:[0,1]
	v_pk_fma_f32 v[4:5], v[4:5], v[18:19], v[24:25] op_sel_hi:[1,0,1]
	v_pk_fma_f32 v[6:7], v[6:7], v[18:19], v[26:27] op_sel_hi:[1,0,1]
	v_mov_b32_e32 v12, v15
	v_readlane_b32 s12, v2, 58
	v_readlane_b32 s14, v3, 58
	v_cvt_pk_bf16_f32 v20, v4, v5
	v_cvt_pk_bf16_f32 v21, v6, v7
	global_store_dwordx2 v1, v[20:21], s[4:5]
	s_add_u32 s4, s4, 0x8000
	s_addc_u32 s5, s5, 0
	v_add_f32_e32 v13, s12, v12
	v_max_f32_e64 v14, s14, s14
	v_max_f32_e32 v15, v13, v14
	v_sub_f32_e32 v13, v13, v15
	v_sub_f32_e32 v14, s14, v15
	v_mul_f32_e32 v14, 0x3fb8aa3b, v14
	v_mul_f32_e32 v13, 0x3fb8aa3b, v13
	v_exp_f32_e32 v16, v14
	v_exp_f32_e32 v18, v13
	s_waitcnt vmcnt(33)
	v_lshlrev_b32_e32 v24, 16, v104
	v_and_b32_e32 v25, 0xffff0000, v104
	v_lshlrev_b32_e32 v26, 16, v105
	v_and_b32_e32 v27, 0xffff0000, v105
	v_pk_mul_f32 v[24:25], v[16:17], v[24:25] op_sel_hi:[0,1]
	v_pk_mul_f32 v[26:27], v[16:17], v[26:27] op_sel_hi:[0,1]
	v_pk_fma_f32 v[4:5], v[4:5], v[18:19], v[24:25] op_sel_hi:[1,0,1]
	v_pk_fma_f32 v[6:7], v[6:7], v[18:19], v[26:27] op_sel_hi:[1,0,1]
	v_mov_b32_e32 v12, v15
	v_readlane_b32 s12, v2, 59
	v_readlane_b32 s14, v3, 59
	v_cvt_pk_bf16_f32 v20, v4, v5
	v_cvt_pk_bf16_f32 v21, v6, v7
	global_store_dwordx2 v1, v[20:21], s[4:5]
	s_add_u32 s4, s4, 0x8000
	s_addc_u32 s5, s5, 0
	v_add_f32_e32 v13, s12, v12
	v_max_f32_e64 v14, s14, s14
	v_max_f32_e32 v15, v13, v14
	v_sub_f32_e32 v13, v13, v15
	v_sub_f32_e32 v14, s14, v15
	v_mul_f32_e32 v14, 0x3fb8aa3b, v14
	v_mul_f32_e32 v13, 0x3fb8aa3b, v13
	v_exp_f32_e32 v16, v14
	v_exp_f32_e32 v18, v13
	s_waitcnt vmcnt(32)
	v_lshlrev_b32_e32 v24, 16, v106
	v_and_b32_e32 v25, 0xffff0000, v106
	v_lshlrev_b32_e32 v26, 16, v107
	v_and_b32_e32 v27, 0xffff0000, v107
	v_pk_mul_f32 v[24:25], v[16:17], v[24:25] op_sel_hi:[0,1]
	v_pk_mul_f32 v[26:27], v[16:17], v[26:27] op_sel_hi:[0,1]
	v_pk_fma_f32 v[4:5], v[4:5], v[18:19], v[24:25] op_sel_hi:[1,0,1]
	v_pk_fma_f32 v[6:7], v[6:7], v[18:19], v[26:27] op_sel_hi:[1,0,1]
	v_mov_b32_e32 v12, v15
	v_readlane_b32 s12, v2, 60
	v_readlane_b32 s14, v3, 60
	v_cvt_pk_bf16_f32 v20, v4, v5
	v_cvt_pk_bf16_f32 v21, v6, v7
	global_store_dwordx2 v1, v[20:21], s[4:5]
	s_add_u32 s4, s4, 0x8000
	s_addc_u32 s5, s5, 0
	v_add_f32_e32 v13, s12, v12
	v_max_f32_e64 v14, s14, s14
	v_max_f32_e32 v15, v13, v14
	v_sub_f32_e32 v13, v13, v15
	v_sub_f32_e32 v14, s14, v15
	v_mul_f32_e32 v14, 0x3fb8aa3b, v14
	v_mul_f32_e32 v13, 0x3fb8aa3b, v13
	v_exp_f32_e32 v16, v14
	v_exp_f32_e32 v18, v13
	s_waitcnt vmcnt(31)
	v_lshlrev_b32_e32 v24, 16, v108
	v_and_b32_e32 v25, 0xffff0000, v108
	v_lshlrev_b32_e32 v26, 16, v109
	v_and_b32_e32 v27, 0xffff0000, v109
	v_pk_mul_f32 v[24:25], v[16:17], v[24:25] op_sel_hi:[0,1]
	v_pk_mul_f32 v[26:27], v[16:17], v[26:27] op_sel_hi:[0,1]
	v_pk_fma_f32 v[4:5], v[4:5], v[18:19], v[24:25] op_sel_hi:[1,0,1]
	v_pk_fma_f32 v[6:7], v[6:7], v[18:19], v[26:27] op_sel_hi:[1,0,1]
	v_mov_b32_e32 v12, v15
	v_readlane_b32 s12, v2, 61
	v_readlane_b32 s14, v3, 61
	v_cvt_pk_bf16_f32 v20, v4, v5
	v_cvt_pk_bf16_f32 v21, v6, v7
	global_store_dwordx2 v1, v[20:21], s[4:5]
	s_add_u32 s4, s4, 0x8000
	s_addc_u32 s5, s5, 0
	v_add_f32_e32 v13, s12, v12
	v_max_f32_e64 v14, s14, s14
	v_max_f32_e32 v15, v13, v14
	v_sub_f32_e32 v13, v13, v15
	v_sub_f32_e32 v14, s14, v15
	v_mul_f32_e32 v14, 0x3fb8aa3b, v14
	v_mul_f32_e32 v13, 0x3fb8aa3b, v13
	v_exp_f32_e32 v16, v14
	v_exp_f32_e32 v18, v13
	s_waitcnt vmcnt(30)
	v_lshlrev_b32_e32 v24, 16, v110
	v_and_b32_e32 v25, 0xffff0000, v110
	v_lshlrev_b32_e32 v26, 16, v111
	v_and_b32_e32 v27, 0xffff0000, v111
	v_pk_mul_f32 v[24:25], v[16:17], v[24:25] op_sel_hi:[0,1]
	v_pk_mul_f32 v[26:27], v[16:17], v[26:27] op_sel_hi:[0,1]
	v_pk_fma_f32 v[4:5], v[4:5], v[18:19], v[24:25] op_sel_hi:[1,0,1]
	v_pk_fma_f32 v[6:7], v[6:7], v[18:19], v[26:27] op_sel_hi:[1,0,1]
	v_mov_b32_e32 v12, v15
	v_readlane_b32 s12, v2, 62
	v_readlane_b32 s14, v3, 62
	v_cvt_pk_bf16_f32 v20, v4, v5
	v_cvt_pk_bf16_f32 v21, v6, v7
	global_store_dwordx2 v1, v[20:21], s[4:5]
	s_add_u32 s4, s4, 0x8000
	s_addc_u32 s5, s5, 0
	v_add_f32_e32 v13, s12, v12
	v_max_f32_e64 v14, s14, s14
	v_max_f32_e32 v15, v13, v14
	v_sub_f32_e32 v13, v13, v15
	v_sub_f32_e32 v14, s14, v15
	v_mul_f32_e32 v14, 0x3fb8aa3b, v14
	v_mul_f32_e32 v13, 0x3fb8aa3b, v13
	v_exp_f32_e32 v16, v14
	v_exp_f32_e32 v18, v13
	s_waitcnt vmcnt(29)
	v_lshlrev_b32_e32 v24, 16, v112
	v_and_b32_e32 v25, 0xffff0000, v112
	v_lshlrev_b32_e32 v26, 16, v113
	v_and_b32_e32 v27, 0xffff0000, v113
	v_pk_mul_f32 v[24:25], v[16:17], v[24:25] op_sel_hi:[0,1]
	v_pk_mul_f32 v[26:27], v[16:17], v[26:27] op_sel_hi:[0,1]
	v_pk_fma_f32 v[4:5], v[4:5], v[18:19], v[24:25] op_sel_hi:[1,0,1]
	v_pk_fma_f32 v[6:7], v[6:7], v[18:19], v[26:27] op_sel_hi:[1,0,1]
	v_mov_b32_e32 v12, v15
	v_readlane_b32 s12, v2, 63
	v_readlane_b32 s14, v3, 63
	v_cvt_pk_bf16_f32 v20, v4, v5
	v_cvt_pk_bf16_f32 v21, v6, v7
	global_store_dwordx2 v1, v[20:21], s[4:5]
	s_add_u32 s4, s4, 0x8000
	s_addc_u32 s5, s5, 0
	v_add_f32_e32 v13, s12, v12
	v_max_f32_e64 v14, s14, s14
	v_max_f32_e32 v15, v13, v14
	v_sub_f32_e32 v13, v13, v15
	v_sub_f32_e32 v14, s14, v15
	v_mul_f32_e32 v14, 0x3fb8aa3b, v14
	v_mul_f32_e32 v13, 0x3fb8aa3b, v13
	v_exp_f32_e32 v16, v14
	v_exp_f32_e32 v18, v13
	s_waitcnt vmcnt(28)
	v_lshlrev_b32_e32 v24, 16, v114
	v_and_b32_e32 v25, 0xffff0000, v114
	v_lshlrev_b32_e32 v26, 16, v115
	v_and_b32_e32 v27, 0xffff0000, v115
	v_pk_mul_f32 v[24:25], v[16:17], v[24:25] op_sel_hi:[0,1]
	v_pk_mul_f32 v[26:27], v[16:17], v[26:27] op_sel_hi:[0,1]
	v_pk_fma_f32 v[4:5], v[4:5], v[18:19], v[24:25] op_sel_hi:[1,0,1]
	v_pk_fma_f32 v[6:7], v[6:7], v[18:19], v[26:27] op_sel_hi:[1,0,1]
	v_mov_b32_e32 v12, v15
	s_branch .Lm2_done
.Lm2_w0:
	s_lshl_b32 s12, s15, 15
	s_add_u32 s6, s82, s12
	s_addc_u32 s7, s83, 0
	s_add_u32 s8, s6, 0x1700000
	s_addc_u32 s9, s7, 0
	s_add_u32 s6, s6, 0x1600000
	s_addc_u32 s7, s7, 0
	s_lshl_b32 s12, s15, 8
	s_add_u32 s10, s82, s12
	s_addc_u32 s11, s83, 0
	s_add_u32 s10, s10, 0x1164000
	s_addc_u32 s11, s11, 0
	s_lshl_b32 s12, s13, 4
	v_add_u32_e32 v9, s12, v0
	v_lshlrev_b32_e32 v9, 2, v9
	v_mov_b32_e32 v10, 0
	global_load_dwordx2 v[100:101], v1, s[2:3]
	s_add_u32 s2, s2, 0x8000
	s_addc_u32 s3, s3, 0
	global_load_dwordx2 v[102:103], v1, s[2:3]
	s_add_u32 s2, s2, 0x8000
	s_addc_u32 s3, s3, 0
	global_load_dwordx2 v[104:105], v1, s[2:3]
	s_add_u32 s2, s2, 0x8000
	s_addc_u32 s3, s3, 0
	global_load_dwordx2 v[106:107], v1, s[2:3]
	s_add_u32 s2, s2, 0x8000
	s_addc_u32 s3, s3, 0
	global_load_dwordx2 v[108:109], v1, s[2:3]
	s_add_u32 s2, s2, 0x8000
	s_addc_u32 s3, s3, 0
	global_load_dwordx2 v[110:111], v1, s[2:3]
	s_add_u32 s2, s2, 0x8000
	s_addc_u32 s3, s3, 0
	global_load_dwordx2 v[112:113], v1, s[2:3]
	s_add_u32 s2, s2, 0x8000
	s_addc_u32 s3, s3, 0
	global_load_dwordx2 v[114:115], v1, s[2:3]
	s_add_u32 s2, s2, 0x8000
	s_addc_u32 s3, s3, 0
	global_load_dwordx2 v[116:117], v1, s[2:3]
	s_add_u32 s2, s2, 0x8000
	s_addc_u32 s3, s3, 0
	global_load_dwordx2 v[118:119], v1, s[2:3]
	s_add_u32 s2, s2, 0x8000
	s_addc_u32 s3, s3, 0
	global_load_dwordx2 v[120:121], v1, s[2:3]
	s_add_u32 s2, s2, 0x8000
	s_addc_u32 s3, s3, 0
	global_load_dwordx2 v[122:123], v1, s[2:3]
	s_add_u32 s2, s2, 0x8000
	s_addc_u32 s3, s3, 0
	global_load_dwordx2 v[124:125], v1, s[2:3]
	s_add_u32 s2, s2, 0x8000
	s_addc_u32 s3, s3, 0
	global_load_dwordx2 v[126:127], v1, s[2:3]
	s_add_u32 s2, s2, 0x8000
	s_addc_u32 s3, s3, 0
	global_load_dwordx2 v[128:129], v1, s[2:3]
	s_add_u32 s2, s2, 0x8000
	s_addc_u32 s3, s3, 0
	global_load_dwordx2 v[130:131], v1, s[2:3]
	s_add_u32 s2, s2, 0x8000
	s_addc_u32 s3, s3, 0
	global_load_dwordx2 v[132:133], v1, s[2:3]
	s_add_u32 s2, s2, 0x8000
	s_addc_u32 s3, s3, 0
	global_load_dwordx2 v[134:135], v1, s[2:3]
	s_add_u32 s2, s2, 0x8000
	s_addc_u32 s3, s3, 0
	global_load_dwordx2 v[136:137], v1, s[2:3]
	s_add_u32 s2, s2, 0x8000
	s_addc_u32 s3, s3, 0
	global_load_dwordx2 v[138:139], v1, s[2:3]
	s_add_u32 s2, s2, 0x8000
	s_addc_u32 s3, s3, 0
	global_load_dwordx2 v[140:141], v1, s[2:3]
	s_add_u32 s2, s2, 0x8000
	s_addc_u32 s3, s3, 0
	global_load_dwordx2 v[142:143], v1, s[2:3]
	s_add_u32 s2, s2, 0x8000
	s_addc_u32 s3, s3, 0
	global_load_dwordx2 v[144:145], v1, s[2:3]
	s_add_u32 s2, s2, 0x8000
	s_addc_u32 s3, s3, 0
	global_load_dwordx2 v[146:147], v1, s[2:3]
	s_add_u32 s2, s2, 0x8000
	s_addc_u32 s3, s3, 0
	s_mov_b64 exec, 0xffff
	global_load_dword v180, v9, s[6:7]
	s_add_u32 s6, s6, 0x200
	s_addc_u32 s7, s7, 0
	global_load_dword v181, v9, s[6:7]
	s_add_u32 s6, s6, 0x200
	s_addc_u32 s7, s7, 0
	global_load_dword v182, v9, s[6:7]
	s_add_u32 s6, s6, 0x200
	s_addc_u32 s7, s7, 0
	global_load_dword v183, v9, s[6:7]
	s_add_u32 s6, s6, 0x200
	s_addc_u32 s7, s7, 0
	global_load_dword v184, v9, s[6:7]
	s_add_u32 s6, s6, 0x200
	s_addc_u32 s7, s7, 0
	global_load_dword v185, v9, s[6:7]
	s_add_u32 s6, s6, 0x200
	s_addc_u32 s7, s7, 0
	global_load_dword v186, v9, s[6:7]
	s_add_u32 s6, s6, 0x200
	s_addc_u32 s7, s7, 0
	global_load_dword v187, v9, s[6:7]
	s_add_u32 s6, s6, 0x200
	s_addc_u32 s7, s7, 0
	global_load_dword v188, v9, s[6:7]
	s_add_u32 s6, s6, 0x200
	s_addc_u32 s7, s7, 0
	global_load_dword v189, v9, s[6:7]
	s_add_u32 s6, s6, 0x200
	s_addc_u32 s7, s7, 0
	global_load_dword v190, v9, s[6:7]
	s_add_u32 s6, s6, 0x200
	s_addc_u32 s7, s7, 0
	global_load_dword v191, v9, s[6:7]
	s_add_u32 s6, s6, 0x200
	s_addc_u32 s7, s7, 0
	global_load_dword v192, v9, s[6:7]
	s_add_u32 s6, s6, 0x200
	s_addc_u32 s7, s7, 0
	global_load_dword v193, v9, s[6:7]
	s_add_u32 s6, s6, 0x200
	s_addc_u32 s7, s7, 0
	global_load_dword v194, v9, s[6:7]
	s_add_u32 s6, s6, 0x200
	s_addc_u32 s7, s7, 0
	global_load_dword v195, v9, s[6:7]
	s_add_u32 s6, s6, 0x200
	s_addc_u32 s7, s7, 0
	global_load_dword v196, v9, s[6:7]
	s_add_u32 s6, s6, 0x200
	s_addc_u32 s7, s7, 0
	global_load_dword v197, v9, s[6:7]
	s_add_u32 s6, s6, 0x200
	s_addc_u32 s7, s7, 0
	global_load_dword v198, v9, s[6:7]
	s_add_u32 s6, s6, 0x200
	s_addc_u32 s7, s7, 0
	global_load_dword v199, v9, s[6:7]
	s_add_u32 s6, s6, 0x200
	s_addc_u32 s7, s7, 0
	global_load_dword v200, v9, s[6:7]
	s_add_u32 s6, s6, 0x200
	s_addc_u32 s7, s7, 0
	global_load_dword v201, v9, s[6:7]
	s_add_u32 s6, s6, 0x200
	s_addc_u32 s7, s7, 0
	global_load_dword v202, v9, s[6:7]
	s_add_u32 s6, s6, 0x200
	s_addc_u32 s7, s7, 0
	global_load_dword v203, v9, s[6:7]
	s_add_u32 s6, s6, 0x200
	s_addc_u32 s7, s7, 0
	s_mov_b64 exec, -1
	s_waitcnt vmcnt(48)
	v_readlane_b32 s12, v2, 0
	v_readlane_b32 s14, v3, 0
	v_cvt_pk_bf16_f32 v20, v4, v5
	v_cvt_pk_bf16_f32 v21, v6, v7
	global_store_dwordx2 v1, v[20:21], s[4:5]
	s_add_u32 s4, s4, 0x8000
	s_addc_u32 s5, s5, 0
	v_add_f32_e32 v13, s12, v12
	v_max_f32_e64 v14, s14, s14
	v_max_f32_e32 v15, v13, v14
	v_sub_f32_e32 v13, v13, v15
	v_sub_f32_e32 v14, s14, v15
	v_mul_f32_e32 v14, 0x3fb8aa3b, v14
	v_mul_f32_e32 v13, 0x3fb8aa3b, v13
	v_exp_f32_e32 v16, v14
	v_exp_f32_e32 v18, v13
	s_mov_b64 exec, 0xffff
	global_store_dword v9, v8, s[8:9]
	s_add_u32 s8, s8, 0x200
	s_addc_u32 s9, s9, 0
	s_cmp_lg_u32 s13, 0
	s_cbranch_scc1 .Lm2_nomc0
	global_store_dword v10, v12, s[10:11]
.Lm2_nomc0:
	s_waitcnt vmcnt(25)
	v_mul_f32_e32 v22, v18, v8
	v_fma_f32 v8, v180, v16, v22
	global_load_dword v180, v9, s[6:7]
	s_add_u32 s6, s6, 0x200
	s_addc_u32 s7, s7, 0
	s_mov_b64 exec, -1
	s_waitcnt vmcnt(50)
	v_lshlrev_b32_e32 v24, 16, v100
	v_and_b32_e32 v25, 0xffff0000, v100
	v_lshlrev_b32_e32 v26, 16, v101
	v_and_b32_e32 v27, 0xffff0000, v101
	global_load_dwordx2 v[100:101], v1, s[2:3]
	s_add_u32 s2, s2, 0x8000
	s_addc_u32 s3, s3, 0
	v_pk_mul_f32 v[24:25], v[16:17], v[24:25] op_sel_hi:[0,1]
	v_pk_mul_f32 v[26:27], v[16:17], v[26:27] op_sel_hi:[0,1]
	v_pk_fma_f32 v[4:5], v[4:5], v[18:19], v[24:25] op_sel_hi:[1,0,1]
	v_pk_fma_f32 v[6:7], v[6:7], v[18:19], v[26:27] op_sel_hi:[1,0,1]
	v_mov_b32_e32 v12, v15
	v_readlane_b32 s12, v2, 1
	v_readlane_b32 s14, v3, 1
	v_cvt_pk_bf16_f32 v20, v4, v5
	v_cvt_pk_bf16_f32 v21, v6, v7
	global_store_dwordx2 v1, v[20:21], s[4:5]
	s_add_u32 s4, s4, 0x8000
	s_addc_u32 s5, s5, 0
	v_add_f32_e32 v13, s12, v12
	v_max_f32_e64 v14, s14, s14
	v_max_f32_e32 v15, v13, v14
	v_sub_f32_e32 v13, v13, v15
	v_sub_f32_e32 v14, s14, v15
	v_mul_f32_e32 v14, 0x3fb8aa3b, v14
	v_mul_f32_e32 v13, 0x3fb8aa3b, v13
	v_exp_f32_e32 v16, v14
	v_exp_f32_e32 v18, v13
	s_mov_b64 exec, 0xffff
	global_store_dword v9, v8, s[8:9]
	s_add_u32 s8, s8, 0x200
	s_addc_u32 s9, s9, 0
	s_cmp_lg_u32 s13, 0
	s_cbranch_scc1 .Lm2_nomc1
	global_store_dword v10, v12, s[10:11] offset:4
.Lm2_nomc1:
	s_waitcnt vmcnt(28)
	v_mul_f32_e32 v22, v18, v8
	v_fma_f32 v8, v181, v16, v22
	global_load_dword v181, v9, s[6:7]
	s_add_u32 s6, s6, 0x200
	s_addc_u32 s7, s7, 0
	s_mov_b64 exec, -1
	s_waitcnt vmcnt(53)
	v_lshlrev_b32_e32 v24, 16, v102
	v_and_b32_e32 v25, 0xffff0000, v102
	v_lshlrev_b32_e32 v26, 16, v103
	v_and_b32_e32 v27, 0xffff0000, v103
	global_load_dwordx2 v[102:103], v1, s[2:3]
	s_add_u32 s2, s2, 0x8000
	s_addc_u32 s3, s3, 0
	v_pk_mul_f32 v[24:25], v[16:17], v[24:25] op_sel_hi:[0,1]
	v_pk_mul_f32 v[26:27], v[16:17], v[26:27] op_sel_hi:[0,1]
	v_pk_fma_f32 v[4:5], v[4:5], v[18:19], v[24:25] op_sel_hi:[1,0,1]
	v_pk_fma_f32 v[6:7], v[6:7], v[18:19], v[26:27] op_sel_hi:[1,0,1]
	v_mov_b32_e32 v12, v15
	v_readlane_b32 s12, v2, 2
	v_readlane_b32 s14, v3, 2
	v_cvt_pk_bf16_f32 v20, v4, v5
	v_cvt_pk_bf16_f32 v21, v6, v7
	global_store_dwordx2 v1, v[20:21], s[4:5]
	s_add_u32 s4, s4, 0x8000
	s_addc_u32 s5, s5, 0
	v_add_f32_e32 v13, s12, v12
	v_max_f32_e64 v14, s14, s14
	v_max_f32_e32 v15, v13, v14
	v_sub_f32_e32 v13, v13, v15
	v_sub_f32_e32 v14, s14, v15
	v_mul_f32_e32 v14, 0x3fb8aa3b, v14
	v_mul_f32_e32 v13, 0x3fb8aa3b, v13
	v_exp_f32_e32 v16, v14
	v_exp_f32_e32 v18, v13
	s_mov_b64 exec, 0xffff
	global_store_dword v9, v8, s[8:9]
	s_add_u32 s8, s8, 0x200
	s_addc_u32 s9, s9, 0
	s_cmp_lg_u32 s13, 0
	s_cbranch_scc1 .Lm2_nomc2
	global_store_dword v10, v12, s[10:11] offset:8
.Lm2_nomc2:
	s_waitcnt vmcnt(31)
	v_mul_f32_e32 v22, v18, v8
	v_fma_f32 v8, v182, v16, v22
	global_load_dword v182, v9, s[6:7]
	s_add_u32 s6, s6, 0x200
	s_addc_u32 s7, s7, 0
	s_mov_b64 exec, -1
	s_waitcnt vmcnt(56)
	v_lshlrev_b32_e32 v24, 16, v104
	v_and_b32_e32 v25, 0xffff0000, v104
	v_lshlrev_b32_e32 v26, 16, v105
	v_and_b32_e32 v27, 0xffff0000, v105
	global_load_dwordx2 v[104:105], v1, s[2:3]
	s_add_u32 s2, s2, 0x8000
	s_addc_u32 s3, s3, 0
	v_pk_mul_f32 v[24:25], v[16:17], v[24:25] op_sel_hi:[0,1]
	v_pk_mul_f32 v[26:27], v[16:17], v[26:27] op_sel_hi:[0,1]
	v_pk_fma_f32 v[4:5], v[4:5], v[18:19], v[24:25] op_sel_hi:[1,0,1]
	v_pk_fma_f32 v[6:7], v[6:7], v[18:19], v[26:27] op_sel_hi:[1,0,1]
	v_mov_b32_e32 v12, v15
	v_readlane_b32 s12, v2, 3
	v_readlane_b32 s14, v3, 3
	v_cvt_pk_bf16_f32 v20, v4, v5
	v_cvt_pk_bf16_f32 v21, v6, v7
	global_store_dwordx2 v1, v[20:21], s[4:5]
	s_add_u32 s4, s4, 0x8000
	s_addc_u32 s5, s5, 0
	v_add_f32_e32 v13, s12, v12
	v_max_f32_e64 v14, s14, s14
	v_max_f32_e32 v15, v13, v14
	v_sub_f32_e32 v13, v13, v15
	v_sub_f32_e32 v14, s14, v15
	v_mul_f32_e32 v14, 0x3fb8aa3b, v14
	v_mul_f32_e32 v13, 0x3fb8aa3b, v13
	v_exp_f32_e32 v16, v14
	v_exp_f32_e32 v18, v13
	s_mov_b64 exec, 0xffff
	global_store_dword v9, v8, s[8:9]
	s_add_u32 s8, s8, 0x200
	s_addc_u32 s9, s9, 0
	s_cmp_lg_u32 s13, 0
	s_cbranch_scc1 .Lm2_nomc3
	global_store_dword v10, v12, s[10:11] offset:12
.Lm2_nomc3:
	s_waitcnt vmcnt(34)
	v_mul_f32_e32 v22, v18, v8
	v_fma_f32 v8, v183, v16, v22
	global_load_dword v183, v9, s[6:7]
	s_add_u32 s6, s6, 0x200
	s_addc_u32 s7, s7, 0
	s_mov_b64 exec, -1
	s_waitcnt vmcnt(59)
	v_lshlrev_b32_e32 v24, 16, v106
	v_and_b32_e32 v25, 0xffff0000, v106
	v_lshlrev_b32_e32 v26, 16, v107
	v_and_b32_e32 v27, 0xffff0000, v107
	global_load_dwordx2 v[106:107], v1, s[2:3]
	s_add_u32 s2, s2, 0x8000
	s_addc_u32 s3, s3, 0
	v_pk_mul_f32 v[24:25], v[16:17], v[24:25] op_sel_hi:[0,1]
	v_pk_mul_f32 v[26:27], v[16:17], v[26:27] op_sel_hi:[0,1]
	v_pk_fma_f32 v[4:5], v[4:5], v[18:19], v[24:25] op_sel_hi:[1,0,1]
	v_pk_fma_f32 v[6:7], v[6:7], v[18:19], v[26:27] op_sel_hi:[1,0,1]
	v_mov_b32_e32 v12, v15
	v_readlane_b32 s12, v2, 4
	v_readlane_b32 s14, v3, 4
	v_cvt_pk_bf16_f32 v20, v4, v5
	v_cvt_pk_bf16_f32 v21, v6, v7
	global_store_dwordx2 v1, v[20:21], s[4:5]
	s_add_u32 s4, s4, 0x8000
	s_addc_u32 s5, s5, 0
	v_add_f32_e32 v13, s12, v12
	v_max_f32_e64 v14, s14, s14
	v_max_f32_e32 v15, v13, v14
	v_sub_f32_e32 v13, v13, v15
	v_sub_f32_e32 v14, s14, v15
	v_mul_f32_e32 v14, 0x3fb8aa3b, v14
	v_mul_f32_e32 v13, 0x3fb8aa3b, v13
	v_exp_f32_e32 v16, v14
	v_exp_f32_e32 v18, v13
	s_mov_b64 exec, 0xffff
	global_store_dword v9, v8, s[8:9]
	s_add_u32 s8, s8, 0x200
	s_addc_u32 s9, s9, 0
	s_cmp_lg_u32 s13, 0
	s_cbranch_scc1 .Lm2_nomc4
	global_store_dword v10, v12, s[10:11] offset:16
.Lm2_nomc4:
	s_waitcnt vmcnt(37)
	v_mul_f32_e32 v22, v18, v8
	v_fma_f32 v8, v184, v16, v22
	global_load_dword v184, v9, s[6:7]
	s_add_u32 s6, s6, 0x200
	s_addc_u32 s7, s7, 0
	s_mov_b64 exec, -1
	s_waitcnt vmcnt(62)
	v_lshlrev_b32_e32 v24, 16, v108
	v_and_b32_e32 v25, 0xffff0000, v108
	v_lshlrev_b32_e32 v26, 16, v109
	v_and_b32_e32 v27, 0xffff0000, v109
	global_load_dwordx2 v[108:109], v1, s[2:3]
	s_add_u32 s2, s2, 0x8000
	s_addc_u32 s3, s3, 0
	v_pk_mul_f32 v[24:25], v[16:17], v[24:25] op_sel_hi:[0,1]
	v_pk_mul_f32 v[26:27], v[16:17], v[26:27] op_sel_hi:[0,1]
	v_pk_fma_f32 v[4:5], v[4:5], v[18:19], v[24:25] op_sel_hi:[1,0,1]
	v_pk_fma_f32 v[6:7], v[6:7], v[18:19], v[26:27] op_sel_hi:[1,0,1]
	v_mov_b32_e32 v12, v15
	v_readlane_b32 s12, v2, 5
	v_readlane_b32 s14, v3, 5
	v_cvt_pk_bf16_f32 v20, v4, v5
	v_cvt_pk_bf16_f32 v21, v6, v7
	global_store_dwordx2 v1, v[20:21], s[4:5]
	s_add_u32 s4, s4, 0x8000
	s_addc_u32 s5, s5, 0
	v_add_f32_e32 v13, s12, v12
	v_max_f32_e64 v14, s14, s14
	v_max_f32_e32 v15, v13, v14
	v_sub_f32_e32 v13, v13, v15
	v_sub_f32_e32 v14, s14, v15
	v_mul_f32_e32 v14, 0x3fb8aa3b, v14
	v_mul_f32_e32 v13, 0x3fb8aa3b, v13
	v_exp_f32_e32 v16, v14
	v_exp_f32_e32 v18, v13
	s_mov_b64 exec, 0xffff
	global_store_dword v9, v8, s[8:9]
	s_add_u32 s8, s8, 0x200
	s_addc_u32 s9, s9, 0
	s_cmp_lg_u32 s13, 0
	s_cbranch_scc1 .Lm2_nomc5
	global_store_dword v10, v12, s[10:11] offset:20
.Lm2_nomc5:
	s_waitcnt vmcnt(40)
	v_mul_f32_e32 v22, v18, v8
	v_fma_f32 v8, v185, v16, v22
	global_load_dword v185, v9, s[6:7]
	s_add_u32 s6, s6, 0x200
	s_addc_u32 s7, s7, 0
	s_mov_b64 exec, -1
	s_waitcnt vmcnt(63)
	v_lshlrev_b32_e32 v24, 16, v110
	v_and_b32_e32 v25, 0xffff0000, v110
	v_lshlrev_b32_e32 v26, 16, v111
	v_and_b32_e32 v27, 0xffff0000, v111
	global_load_dwordx2 v[110:111], v1, s[2:3]
	s_add_u32 s2, s2, 0x8000
	s_addc_u32 s3, s3, 0
	v_pk_mul_f32 v[24:25], v[16:17], v[24:25] op_sel_hi:[0,1]
	v_pk_mul_f32 v[26:27], v[16:17], v[26:27] op_sel_hi:[0,1]
	v_pk_fma_f32 v[4:5], v[4:5], v[18:19], v[24:25] op_sel_hi:[1,0,1]
	v_pk_fma_f32 v[6:7], v[6:7], v[18:19], v[26:27] op_sel_hi:[1,0,1]
	v_mov_b32_e32 v12, v15
	v_readlane_b32 s12, v2, 6
	v_readlane_b32 s14, v3, 6
	v_cvt_pk_bf16_f32 v20, v4, v5
	v_cvt_pk_bf16_f32 v21, v6, v7
	global_store_dwordx2 v1, v[20:21], s[4:5]
	s_add_u32 s4, s4, 0x8000
	s_addc_u32 s5, s5, 0
	v_add_f32_e32 v13, s12, v12
	v_max_f32_e64 v14, s14, s14
	v_max_f32_e32 v15, v13, v14
	v_sub_f32_e32 v13, v13, v15
	v_sub_f32_e32 v14, s14, v15
	v_mul_f32_e32 v14, 0x3fb8aa3b, v14
	v_mul_f32_e32 v13, 0x3fb8aa3b, v13
	v_exp_f32_e32 v16, v14
	v_exp_f32_e32 v18, v13
	s_mov_b64 exec, 0xffff
	global_store_dword v9, v8, s[8:9]
	s_add_u32 s8, s8, 0x200
	s_addc_u32 s9, s9, 0
	s_cmp_lg_u32 s13, 0
	s_cbranch_scc1 .Lm2_nomc6
	global_store_dword v10, v12, s[10:11] offset:24
.Lm2_nomc6:
	s_waitcnt vmcnt(43)
	v_mul_f32_e32 v22, v18, v8
	v_fma_f32 v8, v186, v16, v22
	global_load_dword v186, v9, s[6:7]
	s_add_u32 s6, s6, 0x200
	s_addc_u32 s7, s7, 0
	s_mov_b64 exec, -1
	s_waitcnt vmcnt(63)
	v_lshlrev_b32_e32 v24, 16, v112
	v_and_b32_e32 v25, 0xffff0000, v112
	v_lshlrev_b32_e32 v26, 16, v113
	v_and_b32_e32 v27, 0xffff0000, v113
	global_load_dwordx2 v[112:113], v1, s[2:3]
	s_add_u32 s2, s2, 0x8000
	s_addc_u32 s3, s3, 0
	v_pk_mul_f32 v[24:25], v[16:17], v[24:25] op_sel_hi:[0,1]
	v_pk_mul_f32 v[26:27], v[16:17], v[26:27] op_sel_hi:[0,1]
	v_pk_fma_f32 v[4:5], v[4:5], v[18:19], v[24:25] op_sel_hi:[1,0,1]
	v_pk_fma_f32 v[6:7], v[6:7], v[18:19], v[26:27] op_sel_hi:[1,0,1]
	v_mov_b32_e32 v12, v15
	v_readlane_b32 s12, v2, 7
	v_readlane_b32 s14, v3, 7
	v_cvt_pk_bf16_f32 v20, v4, v5
	v_cvt_pk_bf16_f32 v21, v6, v7
	global_store_dwordx2 v1, v[20:21], s[4:5]
	s_add_u32 s4, s4, 0x8000
	s_addc_u32 s5, s5, 0
	v_add_f32_e32 v13, s12, v12
	v_max_f32_e64 v14, s14, s14
	v_max_f32_e32 v15, v13, v14
	v_sub_f32_e32 v13, v13, v15
	v_sub_f32_e32 v14, s14, v15
	v_mul_f32_e32 v14, 0x3fb8aa3b, v14
	v_mul_f32_e32 v13, 0x3fb8aa3b, v13
	v_exp_f32_e32 v16, v14
	v_exp_f32_e32 v18, v13
	s_mov_b64 exec, 0xffff
	global_store_dword v9, v8, s[8:9]
	s_add_u32 s8, s8, 0x200
	s_addc_u32 s9, s9, 0
	s_cmp_lg_u32 s13, 0
	s_cbranch_scc1 .Lm2_nomc7
	global_store_dword v10, v12, s[10:11] offset:28
.Lm2_nomc7:
	s_waitcnt vmcnt(46)
	v_mul_f32_e32 v22, v18, v8
	v_fma_f32 v8, v187, v16, v22
	global_load_dword v187, v9, s[6:7]
	s_add_u32 s6, s6, 0x200
	s_addc_u32 s7, s7, 0
	s_mov_b64 exec, -1
	s_waitcnt vmcnt(63)
	v_lshlrev_b32_e32 v24, 16, v114
	v_and_b32_e32 v25, 0xffff0000, v114
	v_lshlrev_b32_e32 v26, 16, v115
	v_and_b32_e32 v27, 0xffff0000, v115
	global_load_dwordx2 v[114:115], v1, s[2:3]
	s_add_u32 s2, s2, 0x8000
	s_addc_u32 s3, s3, 0
	v_pk_mul_f32 v[24:25], v[16:17], v[24:25] op_sel_hi:[0,1]
	v_pk_mul_f32 v[26:27], v[16:17], v[26:27] op_sel_hi:[0,1]
	v_pk_fma_f32 v[4:5], v[4:5], v[18:19], v[24:25] op_sel_hi:[1,0,1]
	v_pk_fma_f32 v[6:7], v[6:7], v[18:19], v[26:27] op_sel_hi:[1,0,1]
	v_mov_b32_e32 v12, v15
	v_readlane_b32 s12, v2, 8
	v_readlane_b32 s14, v3, 8
	v_cvt_pk_bf16_f32 v20, v4, v5
	v_cvt_pk_bf16_f32 v21, v6, v7
	global_store_dwordx2 v1, v[20:21], s[4:5]
	s_add_u32 s4, s4, 0x8000
	s_addc_u32 s5, s5, 0
	v_add_f32_e32 v13, s12, v12
	v_max_f32_e64 v14, s14, s14
	v_max_f32_e32 v15, v13, v14
	v_sub_f32_e32 v13, v13, v15
	v_sub_f32_e32 v14, s14, v15
	v_mul_f32_e32 v14, 0x3fb8aa3b, v14
	v_mul_f32_e32 v13, 0x3fb8aa3b, v13
	v_exp_f32_e32 v16, v14
	v_exp_f32_e32 v18, v13
	s_mov_b64 exec, 0xffff
	global_store_dword v9, v8, s[8:9]
	s_add_u32 s8, s8, 0x200
	s_addc_u32 s9, s9, 0
	s_cmp_lg_u32 s13, 0
	s_cbranch_scc1 .Lm2_nomc8
	global_store_dword v10, v12, s[10:11] offset:32
.Lm2_nomc8:
	s_waitcnt vmcnt(49)
	v_mul_f32_e32 v22, v18, v8
	v_fma_f32 v8, v188, v16, v22
	global_load_dword v188, v9, s[6:7]
	s_add_u32 s6, s6, 0x200
	s_addc_u32 s7, s7, 0
	s_mov_b64 exec, -1
	s_waitcnt vmcnt(63)
	v_lshlrev_b32_e32 v24, 16, v116
	v_and_b32_e32 v25, 0xffff0000, v116
	v_lshlrev_b32_e32 v26, 16, v117
	v_and_b32_e32 v27, 0xffff0000, v117
	global_load_dwordx2 v[116:117], v1, s[2:3]
	s_add_u32 s2, s2, 0x8000
	s_addc_u32 s3, s3, 0
	v_pk_mul_f32 v[24:25], v[16:17], v[24:25] op_sel_hi:[0,1]
	v_pk_mul_f32 v[26:27], v[16:17], v[26:27] op_sel_hi:[0,1]
	v_pk_fma_f32 v[4:5], v[4:5], v[18:19], v[24:25] op_sel_hi:[1,0,1]
	v_pk_fma_f32 v[6:7], v[6:7], v[18:19], v[26:27] op_sel_hi:[1,0,1]
	v_mov_b32_e32 v12, v15
	v_readlane_b32 s12, v2, 9
	v_readlane_b32 s14, v3, 9
	v_cvt_pk_bf16_f32 v20, v4, v5
	v_cvt_pk_bf16_f32 v21, v6, v7
	global_store_dwordx2 v1, v[20:21], s[4:5]
	s_add_u32 s4, s4, 0x8000
	s_addc_u32 s5, s5, 0
	v_add_f32_e32 v13, s12, v12
	v_max_f32_e64 v14, s14, s14
	v_max_f32_e32 v15, v13, v14
	v_sub_f32_e32 v13, v13, v15
	v_sub_f32_e32 v14, s14, v15
	v_mul_f32_e32 v14, 0x3fb8aa3b, v14
	v_mul_f32_e32 v13, 0x3fb8aa3b, v13
	v_exp_f32_e32 v16, v14
	v_exp_f32_e32 v18, v13
	s_mov_b64 exec, 0xffff
	global_store_dword v9, v8, s[8:9]
	s_add_u32 s8, s8, 0x200
	s_addc_u32 s9, s9, 0
	s_cmp_lg_u32 s13, 0
	s_cbranch_scc1 .Lm2_nomc9
	global_store_dword v10, v12, s[10:11] offset:36
.Lm2_nomc9:
	s_waitcnt vmcnt(52)
	v_mul_f32_e32 v22, v18, v8
	v_fma_f32 v8, v189, v16, v22
	global_load_dword v189, v9, s[6:7]
	s_add_u32 s6, s6, 0x200
	s_addc_u32 s7, s7, 0
	s_mov_b64 exec, -1
	s_waitcnt vmcnt(63)
	v_lshlrev_b32_e32 v24, 16, v118
	v_and_b32_e32 v25, 0xffff0000, v118
	v_lshlrev_b32_e32 v26, 16, v119
	v_and_b32_e32 v27, 0xffff0000, v119
	global_load_dwordx2 v[118:119], v1, s[2:3]
	s_add_u32 s2, s2, 0x8000
	s_addc_u32 s3, s3, 0
	v_pk_mul_f32 v[24:25], v[16:17], v[24:25] op_sel_hi:[0,1]
	v_pk_mul_f32 v[26:27], v[16:17], v[26:27] op_sel_hi:[0,1]
	v_pk_fma_f32 v[4:5], v[4:5], v[18:19], v[24:25] op_sel_hi:[1,0,1]
	v_pk_fma_f32 v[6:7], v[6:7], v[18:19], v[26:27] op_sel_hi:[1,0,1]
	v_mov_b32_e32 v12, v15
	v_readlane_b32 s12, v2, 10
	v_readlane_b32 s14, v3, 10
	v_cvt_pk_bf16_f32 v20, v4, v5
	v_cvt_pk_bf16_f32 v21, v6, v7
	global_store_dwordx2 v1, v[20:21], s[4:5]
	s_add_u32 s4, s4, 0x8000
	s_addc_u32 s5, s5, 0
	v_add_f32_e32 v13, s12, v12
	v_max_f32_e64 v14, s14, s14
	v_max_f32_e32 v15, v13, v14
	v_sub_f32_e32 v13, v13, v15
	v_sub_f32_e32 v14, s14, v15
	v_mul_f32_e32 v14, 0x3fb8aa3b, v14
	v_mul_f32_e32 v13, 0x3fb8aa3b, v13
	v_exp_f32_e32 v16, v14
	v_exp_f32_e32 v18, v13
	s_mov_b64 exec, 0xffff
	global_store_dword v9, v8, s[8:9]
	s_add_u32 s8, s8, 0x200
	s_addc_u32 s9, s9, 0
	s_cmp_lg_u32 s13, 0
	s_cbranch_scc1 .Lm2_nomc10
	global_store_dword v10, v12, s[10:11] offset:40
.Lm2_nomc10:
	s_waitcnt vmcnt(55)
	v_mul_f32_e32 v22, v18, v8
	v_fma_f32 v8, v190, v16, v22
	global_load_dword v190, v9, s[6:7]
	s_add_u32 s6, s6, 0x200
	s_addc_u32 s7, s7, 0
	s_mov_b64 exec, -1
	s_waitcnt vmcnt(63)
	v_lshlrev_b32_e32 v24, 16, v120
	v_and_b32_e32 v25, 0xffff0000, v120
	v_lshlrev_b32_e32 v26, 16, v121
	v_and_b32_e32 v27, 0xffff0000, v121
	global_load_dwordx2 v[120:121], v1, s[2:3]
	s_add_u32 s2, s2, 0x8000
	s_addc_u32 s3, s3, 0
	v_pk_mul_f32 v[24:25], v[16:17], v[24:25] op_sel_hi:[0,1]
	v_pk_mul_f32 v[26:27], v[16:17], v[26:27] op_sel_hi:[0,1]
	v_pk_fma_f32 v[4:5], v[4:5], v[18:19], v[24:25] op_sel_hi:[1,0,1]
	v_pk_fma_f32 v[6:7], v[6:7], v[18:19], v[26:27] op_sel_hi:[1,0,1]
	v_mov_b32_e32 v12, v15
	v_readlane_b32 s12, v2, 11
	v_readlane_b32 s14, v3, 11
	v_cvt_pk_bf16_f32 v20, v4, v5
	v_cvt_pk_bf16_f32 v21, v6, v7
	global_store_dwordx2 v1, v[20:21], s[4:5]
	s_add_u32 s4, s4, 0x8000
	s_addc_u32 s5, s5, 0
	v_add_f32_e32 v13, s12, v12
	v_max_f32_e64 v14, s14, s14
	v_max_f32_e32 v15, v13, v14
	v_sub_f32_e32 v13, v13, v15
	v_sub_f32_e32 v14, s14, v15
	v_mul_f32_e32 v14, 0x3fb8aa3b, v14
	v_mul_f32_e32 v13, 0x3fb8aa3b, v13
	v_exp_f32_e32 v16, v14
	v_exp_f32_e32 v18, v13
	s_mov_b64 exec, 0xffff
	global_store_dword v9, v8, s[8:9]
	s_add_u32 s8, s8, 0x200
	s_addc_u32 s9, s9, 0
	s_cmp_lg_u32 s13, 0
	s_cbranch_scc1 .Lm2_nomc11
	global_store_dword v10, v12, s[10:11] offset:44
.Lm2_nomc11:
	s_waitcnt vmcnt(58)
	v_mul_f32_e32 v22, v18, v8
	v_fma_f32 v8, v191, v16, v22
	global_load_dword v191, v9, s[6:7]
	s_add_u32 s6, s6, 0x200
	s_addc_u32 s7, s7, 0
	s_mov_b64 exec, -1
	s_waitcnt vmcnt(63)
	v_lshlrev_b32_e32 v24, 16, v122
	v_and_b32_e32 v25, 0xffff0000, v122
	v_lshlrev_b32_e32 v26, 16, v123
	v_and_b32_e32 v27, 0xffff0000, v123
	global_load_dwordx2 v[122:123], v1, s[2:3]
	s_add_u32 s2, s2, 0x8000
	s_addc_u32 s3, s3, 0
	v_pk_mul_f32 v[24:25], v[16:17], v[24:25] op_sel_hi:[0,1]
	v_pk_mul_f32 v[26:27], v[16:17], v[26:27] op_sel_hi:[0,1]
	v_pk_fma_f32 v[4:5], v[4:5], v[18:19], v[24:25] op_sel_hi:[1,0,1]
	v_pk_fma_f32 v[6:7], v[6:7], v[18:19], v[26:27] op_sel_hi:[1,0,1]
	v_mov_b32_e32 v12, v15
	v_readlane_b32 s12, v2, 12
	v_readlane_b32 s14, v3, 12
	v_cvt_pk_bf16_f32 v20, v4, v5
	v_cvt_pk_bf16_f32 v21, v6, v7
	global_store_dwordx2 v1, v[20:21], s[4:5]
	s_add_u32 s4, s4, 0x8000
	s_addc_u32 s5, s5, 0
	v_add_f32_e32 v13, s12, v12
	v_max_f32_e64 v14, s14, s14
	v_max_f32_e32 v15, v13, v14
	v_sub_f32_e32 v13, v13, v15
	v_sub_f32_e32 v14, s14, v15
	v_mul_f32_e32 v14, 0x3fb8aa3b, v14
	v_mul_f32_e32 v13, 0x3fb8aa3b, v13
	v_exp_f32_e32 v16, v14
	v_exp_f32_e32 v18, v13
	s_mov_b64 exec, 0xffff
	global_store_dword v9, v8, s[8:9]
	s_add_u32 s8, s8, 0x200
	s_addc_u32 s9, s9, 0
	s_cmp_lg_u32 s13, 0
	s_cbranch_scc1 .Lm2_nomc12
	global_store_dword v10, v12, s[10:11] offset:48
.Lm2_nomc12:
	s_waitcnt vmcnt(61)
	v_mul_f32_e32 v22, v18, v8
	v_fma_f32 v8, v192, v16, v22
	global_load_dword v192, v9, s[6:7]
	s_add_u32 s6, s6, 0x200
	s_addc_u32 s7, s7, 0
	s_mov_b64 exec, -1
	s_waitcnt vmcnt(63)
	v_lshlrev_b32_e32 v24, 16, v124
	v_and_b32_e32 v25, 0xffff0000, v124
	v_lshlrev_b32_e32 v26, 16, v125
	v_and_b32_e32 v27, 0xffff0000, v125
	global_load_dwordx2 v[124:125], v1, s[2:3]
	s_add_u32 s2, s2, 0x8000
	s_addc_u32 s3, s3, 0
	v_pk_mul_f32 v[24:25], v[16:17], v[24:25] op_sel_hi:[0,1]
	v_pk_mul_f32 v[26:27], v[16:17], v[26:27] op_sel_hi:[0,1]
	v_pk_fma_f32 v[4:5], v[4:5], v[18:19], v[24:25] op_sel_hi:[1,0,1]
	v_pk_fma_f32 v[6:7], v[6:7], v[18:19], v[26:27] op_sel_hi:[1,0,1]
	v_mov_b32_e32 v12, v15
	v_readlane_b32 s12, v2, 13
	v_readlane_b32 s14, v3, 13
	v_cvt_pk_bf16_f32 v20, v4, v5
	v_cvt_pk_bf16_f32 v21, v6, v7
	global_store_dwordx2 v1, v[20:21], s[4:5]
	s_add_u32 s4, s4, 0x8000
	s_addc_u32 s5, s5, 0
	v_add_f32_e32 v13, s12, v12
	v_max_f32_e64 v14, s14, s14
	v_max_f32_e32 v15, v13, v14
	v_sub_f32_e32 v13, v13, v15
	v_sub_f32_e32 v14, s14, v15
	v_mul_f32_e32 v14, 0x3fb8aa3b, v14
	v_mul_f32_e32 v13, 0x3fb8aa3b, v13
	v_exp_f32_e32 v16, v14
	v_exp_f32_e32 v18, v13
	s_mov_b64 exec, 0xffff
	global_store_dword v9, v8, s[8:9]
	s_add_u32 s8, s8, 0x200
	s_addc_u32 s9, s9, 0
	s_cmp_lg_u32 s13, 0
	s_cbranch_scc1 .Lm2_nomc13
	global_store_dword v10, v12, s[10:11] offset:52
.Lm2_nomc13:
	s_waitcnt vmcnt(63)
	v_mul_f32_e32 v22, v18, v8
	v_fma_f32 v8, v193, v16, v22
	global_load_dword v193, v9, s[6:7]
	s_add_u32 s6, s6, 0x200
	s_addc_u32 s7, s7, 0
	s_mov_b64 exec, -1
	s_waitcnt vmcnt(63)
	v_lshlrev_b32_e32 v24, 16, v126
	v_and_b32_e32 v25, 0xffff0000, v126
	v_lshlrev_b32_e32 v26, 16, v127
	v_and_b32_e32 v27, 0xffff0000, v127
	global_load_dwordx2 v[126:127], v1, s[2:3]
	s_add_u32 s2, s2, 0x8000
	s_addc_u32 s3, s3, 0
	v_pk_mul_f32 v[24:25], v[16:17], v[24:25] op_sel_hi:[0,1]
	v_pk_mul_f32 v[26:27], v[16:17], v[26:27] op_sel_hi:[0,1]
	v_pk_fma_f32 v[4:5], v[4:5], v[18:19], v[24:25] op_sel_hi:[1,0,1]
	v_pk_fma_f32 v[6:7], v[6:7], v[18:19], v[26:27] op_sel_hi:[1,0,1]
	v_mov_b32_e32 v12, v15
	v_readlane_b32 s12, v2, 14
	v_readlane_b32 s14, v3, 14
	v_cvt_pk_bf16_f32 v20, v4, v5
	v_cvt_pk_bf16_f32 v21, v6, v7
	global_store_dwordx2 v1, v[20:21], s[4:5]
	s_add_u32 s4, s4, 0x8000
	s_addc_u32 s5, s5, 0
	v_add_f32_e32 v13, s12, v12
	v_max_f32_e64 v14, s14, s14
	v_max_f32_e32 v15, v13, v14
	v_sub_f32_e32 v13, v13, v15
	v_sub_f32_e32 v14, s14, v15
	v_mul_f32_e32 v14, 0x3fb8aa3b, v14
	v_mul_f32_e32 v13, 0x3fb8aa3b, v13
	v_exp_f32_e32 v16, v14
	v_exp_f32_e32 v18, v13
	s_mov_b64 exec, 0xffff
	global_store_dword v9, v8, s[8:9]
	s_add_u32 s8, s8, 0x200
	s_addc_u32 s9, s9, 0
	s_cmp_lg_u32 s13, 0
	s_cbranch_scc1 .Lm2_nomc14
	global_store_dword v10, v12, s[10:11] offset:56
.Lm2_nomc14:
	s_waitcnt vmcnt(63)
	v_mul_f32_e32 v22, v18, v8
	v_fma_f32 v8, v194, v16, v22
	global_load_dword v194, v9, s[6:7]
	s_add_u32 s6, s6, 0x200
	s_addc_u32 s7, s7, 0
	s_mov_b64 exec, -1
	s_waitcnt vmcnt(63)
	v_lshlrev_b32_e32 v24, 16, v128
	v_and_b32_e32 v25, 0xffff0000, v128
	v_lshlrev_b32_e32 v26, 16, v129
	v_and_b32_e32 v27, 0xffff0000, v129
	global_load_dwordx2 v[128:129], v1, s[2:3]
	s_add_u32 s2, s2, 0x8000
	s_addc_u32 s3, s3, 0
	v_pk_mul_f32 v[24:25], v[16:17], v[24:25] op_sel_hi:[0,1]
	v_pk_mul_f32 v[26:27], v[16:17], v[26:27] op_sel_hi:[0,1]
	v_pk_fma_f32 v[4:5], v[4:5], v[18:19], v[24:25] op_sel_hi:[1,0,1]
	v_pk_fma_f32 v[6:7], v[6:7], v[18:19], v[26:27] op_sel_hi:[1,0,1]
	v_mov_b32_e32 v12, v15
	v_readlane_b32 s12, v2, 15
	v_readlane_b32 s14, v3, 15
	v_cvt_pk_bf16_f32 v20, v4, v5
	v_cvt_pk_bf16_f32 v21, v6, v7
	global_store_dwordx2 v1, v[20:21], s[4:5]
	s_add_u32 s4, s4, 0x8000
	s_addc_u32 s5, s5, 0
	v_add_f32_e32 v13, s12, v12
	v_max_f32_e64 v14, s14, s14
	v_max_f32_e32 v15, v13, v14
	v_sub_f32_e32 v13, v13, v15
	v_sub_f32_e32 v14, s14, v15
	v_mul_f32_e32 v14, 0x3fb8aa3b, v14
	v_mul_f32_e32 v13, 0x3fb8aa3b, v13
	v_exp_f32_e32 v16, v14
	v_exp_f32_e32 v18, v13
	s_mov_b64 exec, 0xffff
	global_store_dword v9, v8, s[8:9]
	s_add_u32 s8, s8, 0x200
	s_addc_u32 s9, s9, 0
	s_cmp_lg_u32 s13, 0
	s_cbranch_scc1 .Lm2_nomc15
	global_store_dword v10, v12, s[10:11] offset:60
.Lm2_nomc15:
	s_waitcnt vmcnt(63)
	v_mul_f32_e32 v22, v18, v8
	v_fma_f32 v8, v195, v16, v22
	global_load_dword v195, v9, s[6:7]
	s_add_u32 s6, s6, 0x200
	s_addc_u32 s7, s7, 0
	s_mov_b64 exec, -1
	s_waitcnt vmcnt(63)
	v_lshlrev_b32_e32 v24, 16, v130
	v_and_b32_e32 v25, 0xffff0000, v130
	v_lshlrev_b32_e32 v26, 16, v131
	v_and_b32_e32 v27, 0xffff0000, v131
	global_load_dwordx2 v[130:131], v1, s[2:3]
	s_add_u32 s2, s2, 0x8000
	s_addc_u32 s3, s3, 0
	v_pk_mul_f32 v[24:25], v[16:17], v[24:25] op_sel_hi:[0,1]
	v_pk_mul_f32 v[26:27], v[16:17], v[26:27] op_sel_hi:[0,1]
	v_pk_fma_f32 v[4:5], v[4:5], v[18:19], v[24:25] op_sel_hi:[1,0,1]
	v_pk_fma_f32 v[6:7], v[6:7], v[18:19], v[26:27] op_sel_hi:[1,0,1]
	v_mov_b32_e32 v12, v15
	v_readlane_b32 s12, v2, 16
	v_readlane_b32 s14, v3, 16
	v_cvt_pk_bf16_f32 v20, v4, v5
	v_cvt_pk_bf16_f32 v21, v6, v7
	global_store_dwordx2 v1, v[20:21], s[4:5]
	s_add_u32 s4, s4, 0x8000
	s_addc_u32 s5, s5, 0
	v_add_f32_e32 v13, s12, v12
	v_max_f32_e64 v14, s14, s14
	v_max_f32_e32 v15, v13, v14
	v_sub_f32_e32 v13, v13, v15
	v_sub_f32_e32 v14, s14, v15
	v_mul_f32_e32 v14, 0x3fb8aa3b, v14
	v_mul_f32_e32 v13, 0x3fb8aa3b, v13
	v_exp_f32_e32 v16, v14
	v_exp_f32_e32 v18, v13
	s_mov_b64 exec, 0xffff
	global_store_dword v9, v8, s[8:9]
	s_add_u32 s8, s8, 0x200
	s_addc_u32 s9, s9, 0
	s_cmp_lg_u32 s13, 0
	s_cbranch_scc1 .Lm2_nomc16
	global_store_dword v10, v12, s[10:11] offset:64
.Lm2_nomc16:
	s_waitcnt vmcnt(63)
	v_mul_f32_e32 v22, v18, v8
	v_fma_f32 v8, v196, v16, v22
	global_load_dword v196, v9, s[6:7]
	s_add_u32 s6, s6, 0x200
	s_addc_u32 s7, s7, 0
	s_mov_b64 exec, -1
	s_waitcnt vmcnt(63)
	v_lshlrev_b32_e32 v24, 16, v132
	v_and_b32_e32 v25, 0xffff0000, v132
	v_lshlrev_b32_e32 v26, 16, v133
	v_and_b32_e32 v27, 0xffff0000, v133
	global_load_dwordx2 v[132:133], v1, s[2:3]
	s_add_u32 s2, s2, 0x8000
	s_addc_u32 s3, s3, 0
	v_pk_mul_f32 v[24:25], v[16:17], v[24:25] op_sel_hi:[0,1]
	v_pk_mul_f32 v[26:27], v[16:17], v[26:27] op_sel_hi:[0,1]
	v_pk_fma_f32 v[4:5], v[4:5], v[18:19], v[24:25] op_sel_hi:[1,0,1]
	v_pk_fma_f32 v[6:7], v[6:7], v[18:19], v[26:27] op_sel_hi:[1,0,1]
	v_mov_b32_e32 v12, v15
	v_readlane_b32 s12, v2, 17
	v_readlane_b32 s14, v3, 17
	v_cvt_pk_bf16_f32 v20, v4, v5
	v_cvt_pk_bf16_f32 v21, v6, v7
	global_store_dwordx2 v1, v[20:21], s[4:5]
	s_add_u32 s4, s4, 0x8000
	s_addc_u32 s5, s5, 0
	v_add_f32_e32 v13, s12, v12
	v_max_f32_e64 v14, s14, s14
	v_max_f32_e32 v15, v13, v14
	v_sub_f32_e32 v13, v13, v15
	v_sub_f32_e32 v14, s14, v15
	v_mul_f32_e32 v14, 0x3fb8aa3b, v14
	v_mul_f32_e32 v13, 0x3fb8aa3b, v13
	v_exp_f32_e32 v16, v14
	v_exp_f32_e32 v18, v13
	s_mov_b64 exec, 0xffff
	global_store_dword v9, v8, s[8:9]
	s_add_u32 s8, s8, 0x200
	s_addc_u32 s9, s9, 0
	s_cmp_lg_u32 s13, 0
	s_cbranch_scc1 .Lm2_nomc17
	global_store_dword v10, v12, s[10:11] offset:68
.Lm2_nomc17:
	s_waitcnt vmcnt(63)
	v_mul_f32_e32 v22, v18, v8
	v_fma_f32 v8, v197, v16, v22
	global_load_dword v197, v9, s[6:7]
	s_add_u32 s6, s6, 0x200
	s_addc_u32 s7, s7, 0
	s_mov_b64 exec, -1
	s_waitcnt vmcnt(63)
	v_lshlrev_b32_e32 v24, 16, v134
	v_and_b32_e32 v25, 0xffff0000, v134
	v_lshlrev_b32_e32 v26, 16, v135
	v_and_b32_e32 v27, 0xffff0000, v135
	global_load_dwordx2 v[134:135], v1, s[2:3]
	s_add_u32 s2, s2, 0x8000
	s_addc_u32 s3, s3, 0
	v_pk_mul_f32 v[24:25], v[16:17], v[24:25] op_sel_hi:[0,1]
	v_pk_mul_f32 v[26:27], v[16:17], v[26:27] op_sel_hi:[0,1]
	v_pk_fma_f32 v[4:5], v[4:5], v[18:19], v[24:25] op_sel_hi:[1,0,1]
	v_pk_fma_f32 v[6:7], v[6:7], v[18:19], v[26:27] op_sel_hi:[1,0,1]
	v_mov_b32_e32 v12, v15
	v_readlane_b32 s12, v2, 18
	v_readlane_b32 s14, v3, 18
	v_cvt_pk_bf16_f32 v20, v4, v5
	v_cvt_pk_bf16_f32 v21, v6, v7
	global_store_dwordx2 v1, v[20:21], s[4:5]
	s_add_u32 s4, s4, 0x8000
	s_addc_u32 s5, s5, 0
	v_add_f32_e32 v13, s12, v12
	v_max_f32_e64 v14, s14, s14
	v_max_f32_e32 v15, v13, v14
	v_sub_f32_e32 v13, v13, v15
	v_sub_f32_e32 v14, s14, v15
	v_mul_f32_e32 v14, 0x3fb8aa3b, v14
	v_mul_f32_e32 v13, 0x3fb8aa3b, v13
	v_exp_f32_e32 v16, v14
	v_exp_f32_e32 v18, v13
	s_mov_b64 exec, 0xffff
	global_store_dword v9, v8, s[8:9]
	s_add_u32 s8, s8, 0x200
	s_addc_u32 s9, s9, 0
	s_cmp_lg_u32 s13, 0
	s_cbranch_scc1 .Lm2_nomc18
	global_store_dword v10, v12, s[10:11] offset:72
.Lm2_nomc18:
	s_waitcnt vmcnt(63)
	v_mul_f32_e32 v22, v18, v8
	v_fma_f32 v8, v198, v16, v22
	global_load_dword v198, v9, s[6:7]
	s_add_u32 s6, s6, 0x200
	s_addc_u32 s7, s7, 0
	s_mov_b64 exec, -1
	s_waitcnt vmcnt(63)
	v_lshlrev_b32_e32 v24, 16, v136
	v_and_b32_e32 v25, 0xffff0000, v136
	v_lshlrev_b32_e32 v26, 16, v137
	v_and_b32_e32 v27, 0xffff0000, v137
	global_load_dwordx2 v[136:137], v1, s[2:3]
	s_add_u32 s2, s2, 0x8000
	s_addc_u32 s3, s3, 0
	v_pk_mul_f32 v[24:25], v[16:17], v[24:25] op_sel_hi:[0,1]
	v_pk_mul_f32 v[26:27], v[16:17], v[26:27] op_sel_hi:[0,1]
	v_pk_fma_f32 v[4:5], v[4:5], v[18:19], v[24:25] op_sel_hi:[1,0,1]
	v_pk_fma_f32 v[6:7], v[6:7], v[18:19], v[26:27] op_sel_hi:[1,0,1]
	v_mov_b32_e32 v12, v15
	v_readlane_b32 s12, v2, 19
	v_readlane_b32 s14, v3, 19
	v_cvt_pk_bf16_f32 v20, v4, v5
	v_cvt_pk_bf16_f32 v21, v6, v7
	global_store_dwordx2 v1, v[20:21], s[4:5]
	s_add_u32 s4, s4, 0x8000
	s_addc_u32 s5, s5, 0
	v_add_f32_e32 v13, s12, v12
	v_max_f32_e64 v14, s14, s14
	v_max_f32_e32 v15, v13, v14
	v_sub_f32_e32 v13, v13, v15
	v_sub_f32_e32 v14, s14, v15
	v_mul_f32_e32 v14, 0x3fb8aa3b, v14
	v_mul_f32_e32 v13, 0x3fb8aa3b, v13
	v_exp_f32_e32 v16, v14
	v_exp_f32_e32 v18, v13
	s_mov_b64 exec, 0xffff
	global_store_dword v9, v8, s[8:9]
	s_add_u32 s8, s8, 0x200
	s_addc_u32 s9, s9, 0
	s_cmp_lg_u32 s13, 0
	s_cbranch_scc1 .Lm2_nomc19
	global_store_dword v10, v12, s[10:11] offset:76
.Lm2_nomc19:
	s_waitcnt vmcnt(63)
	v_mul_f32_e32 v22, v18, v8
	v_fma_f32 v8, v199, v16, v22
	global_load_dword v199, v9, s[6:7]
	s_add_u32 s6, s6, 0x200
	s_addc_u32 s7, s7, 0
	s_mov_b64 exec, -1
	s_waitcnt vmcnt(63)
	v_lshlrev_b32_e32 v24, 16, v138
	v_and_b32_e32 v25, 0xffff0000, v138
	v_lshlrev_b32_e32 v26, 16, v139
	v_and_b32_e32 v27, 0xffff0000, v139
	global_load_dwordx2 v[138:139], v1, s[2:3]
	s_add_u32 s2, s2, 0x8000
	s_addc_u32 s3, s3, 0
	v_pk_mul_f32 v[24:25], v[16:17], v[24:25] op_sel_hi:[0,1]
	v_pk_mul_f32 v[26:27], v[16:17], v[26:27] op_sel_hi:[0,1]
	v_pk_fma_f32 v[4:5], v[4:5], v[18:19], v[24:25] op_sel_hi:[1,0,1]
	v_pk_fma_f32 v[6:7], v[6:7], v[18:19], v[26:27] op_sel_hi:[1,0,1]
	v_mov_b32_e32 v12, v15
	v_readlane_b32 s12, v2, 20
	v_readlane_b32 s14, v3, 20
	v_cvt_pk_bf16_f32 v20, v4, v5
	v_cvt_pk_bf16_f32 v21, v6, v7
	global_store_dwordx2 v1, v[20:21], s[4:5]
	s_add_u32 s4, s4, 0x8000
	s_addc_u32 s5, s5, 0
	v_add_f32_e32 v13, s12, v12
	v_max_f32_e64 v14, s14, s14
	v_max_f32_e32 v15, v13, v14
	v_sub_f32_e32 v13, v13, v15
	v_sub_f32_e32 v14, s14, v15
	v_mul_f32_e32 v14, 0x3fb8aa3b, v14
	v_mul_f32_e32 v13, 0x3fb8aa3b, v13
	v_exp_f32_e32 v16, v14
	v_exp_f32_e32 v18, v13
	s_mov_b64 exec, 0xffff
	global_store_dword v9, v8, s[8:9]
	s_add_u32 s8, s8, 0x200
	s_addc_u32 s9, s9, 0
	s_cmp_lg_u32 s13, 0
	s_cbranch_scc1 .Lm2_nomc20
	global_store_dword v10, v12, s[10:11] offset:80
.Lm2_nomc20:
	s_waitcnt vmcnt(63)
	v_mul_f32_e32 v22, v18, v8
	v_fma_f32 v8, v200, v16, v22
	global_load_dword v200, v9, s[6:7]
	s_add_u32 s6, s6, 0x200
	s_addc_u32 s7, s7, 0
	s_mov_b64 exec, -1
	s_waitcnt vmcnt(63)
	v_lshlrev_b32_e32 v24, 16, v140
	v_and_b32_e32 v25, 0xffff0000, v140
	v_lshlrev_b32_e32 v26, 16, v141
	v_and_b32_e32 v27, 0xffff0000, v141
	global_load_dwordx2 v[140:141], v1, s[2:3]
	s_add_u32 s2, s2, 0x8000
	s_addc_u32 s3, s3, 0
	v_pk_mul_f32 v[24:25], v[16:17], v[24:25] op_sel_hi:[0,1]
	v_pk_mul_f32 v[26:27], v[16:17], v[26:27] op_sel_hi:[0,1]
	v_pk_fma_f32 v[4:5], v[4:5], v[18:19], v[24:25] op_sel_hi:[1,0,1]
	v_pk_fma_f32 v[6:7], v[6:7], v[18:19], v[26:27] op_sel_hi:[1,0,1]
	v_mov_b32_e32 v12, v15
	v_readlane_b32 s12, v2, 21
	v_readlane_b32 s14, v3, 21
	v_cvt_pk_bf16_f32 v20, v4, v5
	v_cvt_pk_bf16_f32 v21, v6, v7
	global_store_dwordx2 v1, v[20:21], s[4:5]
	s_add_u32 s4, s4, 0x8000
	s_addc_u32 s5, s5, 0
	v_add_f32_e32 v13, s12, v12
	v_max_f32_e64 v14, s14, s14
	v_max_f32_e32 v15, v13, v14
	v_sub_f32_e32 v13, v13, v15
	v_sub_f32_e32 v14, s14, v15
	v_mul_f32_e32 v14, 0x3fb8aa3b, v14
	v_mul_f32_e32 v13, 0x3fb8aa3b, v13
	v_exp_f32_e32 v16, v14
	v_exp_f32_e32 v18, v13
	s_mov_b64 exec, 0xffff
	global_store_dword v9, v8, s[8:9]
	s_add_u32 s8, s8, 0x200
	s_addc_u32 s9, s9, 0
	s_cmp_lg_u32 s13, 0
	s_cbranch_scc1 .Lm2_nomc21
	global_store_dword v10, v12, s[10:11] offset:84
.Lm2_nomc21:
	s_waitcnt vmcnt(63)
	v_mul_f32_e32 v22, v18, v8
	v_fma_f32 v8, v201, v16, v22
	global_load_dword v201, v9, s[6:7]
	s_add_u32 s6, s6, 0x200
	s_addc_u32 s7, s7, 0
	s_mov_b64 exec, -1
	s_waitcnt vmcnt(63)
	v_lshlrev_b32_e32 v24, 16, v142
	v_and_b32_e32 v25, 0xffff0000, v142
	v_lshlrev_b32_e32 v26, 16, v143
	v_and_b32_e32 v27, 0xffff0000, v143
	global_load_dwordx2 v[142:143], v1, s[2:3]
	s_add_u32 s2, s2, 0x8000
	s_addc_u32 s3, s3, 0
	v_pk_mul_f32 v[24:25], v[16:17], v[24:25] op_sel_hi:[0,1]
	v_pk_mul_f32 v[26:27], v[16:17], v[26:27] op_sel_hi:[0,1]
	v_pk_fma_f32 v[4:5], v[4:5], v[18:19], v[24:25] op_sel_hi:[1,0,1]
	v_pk_fma_f32 v[6:7], v[6:7], v[18:19], v[26:27] op_sel_hi:[1,0,1]
	v_mov_b32_e32 v12, v15
	v_readlane_b32 s12, v2, 22
	v_readlane_b32 s14, v3, 22
	v_cvt_pk_bf16_f32 v20, v4, v5
	v_cvt_pk_bf16_f32 v21, v6, v7
	global_store_dwordx2 v1, v[20:21], s[4:5]
	s_add_u32 s4, s4, 0x8000
	s_addc_u32 s5, s5, 0
	v_add_f32_e32 v13, s12, v12
	v_max_f32_e64 v14, s14, s14
	v_max_f32_e32 v15, v13, v14
	v_sub_f32_e32 v13, v13, v15
	v_sub_f32_e32 v14, s14, v15
	v_mul_f32_e32 v14, 0x3fb8aa3b, v14
	v_mul_f32_e32 v13, 0x3fb8aa3b, v13
	v_exp_f32_e32 v16, v14
	v_exp_f32_e32 v18, v13
	s_mov_b64 exec, 0xffff
	global_store_dword v9, v8, s[8:9]
	s_add_u32 s8, s8, 0x200
	s_addc_u32 s9, s9, 0
	s_cmp_lg_u32 s13, 0
	s_cbranch_scc1 .Lm2_nomc22
	global_store_dword v10, v12, s[10:11] offset:88
.Lm2_nomc22:
	s_waitcnt vmcnt(63)
	v_mul_f32_e32 v22, v18, v8
	v_fma_f32 v8, v202, v16, v22
	global_load_dword v202, v9, s[6:7]
	s_add_u32 s6, s6, 0x200
	s_addc_u32 s7, s7, 0
	s_mov_b64 exec, -1
	s_waitcnt vmcnt(63)
	v_lshlrev_b32_e32 v24, 16, v144
	v_and_b32_e32 v25, 0xffff0000, v144
	v_lshlrev_b32_e32 v26, 16, v145
	v_and_b32_e32 v27, 0xffff0000, v145
	global_load_dwordx2 v[144:145], v1, s[2:3]
	s_add_u32 s2, s2, 0x8000
	s_addc_u32 s3, s3, 0
	v_pk_mul_f32 v[24:25], v[16:17], v[24:25] op_sel_hi:[0,1]
	v_pk_mul_f32 v[26:27], v[16:17], v[26:27] op_sel_hi:[0,1]
	v_pk_fma_f32 v[4:5], v[4:5], v[18:19], v[24:25] op_sel_hi:[1,0,1]
	v_pk_fma_f32 v[6:7], v[6:7], v[18:19], v[26:27] op_sel_hi:[1,0,1]
	v_mov_b32_e32 v12, v15
	v_readlane_b32 s12, v2, 23
	v_readlane_b32 s14, v3, 23
	v_cvt_pk_bf16_f32 v20, v4, v5
	v_cvt_pk_bf16_f32 v21, v6, v7
	global_store_dwordx2 v1, v[20:21], s[4:5]
	s_add_u32 s4, s4, 0x8000
	s_addc_u32 s5, s5, 0
	v_add_f32_e32 v13, s12, v12
	v_max_f32_e64 v14, s14, s14
	v_max_f32_e32 v15, v13, v14
	v_sub_f32_e32 v13, v13, v15
	v_sub_f32_e32 v14, s14, v15
	v_mul_f32_e32 v14, 0x3fb8aa3b, v14
	v_mul_f32_e32 v13, 0x3fb8aa3b, v13
	v_exp_f32_e32 v16, v14
	v_exp_f32_e32 v18, v13
	s_mov_b64 exec, 0xffff
	global_store_dword v9, v8, s[8:9]
	s_add_u32 s8, s8, 0x200
	s_addc_u32 s9, s9, 0
	s_cmp_lg_u32 s13, 0
	s_cbranch_scc1 .Lm2_nomc23
	global_store_dword v10, v12, s[10:11] offset:92
.Lm2_nomc23:
	s_waitcnt vmcnt(63)
	v_mul_f32_e32 v22, v18, v8
	v_fma_f32 v8, v203, v16, v22
	global_load_dword v203, v9, s[6:7]
	s_add_u32 s6, s6, 0x200
	s_addc_u32 s7, s7, 0
	s_mov_b64 exec, -1
	s_waitcnt vmcnt(63)
	v_lshlrev_b32_e32 v24, 16, v146
	v_and_b32_e32 v25, 0xffff0000, v146
	v_lshlrev_b32_e32 v26, 16, v147
	v_and_b32_e32 v27, 0xffff0000, v147
	global_load_dwordx2 v[146:147], v1, s[2:3]
	s_add_u32 s2, s2, 0x8000
	s_addc_u32 s3, s3, 0
	v_pk_mul_f32 v[24:25], v[16:17], v[24:25] op_sel_hi:[0,1]
	v_pk_mul_f32 v[26:27], v[16:17], v[26:27] op_sel_hi:[0,1]
	v_pk_fma_f32 v[4:5], v[4:5], v[18:19], v[24:25] op_sel_hi:[1,0,1]
	v_pk_fma_f32 v[6:7], v[6:7], v[18:19], v[26:27] op_sel_hi:[1,0,1]
	v_mov_b32_e32 v12, v15
	v_readlane_b32 s12, v2, 24
	v_readlane_b32 s14, v3, 24
	v_cvt_pk_bf16_f32 v20, v4, v5
	v_cvt_pk_bf16_f32 v21, v6, v7
	global_store_dwordx2 v1, v[20:21], s[4:5]
	s_add_u32 s4, s4, 0x8000
	s_addc_u32 s5, s5, 0
	v_add_f32_e32 v13, s12, v12
	v_max_f32_e64 v14, s14, s14
	v_max_f32_e32 v15, v13, v14
	v_sub_f32_e32 v13, v13, v15
	v_sub_f32_e32 v14, s14, v15
	v_mul_f32_e32 v14, 0x3fb8aa3b, v14
	v_mul_f32_e32 v13, 0x3fb8aa3b, v13
	v_exp_f32_e32 v16, v14
	v_exp_f32_e32 v18, v13
	s_mov_b64 exec, 0xffff
	global_store_dword v9, v8, s[8:9]
	s_add_u32 s8, s8, 0x200
	s_addc_u32 s9, s9, 0
	s_cmp_lg_u32 s13, 0
	s_cbranch_scc1 .Lm2_nomc24
	global_store_dword v10, v12, s[10:11] offset:96
.Lm2_nomc24:
	s_waitcnt vmcnt(63)
	v_mul_f32_e32 v22, v18, v8
	v_fma_f32 v8, v180, v16, v22
	global_load_dword v180, v9, s[6:7]
	s_add_u32 s6, s6, 0x200
	s_addc_u32 s7, s7, 0
	s_mov_b64 exec, -1
	s_waitcnt vmcnt(63)
	v_lshlrev_b32_e32 v24, 16, v100
	v_and_b32_e32 v25, 0xffff0000, v100
	v_lshlrev_b32_e32 v26, 16, v101
	v_and_b32_e32 v27, 0xffff0000, v101
	global_load_dwordx2 v[100:101], v1, s[2:3]
	s_add_u32 s2, s2, 0x8000
	s_addc_u32 s3, s3, 0
	v_pk_mul_f32 v[24:25], v[16:17], v[24:25] op_sel_hi:[0,1]
	v_pk_mul_f32 v[26:27], v[16:17], v[26:27] op_sel_hi:[0,1]
	v_pk_fma_f32 v[4:5], v[4:5], v[18:19], v[24:25] op_sel_hi:[1,0,1]
	v_pk_fma_f32 v[6:7], v[6:7], v[18:19], v[26:27] op_sel_hi:[1,0,1]
	v_mov_b32_e32 v12, v15
	v_readlane_b32 s12, v2, 25
	v_readlane_b32 s14, v3, 25
	v_cvt_pk_bf16_f32 v20, v4, v5
	v_cvt_pk_bf16_f32 v21, v6, v7
	global_store_dwordx2 v1, v[20:21], s[4:5]
	s_add_u32 s4, s4, 0x8000
	s_addc_u32 s5, s5, 0
	v_add_f32_e32 v13, s12, v12
	v_max_f32_e64 v14, s14, s14
	v_max_f32_e32 v15, v13, v14
	v_sub_f32_e32 v13, v13, v15
	v_sub_f32_e32 v14, s14, v15
	v_mul_f32_e32 v14, 0x3fb8aa3b, v14
	v_mul_f32_e32 v13, 0x3fb8aa3b, v13
	v_exp_f32_e32 v16, v14
	v_exp_f32_e32 v18, v13
	s_mov_b64 exec, 0xffff
	global_store_dword v9, v8, s[8:9]
	s_add_u32 s8, s8, 0x200
	s_addc_u32 s9, s9, 0
	s_cmp_lg_u32 s13, 0
	s_cbranch_scc1 .Lm2_nomc25
	global_store_dword v10, v12, s[10:11] offset:100
.Lm2_nomc25:
	s_waitcnt vmcnt(63)
	v_mul_f32_e32 v22, v18, v8
	v_fma_f32 v8, v181, v16, v22
	global_load_dword v181, v9, s[6:7]
	s_add_u32 s6, s6, 0x200
	s_addc_u32 s7, s7, 0
	s_mov_b64 exec, -1
	s_waitcnt vmcnt(63)
	v_lshlrev_b32_e32 v24, 16, v102
	v_and_b32_e32 v25, 0xffff0000, v102
	v_lshlrev_b32_e32 v26, 16, v103
	v_and_b32_e32 v27, 0xffff0000, v103
	global_load_dwordx2 v[102:103], v1, s[2:3]
	s_add_u32 s2, s2, 0x8000
	s_addc_u32 s3, s3, 0
	v_pk_mul_f32 v[24:25], v[16:17], v[24:25] op_sel_hi:[0,1]
	v_pk_mul_f32 v[26:27], v[16:17], v[26:27] op_sel_hi:[0,1]
	v_pk_fma_f32 v[4:5], v[4:5], v[18:19], v[24:25] op_sel_hi:[1,0,1]
	v_pk_fma_f32 v[6:7], v[6:7], v[18:19], v[26:27] op_sel_hi:[1,0,1]
	v_mov_b32_e32 v12, v15
	v_readlane_b32 s12, v2, 26
	v_readlane_b32 s14, v3, 26
	v_cvt_pk_bf16_f32 v20, v4, v5
	v_cvt_pk_bf16_f32 v21, v6, v7
	global_store_dwordx2 v1, v[20:21], s[4:5]
	s_add_u32 s4, s4, 0x8000
	s_addc_u32 s5, s5, 0
	v_add_f32_e32 v13, s12, v12
	v_max_f32_e64 v14, s14, s14
	v_max_f32_e32 v15, v13, v14
	v_sub_f32_e32 v13, v13, v15
	v_sub_f32_e32 v14, s14, v15
	v_mul_f32_e32 v14, 0x3fb8aa3b, v14
	v_mul_f32_e32 v13, 0x3fb8aa3b, v13
	v_exp_f32_e32 v16, v14
	v_exp_f32_e32 v18, v13
	s_mov_b64 exec, 0xffff
	global_store_dword v9, v8, s[8:9]
	s_add_u32 s8, s8, 0x200
	s_addc_u32 s9, s9, 0
	s_cmp_lg_u32 s13, 0
	s_cbranch_scc1 .Lm2_nomc26
	global_store_dword v10, v12, s[10:11] offset:104
.Lm2_nomc26:
	s_waitcnt vmcnt(63)
	v_mul_f32_e32 v22, v18, v8
	v_fma_f32 v8, v182, v16, v22
	global_load_dword v182, v9, s[6:7]
	s_add_u32 s6, s6, 0x200
	s_addc_u32 s7, s7, 0
	s_mov_b64 exec, -1
	s_waitcnt vmcnt(63)
	v_lshlrev_b32_e32 v24, 16, v104
	v_and_b32_e32 v25, 0xffff0000, v104
	v_lshlrev_b32_e32 v26, 16, v105
	v_and_b32_e32 v27, 0xffff0000, v105
	global_load_dwordx2 v[104:105], v1, s[2:3]
	s_add_u32 s2, s2, 0x8000
	s_addc_u32 s3, s3, 0
	v_pk_mul_f32 v[24:25], v[16:17], v[24:25] op_sel_hi:[0,1]
	v_pk_mul_f32 v[26:27], v[16:17], v[26:27] op_sel_hi:[0,1]
	v_pk_fma_f32 v[4:5], v[4:5], v[18:19], v[24:25] op_sel_hi:[1,0,1]
	v_pk_fma_f32 v[6:7], v[6:7], v[18:19], v[26:27] op_sel_hi:[1,0,1]
	v_mov_b32_e32 v12, v15
	v_readlane_b32 s12, v2, 27
	v_readlane_b32 s14, v3, 27
	v_cvt_pk_bf16_f32 v20, v4, v5
	v_cvt_pk_bf16_f32 v21, v6, v7
	global_store_dwordx2 v1, v[20:21], s[4:5]
	s_add_u32 s4, s4, 0x8000
	s_addc_u32 s5, s5, 0
	v_add_f32_e32 v13, s12, v12
	v_max_f32_e64 v14, s14, s14
	v_max_f32_e32 v15, v13, v14
	v_sub_f32_e32 v13, v13, v15
	v_sub_f32_e32 v14, s14, v15
	v_mul_f32_e32 v14, 0x3fb8aa3b, v14
	v_mul_f32_e32 v13, 0x3fb8aa3b, v13
	v_exp_f32_e32 v16, v14
	v_exp_f32_e32 v18, v13
	s_mov_b64 exec, 0xffff
	global_store_dword v9, v8, s[8:9]
	s_add_u32 s8, s8, 0x200
	s_addc_u32 s9, s9, 0
	s_cmp_lg_u32 s13, 0
	s_cbranch_scc1 .Lm2_nomc27
	global_store_dword v10, v12, s[10:11] offset:108
.Lm2_nomc27:
	s_waitcnt vmcnt(63)
	v_mul_f32_e32 v22, v18, v8
	v_fma_f32 v8, v183, v16, v22
	global_load_dword v183, v9, s[6:7]
	s_add_u32 s6, s6, 0x200
	s_addc_u32 s7, s7, 0
	s_mov_b64 exec, -1
	s_waitcnt vmcnt(63)
	v_lshlrev_b32_e32 v24, 16, v106
	v_and_b32_e32 v25, 0xffff0000, v106
	v_lshlrev_b32_e32 v26, 16, v107
	v_and_b32_e32 v27, 0xffff0000, v107
	global_load_dwordx2 v[106:107], v1, s[2:3]
	s_add_u32 s2, s2, 0x8000
	s_addc_u32 s3, s3, 0
	v_pk_mul_f32 v[24:25], v[16:17], v[24:25] op_sel_hi:[0,1]
	v_pk_mul_f32 v[26:27], v[16:17], v[26:27] op_sel_hi:[0,1]
	v_pk_fma_f32 v[4:5], v[4:5], v[18:19], v[24:25] op_sel_hi:[1,0,1]
	v_pk_fma_f32 v[6:7], v[6:7], v[18:19], v[26:27] op_sel_hi:[1,0,1]
	v_mov_b32_e32 v12, v15
	v_readlane_b32 s12, v2, 28
	v_readlane_b32 s14, v3, 28
	v_cvt_pk_bf16_f32 v20, v4, v5
	v_cvt_pk_bf16_f32 v21, v6, v7
	global_store_dwordx2 v1, v[20:21], s[4:5]
	s_add_u32 s4, s4, 0x8000
	s_addc_u32 s5, s5, 0
	v_add_f32_e32 v13, s12, v12
	v_max_f32_e64 v14, s14, s14
	v_max_f32_e32 v15, v13, v14
	v_sub_f32_e32 v13, v13, v15
	v_sub_f32_e32 v14, s14, v15
	v_mul_f32_e32 v14, 0x3fb8aa3b, v14
	v_mul_f32_e32 v13, 0x3fb8aa3b, v13
	v_exp_f32_e32 v16, v14
	v_exp_f32_e32 v18, v13
	s_mov_b64 exec, 0xffff
	global_store_dword v9, v8, s[8:9]
	s_add_u32 s8, s8, 0x200
	s_addc_u32 s9, s9, 0
	s_cmp_lg_u32 s13, 0
	s_cbranch_scc1 .Lm2_nomc28
	global_store_dword v10, v12, s[10:11] offset:112
.Lm2_nomc28:
	s_waitcnt vmcnt(63)
	v_mul_f32_e32 v22, v18, v8
	v_fma_f32 v8, v184, v16, v22
	global_load_dword v184, v9, s[6:7]
	s_add_u32 s6, s6, 0x200
	s_addc_u32 s7, s7, 0
	s_mov_b64 exec, -1
	s_waitcnt vmcnt(63)
	v_lshlrev_b32_e32 v24, 16, v108
	v_and_b32_e32 v25, 0xffff0000, v108
	v_lshlrev_b32_e32 v26, 16, v109
	v_and_b32_e32 v27, 0xffff0000, v109
	global_load_dwordx2 v[108:109], v1, s[2:3]
	s_add_u32 s2, s2, 0x8000
	s_addc_u32 s3, s3, 0
	v_pk_mul_f32 v[24:25], v[16:17], v[24:25] op_sel_hi:[0,1]
	v_pk_mul_f32 v[26:27], v[16:17], v[26:27] op_sel_hi:[0,1]
	v_pk_fma_f32 v[4:5], v[4:5], v[18:19], v[24:25] op_sel_hi:[1,0,1]
	v_pk_fma_f32 v[6:7], v[6:7], v[18:19], v[26:27] op_sel_hi:[1,0,1]
	v_mov_b32_e32 v12, v15
	v_readlane_b32 s12, v2, 29
	v_readlane_b32 s14, v3, 29
	v_cvt_pk_bf16_f32 v20, v4, v5
	v_cvt_pk_bf16_f32 v21, v6, v7
	global_store_dwordx2 v1, v[20:21], s[4:5]
	s_add_u32 s4, s4, 0x8000
	s_addc_u32 s5, s5, 0
	v_add_f32_e32 v13, s12, v12
	v_max_f32_e64 v14, s14, s14
	v_max_f32_e32 v15, v13, v14
	v_sub_f32_e32 v13, v13, v15
	v_sub_f32_e32 v14, s14, v15
	v_mul_f32_e32 v14, 0x3fb8aa3b, v14
	v_mul_f32_e32 v13, 0x3fb8aa3b, v13
	v_exp_f32_e32 v16, v14
	v_exp_f32_e32 v18, v13
	s_mov_b64 exec, 0xffff
	global_store_dword v9, v8, s[8:9]
	s_add_u32 s8, s8, 0x200
	s_addc_u32 s9, s9, 0
	s_cmp_lg_u32 s13, 0
	s_cbranch_scc1 .Lm2_nomc29
	global_store_dword v10, v12, s[10:11] offset:116
.Lm2_nomc29:
	s_waitcnt vmcnt(63)
	v_mul_f32_e32 v22, v18, v8
	v_fma_f32 v8, v185, v16, v22
	global_load_dword v185, v9, s[6:7]
	s_add_u32 s6, s6, 0x200
	s_addc_u32 s7, s7, 0
	s_mov_b64 exec, -1
	s_waitcnt vmcnt(63)
	v_lshlrev_b32_e32 v24, 16, v110
	v_and_b32_e32 v25, 0xffff0000, v110
	v_lshlrev_b32_e32 v26, 16, v111
	v_and_b32_e32 v27, 0xffff0000, v111
	global_load_dwordx2 v[110:111], v1, s[2:3]
	s_add_u32 s2, s2, 0x8000
	s_addc_u32 s3, s3, 0
	v_pk_mul_f32 v[24:25], v[16:17], v[24:25] op_sel_hi:[0,1]
	v_pk_mul_f32 v[26:27], v[16:17], v[26:27] op_sel_hi:[0,1]
	v_pk_fma_f32 v[4:5], v[4:5], v[18:19], v[24:25] op_sel_hi:[1,0,1]
	v_pk_fma_f32 v[6:7], v[6:7], v[18:19], v[26:27] op_sel_hi:[1,0,1]
	v_mov_b32_e32 v12, v15
	v_readlane_b32 s12, v2, 30
	v_readlane_b32 s14, v3, 30
	v_cvt_pk_bf16_f32 v20, v4, v5
	v_cvt_pk_bf16_f32 v21, v6, v7
	global_store_dwordx2 v1, v[20:21], s[4:5]
	s_add_u32 s4, s4, 0x8000
	s_addc_u32 s5, s5, 0
	v_add_f32_e32 v13, s12, v12
	v_max_f32_e64 v14, s14, s14
	v_max_f32_e32 v15, v13, v14
	v_sub_f32_e32 v13, v13, v15
	v_sub_f32_e32 v14, s14, v15
	v_mul_f32_e32 v14, 0x3fb8aa3b, v14
	v_mul_f32_e32 v13, 0x3fb8aa3b, v13
	v_exp_f32_e32 v16, v14
	v_exp_f32_e32 v18, v13
	s_mov_b64 exec, 0xffff
	global_store_dword v9, v8, s[8:9]
	s_add_u32 s8, s8, 0x200
	s_addc_u32 s9, s9, 0
	s_cmp_lg_u32 s13, 0
	s_cbranch_scc1 .Lm2_nomc30
	global_store_dword v10, v12, s[10:11] offset:120
.Lm2_nomc30:
	s_waitcnt vmcnt(63)
	v_mul_f32_e32 v22, v18, v8
	v_fma_f32 v8, v186, v16, v22
	global_load_dword v186, v9, s[6:7]
	s_add_u32 s6, s6, 0x200
	s_addc_u32 s7, s7, 0
	s_mov_b64 exec, -1
	s_waitcnt vmcnt(63)
	v_lshlrev_b32_e32 v24, 16, v112
	v_and_b32_e32 v25, 0xffff0000, v112
	v_lshlrev_b32_e32 v26, 16, v113
	v_and_b32_e32 v27, 0xffff0000, v113
	global_load_dwordx2 v[112:113], v1, s[2:3]
	s_add_u32 s2, s2, 0x8000
	s_addc_u32 s3, s3, 0
	v_pk_mul_f32 v[24:25], v[16:17], v[24:25] op_sel_hi:[0,1]
	v_pk_mul_f32 v[26:27], v[16:17], v[26:27] op_sel_hi:[0,1]
	v_pk_fma_f32 v[4:5], v[4:5], v[18:19], v[24:25] op_sel_hi:[1,0,1]
	v_pk_fma_f32 v[6:7], v[6:7], v[18:19], v[26:27] op_sel_hi:[1,0,1]
	v_mov_b32_e32 v12, v15
	v_readlane_b32 s12, v2, 31
	v_readlane_b32 s14, v3, 31
	v_cvt_pk_bf16_f32 v20, v4, v5
	v_cvt_pk_bf16_f32 v21, v6, v7
	global_store_dwordx2 v1, v[20:21], s[4:5]
	s_add_u32 s4, s4, 0x8000
	s_addc_u32 s5, s5, 0
	v_add_f32_e32 v13, s12, v12
	v_max_f32_e64 v14, s14, s14
	v_max_f32_e32 v15, v13, v14
	v_sub_f32_e32 v13, v13, v15
	v_sub_f32_e32 v14, s14, v15
	v_mul_f32_e32 v14, 0x3fb8aa3b, v14
	v_mul_f32_e32 v13, 0x3fb8aa3b, v13
	v_exp_f32_e32 v16, v14
	v_exp_f32_e32 v18, v13
	s_mov_b64 exec, 0xffff
	global_store_dword v9, v8, s[8:9]
	s_add_u32 s8, s8, 0x200
	s_addc_u32 s9, s9, 0
	s_cmp_lg_u32 s13, 0
	s_cbranch_scc1 .Lm2_nomc31
	global_store_dword v10, v12, s[10:11] offset:124
.Lm2_nomc31:
	s_waitcnt vmcnt(63)
	v_mul_f32_e32 v22, v18, v8
	v_fma_f32 v8, v187, v16, v22
	global_load_dword v187, v9, s[6:7]
	s_add_u32 s6, s6, 0x200
	s_addc_u32 s7, s7, 0
	s_mov_b64 exec, -1
	s_waitcnt vmcnt(63)
	v_lshlrev_b32_e32 v24, 16, v114
	v_and_b32_e32 v25, 0xffff0000, v114
	v_lshlrev_b32_e32 v26, 16, v115
	v_and_b32_e32 v27, 0xffff0000, v115
	global_load_dwordx2 v[114:115], v1, s[2:3]
	s_add_u32 s2, s2, 0x8000
	s_addc_u32 s3, s3, 0
	v_pk_mul_f32 v[24:25], v[16:17], v[24:25] op_sel_hi:[0,1]
	v_pk_mul_f32 v[26:27], v[16:17], v[26:27] op_sel_hi:[0,1]
	v_pk_fma_f32 v[4:5], v[4:5], v[18:19], v[24:25] op_sel_hi:[1,0,1]
	v_pk_fma_f32 v[6:7], v[6:7], v[18:19], v[26:27] op_sel_hi:[1,0,1]
	v_mov_b32_e32 v12, v15
	v_readlane_b32 s12, v2, 32
	v_readlane_b32 s14, v3, 32
	v_cvt_pk_bf16_f32 v20, v4, v5
	v_cvt_pk_bf16_f32 v21, v6, v7
	global_store_dwordx2 v1, v[20:21], s[4:5]
	s_add_u32 s4, s4, 0x8000
	s_addc_u32 s5, s5, 0
	v_add_f32_e32 v13, s12, v12
	v_max_f32_e64 v14, s14, s14
	v_max_f32_e32 v15, v13, v14
	v_sub_f32_e32 v13, v13, v15
	v_sub_f32_e32 v14, s14, v15
	v_mul_f32_e32 v14, 0x3fb8aa3b, v14
	v_mul_f32_e32 v13, 0x3fb8aa3b, v13
	v_exp_f32_e32 v16, v14
	v_exp_f32_e32 v18, v13
	s_mov_b64 exec, 0xffff
	global_store_dword v9, v8, s[8:9]
	s_add_u32 s8, s8, 0x200
	s_addc_u32 s9, s9, 0
	s_cmp_lg_u32 s13, 0
	s_cbranch_scc1 .Lm2_nomc32
	global_store_dword v10, v12, s[10:11] offset:128
.Lm2_nomc32:
	s_waitcnt vmcnt(63)
	v_mul_f32_e32 v22, v18, v8
	v_fma_f32 v8, v188, v16, v22
	global_load_dword v188, v9, s[6:7]
	s_add_u32 s6, s6, 0x200
	s_addc_u32 s7, s7, 0
	s_mov_b64 exec, -1
	s_waitcnt vmcnt(63)
	v_lshlrev_b32_e32 v24, 16, v116
	v_and_b32_e32 v25, 0xffff0000, v116
	v_lshlrev_b32_e32 v26, 16, v117
	v_and_b32_e32 v27, 0xffff0000, v117
	global_load_dwordx2 v[116:117], v1, s[2:3]
	s_add_u32 s2, s2, 0x8000
	s_addc_u32 s3, s3, 0
	v_pk_mul_f32 v[24:25], v[16:17], v[24:25] op_sel_hi:[0,1]
	v_pk_mul_f32 v[26:27], v[16:17], v[26:27] op_sel_hi:[0,1]
	v_pk_fma_f32 v[4:5], v[4:5], v[18:19], v[24:25] op_sel_hi:[1,0,1]
	v_pk_fma_f32 v[6:7], v[6:7], v[18:19], v[26:27] op_sel_hi:[1,0,1]
	v_mov_b32_e32 v12, v15
	v_readlane_b32 s12, v2, 33
	v_readlane_b32 s14, v3, 33
	v_cvt_pk_bf16_f32 v20, v4, v5
	v_cvt_pk_bf16_f32 v21, v6, v7
	global_store_dwordx2 v1, v[20:21], s[4:5]
	s_add_u32 s4, s4, 0x8000
	s_addc_u32 s5, s5, 0
	v_add_f32_e32 v13, s12, v12
	v_max_f32_e64 v14, s14, s14
	v_max_f32_e32 v15, v13, v14
	v_sub_f32_e32 v13, v13, v15
	v_sub_f32_e32 v14, s14, v15
	v_mul_f32_e32 v14, 0x3fb8aa3b, v14
	v_mul_f32_e32 v13, 0x3fb8aa3b, v13
	v_exp_f32_e32 v16, v14
	v_exp_f32_e32 v18, v13
	s_mov_b64 exec, 0xffff
	global_store_dword v9, v8, s[8:9]
	s_add_u32 s8, s8, 0x200
	s_addc_u32 s9, s9, 0
	s_cmp_lg_u32 s13, 0
	s_cbranch_scc1 .Lm2_nomc33
	global_store_dword v10, v12, s[10:11] offset:132
.Lm2_nomc33:
	s_waitcnt vmcnt(63)
	v_mul_f32_e32 v22, v18, v8
	v_fma_f32 v8, v189, v16, v22
	global_load_dword v189, v9, s[6:7]
	s_add_u32 s6, s6, 0x200
	s_addc_u32 s7, s7, 0
	s_mov_b64 exec, -1
	s_waitcnt vmcnt(63)
	v_lshlrev_b32_e32 v24, 16, v118
	v_and_b32_e32 v25, 0xffff0000, v118
	v_lshlrev_b32_e32 v26, 16, v119
	v_and_b32_e32 v27, 0xffff0000, v119
	global_load_dwordx2 v[118:119], v1, s[2:3]
	s_add_u32 s2, s2, 0x8000
	s_addc_u32 s3, s3, 0
	v_pk_mul_f32 v[24:25], v[16:17], v[24:25] op_sel_hi:[0,1]
	v_pk_mul_f32 v[26:27], v[16:17], v[26:27] op_sel_hi:[0,1]
	v_pk_fma_f32 v[4:5], v[4:5], v[18:19], v[24:25] op_sel_hi:[1,0,1]
	v_pk_fma_f32 v[6:7], v[6:7], v[18:19], v[26:27] op_sel_hi:[1,0,1]
	v_mov_b32_e32 v12, v15
	v_readlane_b32 s12, v2, 34
	v_readlane_b32 s14, v3, 34
	v_cvt_pk_bf16_f32 v20, v4, v5
	v_cvt_pk_bf16_f32 v21, v6, v7
	global_store_dwordx2 v1, v[20:21], s[4:5]
	s_add_u32 s4, s4, 0x8000
	s_addc_u32 s5, s5, 0
	v_add_f32_e32 v13, s12, v12
	v_max_f32_e64 v14, s14, s14
	v_max_f32_e32 v15, v13, v14
	v_sub_f32_e32 v13, v13, v15
	v_sub_f32_e32 v14, s14, v15
	v_mul_f32_e32 v14, 0x3fb8aa3b, v14
	v_mul_f32_e32 v13, 0x3fb8aa3b, v13
	v_exp_f32_e32 v16, v14
	v_exp_f32_e32 v18, v13
	s_mov_b64 exec, 0xffff
	global_store_dword v9, v8, s[8:9]
	s_add_u32 s8, s8, 0x200
	s_addc_u32 s9, s9, 0
	s_cmp_lg_u32 s13, 0
	s_cbranch_scc1 .Lm2_nomc34
	global_store_dword v10, v12, s[10:11] offset:136
.Lm2_nomc34:
	s_waitcnt vmcnt(63)
	v_mul_f32_e32 v22, v18, v8
	v_fma_f32 v8, v190, v16, v22
	global_load_dword v190, v9, s[6:7]
	s_add_u32 s6, s6, 0x200
	s_addc_u32 s7, s7, 0
	s_mov_b64 exec, -1
	s_waitcnt vmcnt(63)
	v_lshlrev_b32_e32 v24, 16, v120
	v_and_b32_e32 v25, 0xffff0000, v120
	v_lshlrev_b32_e32 v26, 16, v121
	v_and_b32_e32 v27, 0xffff0000, v121
	global_load_dwordx2 v[120:121], v1, s[2:3]
	s_add_u32 s2, s2, 0x8000
	s_addc_u32 s3, s3, 0
	v_pk_mul_f32 v[24:25], v[16:17], v[24:25] op_sel_hi:[0,1]
	v_pk_mul_f32 v[26:27], v[16:17], v[26:27] op_sel_hi:[0,1]
	v_pk_fma_f32 v[4:5], v[4:5], v[18:19], v[24:25] op_sel_hi:[1,0,1]
	v_pk_fma_f32 v[6:7], v[6:7], v[18:19], v[26:27] op_sel_hi:[1,0,1]
	v_mov_b32_e32 v12, v15
	v_readlane_b32 s12, v2, 35
	v_readlane_b32 s14, v3, 35
	v_cvt_pk_bf16_f32 v20, v4, v5
	v_cvt_pk_bf16_f32 v21, v6, v7
	global_store_dwordx2 v1, v[20:21], s[4:5]
	s_add_u32 s4, s4, 0x8000
	s_addc_u32 s5, s5, 0
	v_add_f32_e32 v13, s12, v12
	v_max_f32_e64 v14, s14, s14
	v_max_f32_e32 v15, v13, v14
	v_sub_f32_e32 v13, v13, v15
	v_sub_f32_e32 v14, s14, v15
	v_mul_f32_e32 v14, 0x3fb8aa3b, v14
	v_mul_f32_e32 v13, 0x3fb8aa3b, v13
	v_exp_f32_e32 v16, v14
	v_exp_f32_e32 v18, v13
	s_mov_b64 exec, 0xffff
	global_store_dword v9, v8, s[8:9]
	s_add_u32 s8, s8, 0x200
	s_addc_u32 s9, s9, 0
	s_cmp_lg_u32 s13, 0
	s_cbranch_scc1 .Lm2_nomc35
	global_store_dword v10, v12, s[10:11] offset:140
.Lm2_nomc35:
	s_waitcnt vmcnt(63)
	v_mul_f32_e32 v22, v18, v8
	v_fma_f32 v8, v191, v16, v22
	global_load_dword v191, v9, s[6:7]
	s_add_u32 s6, s6, 0x200
	s_addc_u32 s7, s7, 0
	s_mov_b64 exec, -1
	s_waitcnt vmcnt(63)
	v_lshlrev_b32_e32 v24, 16, v122
	v_and_b32_e32 v25, 0xffff0000, v122
	v_lshlrev_b32_e32 v26, 16, v123
	v_and_b32_e32 v27, 0xffff0000, v123
	global_load_dwordx2 v[122:123], v1, s[2:3]
	s_add_u32 s2, s2, 0x8000
	s_addc_u32 s3, s3, 0
	v_pk_mul_f32 v[24:25], v[16:17], v[24:25] op_sel_hi:[0,1]
	v_pk_mul_f32 v[26:27], v[16:17], v[26:27] op_sel_hi:[0,1]
	v_pk_fma_f32 v[4:5], v[4:5], v[18:19], v[24:25] op_sel_hi:[1,0,1]
	v_pk_fma_f32 v[6:7], v[6:7], v[18:19], v[26:27] op_sel_hi:[1,0,1]
	v_mov_b32_e32 v12, v15
	v_readlane_b32 s12, v2, 36
	v_readlane_b32 s14, v3, 36
	v_cvt_pk_bf16_f32 v20, v4, v5
	v_cvt_pk_bf16_f32 v21, v6, v7
	global_store_dwordx2 v1, v[20:21], s[4:5]
	s_add_u32 s4, s4, 0x8000
	s_addc_u32 s5, s5, 0
	v_add_f32_e32 v13, s12, v12
	v_max_f32_e64 v14, s14, s14
	v_max_f32_e32 v15, v13, v14
	v_sub_f32_e32 v13, v13, v15
	v_sub_f32_e32 v14, s14, v15
	v_mul_f32_e32 v14, 0x3fb8aa3b, v14
	v_mul_f32_e32 v13, 0x3fb8aa3b, v13
	v_exp_f32_e32 v16, v14
	v_exp_f32_e32 v18, v13
	s_mov_b64 exec, 0xffff
	global_store_dword v9, v8, s[8:9]
	s_add_u32 s8, s8, 0x200
	s_addc_u32 s9, s9, 0
	s_cmp_lg_u32 s13, 0
	s_cbranch_scc1 .Lm2_nomc36
	global_store_dword v10, v12, s[10:11] offset:144
.Lm2_nomc36:
	s_waitcnt vmcnt(63)
	v_mul_f32_e32 v22, v18, v8
	v_fma_f32 v8, v192, v16, v22
	global_load_dword v192, v9, s[6:7]
	s_add_u32 s6, s6, 0x200
	s_addc_u32 s7, s7, 0
	s_mov_b64 exec, -1
	s_waitcnt vmcnt(63)
	v_lshlrev_b32_e32 v24, 16, v124
	v_and_b32_e32 v25, 0xffff0000, v124
	v_lshlrev_b32_e32 v26, 16, v125
	v_and_b32_e32 v27, 0xffff0000, v125
	global_load_dwordx2 v[124:125], v1, s[2:3]
	s_add_u32 s2, s2, 0x8000
	s_addc_u32 s3, s3, 0
	v_pk_mul_f32 v[24:25], v[16:17], v[24:25] op_sel_hi:[0,1]
	v_pk_mul_f32 v[26:27], v[16:17], v[26:27] op_sel_hi:[0,1]
	v_pk_fma_f32 v[4:5], v[4:5], v[18:19], v[24:25] op_sel_hi:[1,0,1]
	v_pk_fma_f32 v[6:7], v[6:7], v[18:19], v[26:27] op_sel_hi:[1,0,1]
	v_mov_b32_e32 v12, v15
	v_readlane_b32 s12, v2, 37
	v_readlane_b32 s14, v3, 37
	v_cvt_pk_bf16_f32 v20, v4, v5
	v_cvt_pk_bf16_f32 v21, v6, v7
	global_store_dwordx2 v1, v[20:21], s[4:5]
	s_add_u32 s4, s4, 0x8000
	s_addc_u32 s5, s5, 0
	v_add_f32_e32 v13, s12, v12
	v_max_f32_e64 v14, s14, s14
	v_max_f32_e32 v15, v13, v14
	v_sub_f32_e32 v13, v13, v15
	v_sub_f32_e32 v14, s14, v15
	v_mul_f32_e32 v14, 0x3fb8aa3b, v14
	v_mul_f32_e32 v13, 0x3fb8aa3b, v13
	v_exp_f32_e32 v16, v14
	v_exp_f32_e32 v18, v13
	s_mov_b64 exec, 0xffff
	global_store_dword v9, v8, s[8:9]
	s_add_u32 s8, s8, 0x200
	s_addc_u32 s9, s9, 0
	s_cmp_lg_u32 s13, 0
	s_cbranch_scc1 .Lm2_nomc37
	global_store_dword v10, v12, s[10:11] offset:148
.Lm2_nomc37:
	s_waitcnt vmcnt(63)
	v_mul_f32_e32 v22, v18, v8
	v_fma_f32 v8, v193, v16, v22
	global_load_dword v193, v9, s[6:7]
	s_add_u32 s6, s6, 0x200
	s_addc_u32 s7, s7, 0
	s_mov_b64 exec, -1
	s_waitcnt vmcnt(63)
	v_lshlrev_b32_e32 v24, 16, v126
	v_and_b32_e32 v25, 0xffff0000, v126
	v_lshlrev_b32_e32 v26, 16, v127
	v_and_b32_e32 v27, 0xffff0000, v127
	global_load_dwordx2 v[126:127], v1, s[2:3]
	s_add_u32 s2, s2, 0x8000
	s_addc_u32 s3, s3, 0
	v_pk_mul_f32 v[24:25], v[16:17], v[24:25] op_sel_hi:[0,1]
	v_pk_mul_f32 v[26:27], v[16:17], v[26:27] op_sel_hi:[0,1]
	v_pk_fma_f32 v[4:5], v[4:5], v[18:19], v[24:25] op_sel_hi:[1,0,1]
	v_pk_fma_f32 v[6:7], v[6:7], v[18:19], v[26:27] op_sel_hi:[1,0,1]
	v_mov_b32_e32 v12, v15
	v_readlane_b32 s12, v2, 38
	v_readlane_b32 s14, v3, 38
	v_cvt_pk_bf16_f32 v20, v4, v5
	v_cvt_pk_bf16_f32 v21, v6, v7
	global_store_dwordx2 v1, v[20:21], s[4:5]
	s_add_u32 s4, s4, 0x8000
	s_addc_u32 s5, s5, 0
	v_add_f32_e32 v13, s12, v12
	v_max_f32_e64 v14, s14, s14
	v_max_f32_e32 v15, v13, v14
	v_sub_f32_e32 v13, v13, v15
	v_sub_f32_e32 v14, s14, v15
	v_mul_f32_e32 v14, 0x3fb8aa3b, v14
	v_mul_f32_e32 v13, 0x3fb8aa3b, v13
	v_exp_f32_e32 v16, v14
	v_exp_f32_e32 v18, v13
	s_mov_b64 exec, 0xffff
	global_store_dword v9, v8, s[8:9]
	s_add_u32 s8, s8, 0x200
	s_addc_u32 s9, s9, 0
	s_cmp_lg_u32 s13, 0
	s_cbranch_scc1 .Lm2_nomc38
	global_store_dword v10, v12, s[10:11] offset:152
.Lm2_nomc38:
	s_waitcnt vmcnt(63)
	v_mul_f32_e32 v22, v18, v8
	v_fma_f32 v8, v194, v16, v22
	global_load_dword v194, v9, s[6:7]
	s_add_u32 s6, s6, 0x200
	s_addc_u32 s7, s7, 0
	s_mov_b64 exec, -1
	s_waitcnt vmcnt(63)
	v_lshlrev_b32_e32 v24, 16, v128
	v_and_b32_e32 v25, 0xffff0000, v128
	v_lshlrev_b32_e32 v26, 16, v129
	v_and_b32_e32 v27, 0xffff0000, v129
	global_load_dwordx2 v[128:129], v1, s[2:3]
	s_add_u32 s2, s2, 0x8000
	s_addc_u32 s3, s3, 0
	v_pk_mul_f32 v[24:25], v[16:17], v[24:25] op_sel_hi:[0,1]
	v_pk_mul_f32 v[26:27], v[16:17], v[26:27] op_sel_hi:[0,1]
	v_pk_fma_f32 v[4:5], v[4:5], v[18:19], v[24:25] op_sel_hi:[1,0,1]
	v_pk_fma_f32 v[6:7], v[6:7], v[18:19], v[26:27] op_sel_hi:[1,0,1]
	v_mov_b32_e32 v12, v15
	v_readlane_b32 s12, v2, 39
	v_readlane_b32 s14, v3, 39
	v_cvt_pk_bf16_f32 v20, v4, v5
	v_cvt_pk_bf16_f32 v21, v6, v7
	global_store_dwordx2 v1, v[20:21], s[4:5]
	s_add_u32 s4, s4, 0x8000
	s_addc_u32 s5, s5, 0
	v_add_f32_e32 v13, s12, v12
	v_max_f32_e64 v14, s14, s14
	v_max_f32_e32 v15, v13, v14
	v_sub_f32_e32 v13, v13, v15
	v_sub_f32_e32 v14, s14, v15
	v_mul_f32_e32 v14, 0x3fb8aa3b, v14
	v_mul_f32_e32 v13, 0x3fb8aa3b, v13
	v_exp_f32_e32 v16, v14
	v_exp_f32_e32 v18, v13
	s_mov_b64 exec, 0xffff
	global_store_dword v9, v8, s[8:9]
	s_add_u32 s8, s8, 0x200
	s_addc_u32 s9, s9, 0
	s_cmp_lg_u32 s13, 0
	s_cbranch_scc1 .Lm2_nomc39
	global_store_dword v10, v12, s[10:11] offset:156
.Lm2_nomc39:
	s_waitcnt vmcnt(63)
	v_mul_f32_e32 v22, v18, v8
	v_fma_f32 v8, v195, v16, v22
	global_load_dword v195, v9, s[6:7]
	s_add_u32 s6, s6, 0x200
	s_addc_u32 s7, s7, 0
	s_mov_b64 exec, -1
	s_waitcnt vmcnt(63)
	v_lshlrev_b32_e32 v24, 16, v130
	v_and_b32_e32 v25, 0xffff0000, v130
	v_lshlrev_b32_e32 v26, 16, v131
	v_and_b32_e32 v27, 0xffff0000, v131
	global_load_dwordx2 v[130:131], v1, s[2:3]
	s_add_u32 s2, s2, 0x8000
	s_addc_u32 s3, s3, 0
	v_pk_mul_f32 v[24:25], v[16:17], v[24:25] op_sel_hi:[0,1]
	v_pk_mul_f32 v[26:27], v[16:17], v[26:27] op_sel_hi:[0,1]
	v_pk_fma_f32 v[4:5], v[4:5], v[18:19], v[24:25] op_sel_hi:[1,0,1]
	v_pk_fma_f32 v[6:7], v[6:7], v[18:19], v[26:27] op_sel_hi:[1,0,1]
	v_mov_b32_e32 v12, v15
	v_readlane_b32 s12, v2, 40
	v_readlane_b32 s14, v3, 40
	v_cvt_pk_bf16_f32 v20, v4, v5
	v_cvt_pk_bf16_f32 v21, v6, v7
	global_store_dwordx2 v1, v[20:21], s[4:5]
	s_add_u32 s4, s4, 0x8000
	s_addc_u32 s5, s5, 0
	v_add_f32_e32 v13, s12, v12
	v_max_f32_e64 v14, s14, s14
	v_max_f32_e32 v15, v13, v14
	v_sub_f32_e32 v13, v13, v15
	v_sub_f32_e32 v14, s14, v15
	v_mul_f32_e32 v14, 0x3fb8aa3b, v14
	v_mul_f32_e32 v13, 0x3fb8aa3b, v13
	v_exp_f32_e32 v16, v14
	v_exp_f32_e32 v18, v13
	s_mov_b64 exec, 0xffff
	global_store_dword v9, v8, s[8:9]
	s_add_u32 s8, s8, 0x200
	s_addc_u32 s9, s9, 0
	s_cmp_lg_u32 s13, 0
	s_cbranch_scc1 .Lm2_nomc40
	global_store_dword v10, v12, s[10:11] offset:160
.Lm2_nomc40:
	s_waitcnt vmcnt(63)
	v_mul_f32_e32 v22, v18, v8
	v_fma_f32 v8, v196, v16, v22
	s_mov_b64 exec, -1
	s_waitcnt vmcnt(63)
	v_lshlrev_b32_e32 v24, 16, v132
	v_and_b32_e32 v25, 0xffff0000, v132
	v_lshlrev_b32_e32 v26, 16, v133
	v_and_b32_e32 v27, 0xffff0000, v133
	v_pk_mul_f32 v[24:25], v[16:17], v[24:25] op_sel_hi:[0,1]
	v_pk_mul_f32 v[26:27], v[16:17], v[26:27] op_sel_hi:[0,1]
	v_pk_fma_f32 v[4:5], v[4:5], v[18:19], v[24:25] op_sel_hi:[1,0,1]
	v_pk_fma_f32 v[6:7], v[6:7], v[18:19], v[26:27] op_sel_hi:[1,0,1]
	v_mov_b32_e32 v12, v15
	v_readlane_b32 s12, v2, 41
	v_readlane_b32 s14, v3, 41
	v_cvt_pk_bf16_f32 v20, v4, v5
	v_cvt_pk_bf16_f32 v21, v6, v7
	global_store_dwordx2 v1, v[20:21], s[4:5]
	s_add_u32 s4, s4, 0x8000
	s_addc_u32 s5, s5, 0
	v_add_f32_e32 v13, s12, v12
	v_max_f32_e64 v14, s14, s14
	v_max_f32_e32 v15, v13, v14
	v_sub_f32_e32 v13, v13, v15
	v_sub_f32_e32 v14, s14, v15
	v_mul_f32_e32 v14, 0x3fb8aa3b, v14
	v_mul_f32_e32 v13, 0x3fb8aa3b, v13
	v_exp_f32_e32 v16, v14
	v_exp_f32_e32 v18, v13
	s_mov_b64 exec, 0xffff
	global_store_dword v9, v8, s[8:9]
	s_add_u32 s8, s8, 0x200
	s_addc_u32 s9, s9, 0
	s_cmp_lg_u32 s13, 0
	s_cbranch_scc1 .Lm2_nomc41
	global_store_dword v10, v12, s[10:11] offset:164
.Lm2_nomc41:
	s_waitcnt vmcnt(63)
	v_mul_f32_e32 v22, v18, v8
	v_fma_f32 v8, v197, v16, v22
	s_mov_b64 exec, -1
	s_waitcnt vmcnt(63)
	v_lshlrev_b32_e32 v24, 16, v134
	v_and_b32_e32 v25, 0xffff0000, v134
	v_lshlrev_b32_e32 v26, 16, v135
	v_and_b32_e32 v27, 0xffff0000, v135
	v_pk_mul_f32 v[24:25], v[16:17], v[24:25] op_sel_hi:[0,1]
	v_pk_mul_f32 v[26:27], v[16:17], v[26:27] op_sel_hi:[0,1]
	v_pk_fma_f32 v[4:5], v[4:5], v[18:19], v[24:25] op_sel_hi:[1,0,1]
	v_pk_fma_f32 v[6:7], v[6:7], v[18:19], v[26:27] op_sel_hi:[1,0,1]
	v_mov_b32_e32 v12, v15
	v_readlane_b32 s12, v2, 42
	v_readlane_b32 s14, v3, 42
	v_cvt_pk_bf16_f32 v20, v4, v5
	v_cvt_pk_bf16_f32 v21, v6, v7
	global_store_dwordx2 v1, v[20:21], s[4:5]
	s_add_u32 s4, s4, 0x8000
	s_addc_u32 s5, s5, 0
	v_add_f32_e32 v13, s12, v12
	v_max_f32_e64 v14, s14, s14
	v_max_f32_e32 v15, v13, v14
	v_sub_f32_e32 v13, v13, v15
	v_sub_f32_e32 v14, s14, v15
	v_mul_f32_e32 v14, 0x3fb8aa3b, v14
	v_mul_f32_e32 v13, 0x3fb8aa3b, v13
	v_exp_f32_e32 v16, v14
	v_exp_f32_e32 v18, v13
	s_mov_b64 exec, 0xffff
	global_store_dword v9, v8, s[8:9]
	s_add_u32 s8, s8, 0x200
	s_addc_u32 s9, s9, 0
	s_cmp_lg_u32 s13, 0
	s_cbranch_scc1 .Lm2_nomc42
	global_store_dword v10, v12, s[10:11] offset:168
.Lm2_nomc42:
	s_waitcnt vmcnt(63)
	v_mul_f32_e32 v22, v18, v8
	v_fma_f32 v8, v198, v16, v22
	s_mov_b64 exec, -1
	s_waitcnt vmcnt(63)
	v_lshlrev_b32_e32 v24, 16, v136
	v_and_b32_e32 v25, 0xffff0000, v136
	v_lshlrev_b32_e32 v26, 16, v137
	v_and_b32_e32 v27, 0xffff0000, v137
	v_pk_mul_f32 v[24:25], v[16:17], v[24:25] op_sel_hi:[0,1]
	v_pk_mul_f32 v[26:27], v[16:17], v[26:27] op_sel_hi:[0,1]
	v_pk_fma_f32 v[4:5], v[4:5], v[18:19], v[24:25] op_sel_hi:[1,0,1]
	v_pk_fma_f32 v[6:7], v[6:7], v[18:19], v[26:27] op_sel_hi:[1,0,1]
	v_mov_b32_e32 v12, v15
	v_readlane_b32 s12, v2, 43
	v_readlane_b32 s14, v3, 43
	v_cvt_pk_bf16_f32 v20, v4, v5
	v_cvt_pk_bf16_f32 v21, v6, v7
	global_store_dwordx2 v1, v[20:21], s[4:5]
	s_add_u32 s4, s4, 0x8000
	s_addc_u32 s5, s5, 0
	v_add_f32_e32 v13, s12, v12
	v_max_f32_e64 v14, s14, s14
	v_max_f32_e32 v15, v13, v14
	v_sub_f32_e32 v13, v13, v15
	v_sub_f32_e32 v14, s14, v15
	v_mul_f32_e32 v14, 0x3fb8aa3b, v14
	v_mul_f32_e32 v13, 0x3fb8aa3b, v13
	v_exp_f32_e32 v16, v14
	v_exp_f32_e32 v18, v13
	s_mov_b64 exec, 0xffff
	global_store_dword v9, v8, s[8:9]
	s_add_u32 s8, s8, 0x200
	s_addc_u32 s9, s9, 0
	s_cmp_lg_u32 s13, 0
	s_cbranch_scc1 .Lm2_nomc43
	global_store_dword v10, v12, s[10:11] offset:172
.Lm2_nomc43:
	s_waitcnt vmcnt(63)
	v_mul_f32_e32 v22, v18, v8
	v_fma_f32 v8, v199, v16, v22
	s_mov_b64 exec, -1
	s_waitcnt vmcnt(63)
	v_lshlrev_b32_e32 v24, 16, v138
	v_and_b32_e32 v25, 0xffff0000, v138
	v_lshlrev_b32_e32 v26, 16, v139
	v_and_b32_e32 v27, 0xffff0000, v139
	v_pk_mul_f32 v[24:25], v[16:17], v[24:25] op_sel_hi:[0,1]
	v_pk_mul_f32 v[26:27], v[16:17], v[26:27] op_sel_hi:[0,1]
	v_pk_fma_f32 v[4:5], v[4:5], v[18:19], v[24:25] op_sel_hi:[1,0,1]
	v_pk_fma_f32 v[6:7], v[6:7], v[18:19], v[26:27] op_sel_hi:[1,0,1]
	v_mov_b32_e32 v12, v15
	v_readlane_b32 s12, v2, 44
	v_readlane_b32 s14, v3, 44
	v_cvt_pk_bf16_f32 v20, v4, v5
	v_cvt_pk_bf16_f32 v21, v6, v7
	global_store_dwordx2 v1, v[20:21], s[4:5]
	s_add_u32 s4, s4, 0x8000
	s_addc_u32 s5, s5, 0
	v_add_f32_e32 v13, s12, v12
	v_max_f32_e64 v14, s14, s14
	v_max_f32_e32 v15, v13, v14
	v_sub_f32_e32 v13, v13, v15
	v_sub_f32_e32 v14, s14, v15
	v_mul_f32_e32 v14, 0x3fb8aa3b, v14
	v_mul_f32_e32 v13, 0x3fb8aa3b, v13
	v_exp_f32_e32 v16, v14
	v_exp_f32_e32 v18, v13
	s_mov_b64 exec, 0xffff
	global_store_dword v9, v8, s[8:9]
	s_add_u32 s8, s8, 0x200
	s_addc_u32 s9, s9, 0
	s_cmp_lg_u32 s13, 0
	s_cbranch_scc1 .Lm2_nomc44
	global_store_dword v10, v12, s[10:11] offset:176
.Lm2_nomc44:
	s_waitcnt vmcnt(63)
	v_mul_f32_e32 v22, v18, v8
	v_fma_f32 v8, v200, v16, v22
	s_mov_b64 exec, -1
	s_waitcnt vmcnt(63)
	v_lshlrev_b32_e32 v24, 16, v140
	v_and_b32_e32 v25, 0xffff0000, v140
	v_lshlrev_b32_e32 v26, 16, v141
	v_and_b32_e32 v27, 0xffff0000, v141
	v_pk_mul_f32 v[24:25], v[16:17], v[24:25] op_sel_hi:[0,1]
	v_pk_mul_f32 v[26:27], v[16:17], v[26:27] op_sel_hi:[0,1]
	v_pk_fma_f32 v[4:5], v[4:5], v[18:19], v[24:25] op_sel_hi:[1,0,1]
	v_pk_fma_f32 v[6:7], v[6:7], v[18:19], v[26:27] op_sel_hi:[1,0,1]
	v_mov_b32_e32 v12, v15
	v_readlane_b32 s12, v2, 45
	v_readlane_b32 s14, v3, 45
	v_cvt_pk_bf16_f32 v20, v4, v5
	v_cvt_pk_bf16_f32 v21, v6, v7
	global_store_dwordx2 v1, v[20:21], s[4:5]
	s_add_u32 s4, s4, 0x8000
	s_addc_u32 s5, s5, 0
	v_add_f32_e32 v13, s12, v12
	v_max_f32_e64 v14, s14, s14
	v_max_f32_e32 v15, v13, v14
	v_sub_f32_e32 v13, v13, v15
	v_sub_f32_e32 v14, s14, v15
	v_mul_f32_e32 v14, 0x3fb8aa3b, v14
	v_mul_f32_e32 v13, 0x3fb8aa3b, v13
	v_exp_f32_e32 v16, v14
	v_exp_f32_e32 v18, v13
	s_mov_b64 exec, 0xffff
	global_store_dword v9, v8, s[8:9]
	s_add_u32 s8, s8, 0x200
	s_addc_u32 s9, s9, 0
	s_cmp_lg_u32 s13, 0
	s_cbranch_scc1 .Lm2_nomc45
	global_store_dword v10, v12, s[10:11] offset:180
.Lm2_nomc45:
	s_waitcnt vmcnt(63)
	v_mul_f32_e32 v22, v18, v8
	v_fma_f32 v8, v201, v16, v22
	s_mov_b64 exec, -1
	s_waitcnt vmcnt(63)
	v_lshlrev_b32_e32 v24, 16, v142
	v_and_b32_e32 v25, 0xffff0000, v142
	v_lshlrev_b32_e32 v26, 16, v143
	v_and_b32_e32 v27, 0xffff0000, v143
	v_pk_mul_f32 v[24:25], v[16:17], v[24:25] op_sel_hi:[0,1]
	v_pk_mul_f32 v[26:27], v[16:17], v[26:27] op_sel_hi:[0,1]
	v_pk_fma_f32 v[4:5], v[4:5], v[18:19], v[24:25] op_sel_hi:[1,0,1]
	v_pk_fma_f32 v[6:7], v[6:7], v[18:19], v[26:27] op_sel_hi:[1,0,1]
	v_mov_b32_e32 v12, v15
	v_readlane_b32 s12, v2, 46
	v_readlane_b32 s14, v3, 46
	v_cvt_pk_bf16_f32 v20, v4, v5
	v_cvt_pk_bf16_f32 v21, v6, v7
	global_store_dwordx2 v1, v[20:21], s[4:5]
	s_add_u32 s4, s4, 0x8000
	s_addc_u32 s5, s5, 0
	v_add_f32_e32 v13, s12, v12
	v_max_f32_e64 v14, s14, s14
	v_max_f32_e32 v15, v13, v14
	v_sub_f32_e32 v13, v13, v15
	v_sub_f32_e32 v14, s14, v15
	v_mul_f32_e32 v14, 0x3fb8aa3b, v14
	v_mul_f32_e32 v13, 0x3fb8aa3b, v13
	v_exp_f32_e32 v16, v14
	v_exp_f32_e32 v18, v13
	s_mov_b64 exec, 0xffff
	global_store_dword v9, v8, s[8:9]
	s_add_u32 s8, s8, 0x200
	s_addc_u32 s9, s9, 0
	s_cmp_lg_u32 s13, 0
	s_cbranch_scc1 .Lm2_nomc46
	global_store_dword v10, v12, s[10:11] offset:184
.Lm2_nomc46:
	s_waitcnt vmcnt(63)
	v_mul_f32_e32 v22, v18, v8
	v_fma_f32 v8, v202, v16, v22
	s_mov_b64 exec, -1
	s_waitcnt vmcnt(63)
	v_lshlrev_b32_e32 v24, 16, v144
	v_and_b32_e32 v25, 0xffff0000, v144
	v_lshlrev_b32_e32 v26, 16, v145
	v_and_b32_e32 v27, 0xffff0000, v145
	v_pk_mul_f32 v[24:25], v[16:17], v[24:25] op_sel_hi:[0,1]
	v_pk_mul_f32 v[26:27], v[16:17], v[26:27] op_sel_hi:[0,1]
	v_pk_fma_f32 v[4:5], v[4:5], v[18:19], v[24:25] op_sel_hi:[1,0,1]
	v_pk_fma_f32 v[6:7], v[6:7], v[18:19], v[26:27] op_sel_hi:[1,0,1]
	v_mov_b32_e32 v12, v15
	v_readlane_b32 s12, v2, 47
	v_readlane_b32 s14, v3, 47
	v_cvt_pk_bf16_f32 v20, v4, v5
	v_cvt_pk_bf16_f32 v21, v6, v7
	global_store_dwordx2 v1, v[20:21], s[4:5]
	s_add_u32 s4, s4, 0x8000
	s_addc_u32 s5, s5, 0
	v_add_f32_e32 v13, s12, v12
	v_max_f32_e64 v14, s14, s14
	v_max_f32_e32 v15, v13, v14
	v_sub_f32_e32 v13, v13, v15
	v_sub_f32_e32 v14, s14, v15
	v_mul_f32_e32 v14, 0x3fb8aa3b, v14
	v_mul_f32_e32 v13, 0x3fb8aa3b, v13
	v_exp_f32_e32 v16, v14
	v_exp_f32_e32 v18, v13
	s_mov_b64 exec, 0xffff
	global_store_dword v9, v8, s[8:9]
	s_add_u32 s8, s8, 0x200
	s_addc_u32 s9, s9, 0
	s_cmp_lg_u32 s13, 0
	s_cbranch_scc1 .Lm2_nomc47
	global_store_dword v10, v12, s[10:11] offset:188
.Lm2_nomc47:
	s_waitcnt vmcnt(63)
	v_mul_f32_e32 v22, v18, v8
	v_fma_f32 v8, v203, v16, v22
	s_mov_b64 exec, -1
	s_waitcnt vmcnt(63)
	v_lshlrev_b32_e32 v24, 16, v146
	v_and_b32_e32 v25, 0xffff0000, v146
	v_lshlrev_b32_e32 v26, 16, v147
	v_and_b32_e32 v27, 0xffff0000, v147
	v_pk_mul_f32 v[24:25], v[16:17], v[24:25] op_sel_hi:[0,1]
	v_pk_mul_f32 v[26:27], v[16:17], v[26:27] op_sel_hi:[0,1]
	v_pk_fma_f32 v[4:5], v[4:5], v[18:19], v[24:25] op_sel_hi:[1,0,1]
	v_pk_fma_f32 v[6:7], v[6:7], v[18:19], v[26:27] op_sel_hi:[1,0,1]
	v_mov_b32_e32 v12, v15
	v_readlane_b32 s12, v2, 48
	v_readlane_b32 s14, v3, 48
	v_cvt_pk_bf16_f32 v20, v4, v5
	v_cvt_pk_bf16_f32 v21, v6, v7
	global_store_dwordx2 v1, v[20:21], s[4:5]
	s_add_u32 s4, s4, 0x8000
	s_addc_u32 s5, s5, 0
	v_add_f32_e32 v13, s12, v12
	v_max_f32_e64 v14, s14, s14
	v_max_f32_e32 v15, v13, v14
	v_sub_f32_e32 v13, v13, v15
	v_sub_f32_e32 v14, s14, v15
	v_mul_f32_e32 v14, 0x3fb8aa3b, v14
	v_mul_f32_e32 v13, 0x3fb8aa3b, v13
	v_exp_f32_e32 v16, v14
	v_exp_f32_e32 v18, v13
	s_mov_b64 exec, 0xffff
	global_store_dword v9, v8, s[8:9]
	s_add_u32 s8, s8, 0x200
	s_addc_u32 s9, s9, 0
	s_cmp_lg_u32 s13, 0
	s_cbranch_scc1 .Lm2_nomc48
	global_store_dword v10, v12, s[10:11] offset:192
.Lm2_nomc48:
	s_waitcnt vmcnt(63)
	v_mul_f32_e32 v22, v18, v8
	v_fma_f32 v8, v180, v16, v22
	s_mov_b64 exec, -1
	s_waitcnt vmcnt(63)
	v_lshlrev_b32_e32 v24, 16, v100
	v_and_b32_e32 v25, 0xffff0000, v100
	v_lshlrev_b32_e32 v26, 16, v101
	v_and_b32_e32 v27, 0xffff0000, v101
	v_pk_mul_f32 v[24:25], v[16:17], v[24:25] op_sel_hi:[0,1]
	v_pk_mul_f32 v[26:27], v[16:17], v[26:27] op_sel_hi:[0,1]
	v_pk_fma_f32 v[4:5], v[4:5], v[18:19], v[24:25] op_sel_hi:[1,0,1]
	v_pk_fma_f32 v[6:7], v[6:7], v[18:19], v[26:27] op_sel_hi:[1,0,1]
	v_mov_b32_e32 v12, v15
	v_readlane_b32 s12, v2, 49
	v_readlane_b32 s14, v3, 49
	v_cvt_pk_bf16_f32 v20, v4, v5
	v_cvt_pk_bf16_f32 v21, v6, v7
	global_store_dwordx2 v1, v[20:21], s[4:5]
	s_add_u32 s4, s4, 0x8000
	s_addc_u32 s5, s5, 0
	v_add_f32_e32 v13, s12, v12
	v_max_f32_e64 v14, s14, s14
	v_max_f32_e32 v15, v13, v14
	v_sub_f32_e32 v13, v13, v15
	v_sub_f32_e32 v14, s14, v15
	v_mul_f32_e32 v14, 0x3fb8aa3b, v14
	v_mul_f32_e32 v13, 0x3fb8aa3b, v13
	v_exp_f32_e32 v16, v14
	v_exp_f32_e32 v18, v13
	s_mov_b64 exec, 0xffff
	global_store_dword v9, v8, s[8:9]
	s_add_u32 s8, s8, 0x200
	s_addc_u32 s9, s9, 0
	s_cmp_lg_u32 s13, 0
	s_cbranch_scc1 .Lm2_nomc49
	global_store_dword v10, v12, s[10:11] offset:196
.Lm2_nomc49:
	s_waitcnt vmcnt(63)
	v_mul_f32_e32 v22, v18, v8
	v_fma_f32 v8, v181, v16, v22
	s_mov_b64 exec, -1
	s_waitcnt vmcnt(63)
	v_lshlrev_b32_e32 v24, 16, v102
	v_and_b32_e32 v25, 0xffff0000, v102
	v_lshlrev_b32_e32 v26, 16, v103
	v_and_b32_e32 v27, 0xffff0000, v103
	v_pk_mul_f32 v[24:25], v[16:17], v[24:25] op_sel_hi:[0,1]
	v_pk_mul_f32 v[26:27], v[16:17], v[26:27] op_sel_hi:[0,1]
	v_pk_fma_f32 v[4:5], v[4:5], v[18:19], v[24:25] op_sel_hi:[1,0,1]
	v_pk_fma_f32 v[6:7], v[6:7], v[18:19], v[26:27] op_sel_hi:[1,0,1]
	v_mov_b32_e32 v12, v15
	v_readlane_b32 s12, v2, 50
	v_readlane_b32 s14, v3, 50
	v_cvt_pk_bf16_f32 v20, v4, v5
	v_cvt_pk_bf16_f32 v21, v6, v7
	global_store_dwordx2 v1, v[20:21], s[4:5]
	s_add_u32 s4, s4, 0x8000
	s_addc_u32 s5, s5, 0
	v_add_f32_e32 v13, s12, v12
	v_max_f32_e64 v14, s14, s14
	v_max_f32_e32 v15, v13, v14
	v_sub_f32_e32 v13, v13, v15
	v_sub_f32_e32 v14, s14, v15
	v_mul_f32_e32 v14, 0x3fb8aa3b, v14
	v_mul_f32_e32 v13, 0x3fb8aa3b, v13
	v_exp_f32_e32 v16, v14
	v_exp_f32_e32 v18, v13
	s_mov_b64 exec, 0xffff
	global_store_dword v9, v8, s[8:9]
	s_add_u32 s8, s8, 0x200
	s_addc_u32 s9, s9, 0
	s_cmp_lg_u32 s13, 0
	s_cbranch_scc1 .Lm2_nomc50
	global_store_dword v10, v12, s[10:11] offset:200
.Lm2_nomc50:
	s_waitcnt vmcnt(63)
	v_mul_f32_e32 v22, v18, v8
	v_fma_f32 v8, v182, v16, v22
	s_mov_b64 exec, -1
	s_waitcnt vmcnt(63)
	v_lshlrev_b32_e32 v24, 16, v104
	v_and_b32_e32 v25, 0xffff0000, v104
	v_lshlrev_b32_e32 v26, 16, v105
	v_and_b32_e32 v27, 0xffff0000, v105
	v_pk_mul_f32 v[24:25], v[16:17], v[24:25] op_sel_hi:[0,1]
	v_pk_mul_f32 v[26:27], v[16:17], v[26:27] op_sel_hi:[0,1]
	v_pk_fma_f32 v[4:5], v[4:5], v[18:19], v[24:25] op_sel_hi:[1,0,1]
	v_pk_fma_f32 v[6:7], v[6:7], v[18:19], v[26:27] op_sel_hi:[1,0,1]
	v_mov_b32_e32 v12, v15
	v_readlane_b32 s12, v2, 51
	v_readlane_b32 s14, v3, 51
	v_cvt_pk_bf16_f32 v20, v4, v5
	v_cvt_pk_bf16_f32 v21, v6, v7
	global_store_dwordx2 v1, v[20:21], s[4:5]
	s_add_u32 s4, s4, 0x8000
	s_addc_u32 s5, s5, 0
	v_add_f32_e32 v13, s12, v12
	v_max_f32_e64 v14, s14, s14
	v_max_f32_e32 v15, v13, v14
	v_sub_f32_e32 v13, v13, v15
	v_sub_f32_e32 v14, s14, v15
	v_mul_f32_e32 v14, 0x3fb8aa3b, v14
	v_mul_f32_e32 v13, 0x3fb8aa3b, v13
	v_exp_f32_e32 v16, v14
	v_exp_f32_e32 v18, v13
	s_mov_b64 exec, 0xffff
	global_store_dword v9, v8, s[8:9]
	s_add_u32 s8, s8, 0x200
	s_addc_u32 s9, s9, 0
	s_cmp_lg_u32 s13, 0
	s_cbranch_scc1 .Lm2_nomc51
	global_store_dword v10, v12, s[10:11] offset:204
.Lm2_nomc51:
	s_waitcnt vmcnt(63)
	v_mul_f32_e32 v22, v18, v8
	v_fma_f32 v8, v183, v16, v22
	s_mov_b64 exec, -1
	s_waitcnt vmcnt(63)
	v_lshlrev_b32_e32 v24, 16, v106
	v_and_b32_e32 v25, 0xffff0000, v106
	v_lshlrev_b32_e32 v26, 16, v107
	v_and_b32_e32 v27, 0xffff0000, v107
	v_pk_mul_f32 v[24:25], v[16:17], v[24:25] op_sel_hi:[0,1]
	v_pk_mul_f32 v[26:27], v[16:17], v[26:27] op_sel_hi:[0,1]
	v_pk_fma_f32 v[4:5], v[4:5], v[18:19], v[24:25] op_sel_hi:[1,0,1]
	v_pk_fma_f32 v[6:7], v[6:7], v[18:19], v[26:27] op_sel_hi:[1,0,1]
	v_mov_b32_e32 v12, v15
	v_readlane_b32 s12, v2, 52
	v_readlane_b32 s14, v3, 52
	v_cvt_pk_bf16_f32 v20, v4, v5
	v_cvt_pk_bf16_f32 v21, v6, v7
	global_store_dwordx2 v1, v[20:21], s[4:5]
	s_add_u32 s4, s4, 0x8000
	s_addc_u32 s5, s5, 0
	v_add_f32_e32 v13, s12, v12
	v_max_f32_e64 v14, s14, s14
	v_max_f32_e32 v15, v13, v14
	v_sub_f32_e32 v13, v13, v15
	v_sub_f32_e32 v14, s14, v15
	v_mul_f32_e32 v14, 0x3fb8aa3b, v14
	v_mul_f32_e32 v13, 0x3fb8aa3b, v13
	v_exp_f32_e32 v16, v14
	v_exp_f32_e32 v18, v13
	s_mov_b64 exec, 0xffff
	global_store_dword v9, v8, s[8:9]
	s_add_u32 s8, s8, 0x200
	s_addc_u32 s9, s9, 0
	s_cmp_lg_u32 s13, 0
	s_cbranch_scc1 .Lm2_nomc52
	global_store_dword v10, v12, s[10:11] offset:208
.Lm2_nomc52:
	s_waitcnt vmcnt(63)
	v_mul_f32_e32 v22, v18, v8
	v_fma_f32 v8, v184, v16, v22
	s_mov_b64 exec, -1
	s_waitcnt vmcnt(63)
	v_lshlrev_b32_e32 v24, 16, v108
	v_and_b32_e32 v25, 0xffff0000, v108
	v_lshlrev_b32_e32 v26, 16, v109
	v_and_b32_e32 v27, 0xffff0000, v109
	v_pk_mul_f32 v[24:25], v[16:17], v[24:25] op_sel_hi:[0,1]
	v_pk_mul_f32 v[26:27], v[16:17], v[26:27] op_sel_hi:[0,1]
	v_pk_fma_f32 v[4:5], v[4:5], v[18:19], v[24:25] op_sel_hi:[1,0,1]
	v_pk_fma_f32 v[6:7], v[6:7], v[18:19], v[26:27] op_sel_hi:[1,0,1]
	v_mov_b32_e32 v12, v15
	v_readlane_b32 s12, v2, 53
	v_readlane_b32 s14, v3, 53
	v_cvt_pk_bf16_f32 v20, v4, v5
	v_cvt_pk_bf16_f32 v21, v6, v7
	global_store_dwordx2 v1, v[20:21], s[4:5]
	s_add_u32 s4, s4, 0x8000
	s_addc_u32 s5, s5, 0
	v_add_f32_e32 v13, s12, v12
	v_max_f32_e64 v14, s14, s14
	v_max_f32_e32 v15, v13, v14
	v_sub_f32_e32 v13, v13, v15
	v_sub_f32_e32 v14, s14, v15
	v_mul_f32_e32 v14, 0x3fb8aa3b, v14
	v_mul_f32_e32 v13, 0x3fb8aa3b, v13
	v_exp_f32_e32 v16, v14
	v_exp_f32_e32 v18, v13
	s_mov_b64 exec, 0xffff
	global_store_dword v9, v8, s[8:9]
	s_add_u32 s8, s8, 0x200
	s_addc_u32 s9, s9, 0
	s_cmp_lg_u32 s13, 0
	s_cbranch_scc1 .Lm2_nomc53
	global_store_dword v10, v12, s[10:11] offset:212
.Lm2_nomc53:
	s_waitcnt vmcnt(63)
	v_mul_f32_e32 v22, v18, v8
	v_fma_f32 v8, v185, v16, v22
	s_mov_b64 exec, -1
	s_waitcnt vmcnt(63)
	v_lshlrev_b32_e32 v24, 16, v110
	v_and_b32_e32 v25, 0xffff0000, v110
	v_lshlrev_b32_e32 v26, 16, v111
	v_and_b32_e32 v27, 0xffff0000, v111
	v_pk_mul_f32 v[24:25], v[16:17], v[24:25] op_sel_hi:[0,1]
	v_pk_mul_f32 v[26:27], v[16:17], v[26:27] op_sel_hi:[0,1]
	v_pk_fma_f32 v[4:5], v[4:5], v[18:19], v[24:25] op_sel_hi:[1,0,1]
	v_pk_fma_f32 v[6:7], v[6:7], v[18:19], v[26:27] op_sel_hi:[1,0,1]
	v_mov_b32_e32 v12, v15
	v_readlane_b32 s12, v2, 54
	v_readlane_b32 s14, v3, 54
	v_cvt_pk_bf16_f32 v20, v4, v5
	v_cvt_pk_bf16_f32 v21, v6, v7
	global_store_dwordx2 v1, v[20:21], s[4:5]
	s_add_u32 s4, s4, 0x8000
	s_addc_u32 s5, s5, 0
	v_add_f32_e32 v13, s12, v12
	v_max_f32_e64 v14, s14, s14
	v_max_f32_e32 v15, v13, v14
	v_sub_f32_e32 v13, v13, v15
	v_sub_f32_e32 v14, s14, v15
	v_mul_f32_e32 v14, 0x3fb8aa3b, v14
	v_mul_f32_e32 v13, 0x3fb8aa3b, v13
	v_exp_f32_e32 v16, v14
	v_exp_f32_e32 v18, v13
	s_mov_b64 exec, 0xffff
	global_store_dword v9, v8, s[8:9]
	s_add_u32 s8, s8, 0x200
	s_addc_u32 s9, s9, 0
	s_cmp_lg_u32 s13, 0
	s_cbranch_scc1 .Lm2_nomc54
	global_store_dword v10, v12, s[10:11] offset:216
.Lm2_nomc54:
	s_waitcnt vmcnt(63)
	v_mul_f32_e32 v22, v18, v8
	v_fma_f32 v8, v186, v16, v22
	s_mov_b64 exec, -1
	s_waitcnt vmcnt(63)
	v_lshlrev_b32_e32 v24, 16, v112
	v_and_b32_e32 v25, 0xffff0000, v112
	v_lshlrev_b32_e32 v26, 16, v113
	v_and_b32_e32 v27, 0xffff0000, v113
	v_pk_mul_f32 v[24:25], v[16:17], v[24:25] op_sel_hi:[0,1]
	v_pk_mul_f32 v[26:27], v[16:17], v[26:27] op_sel_hi:[0,1]
	v_pk_fma_f32 v[4:5], v[4:5], v[18:19], v[24:25] op_sel_hi:[1,0,1]
	v_pk_fma_f32 v[6:7], v[6:7], v[18:19], v[26:27] op_sel_hi:[1,0,1]
	v_mov_b32_e32 v12, v15
	v_readlane_b32 s12, v2, 55
	v_readlane_b32 s14, v3, 55
	v_cvt_pk_bf16_f32 v20, v4, v5
	v_cvt_pk_bf16_f32 v21, v6, v7
	global_store_dwordx2 v1, v[20:21], s[4:5]
	s_add_u32 s4, s4, 0x8000
	s_addc_u32 s5, s5, 0
	v_add_f32_e32 v13, s12, v12
	v_max_f32_e64 v14, s14, s14
	v_max_f32_e32 v15, v13, v14
	v_sub_f32_e32 v13, v13, v15
	v_sub_f32_e32 v14, s14, v15
	v_mul_f32_e32 v14, 0x3fb8aa3b, v14
	v_mul_f32_e32 v13, 0x3fb8aa3b, v13
	v_exp_f32_e32 v16, v14
	v_exp_f32_e32 v18, v13
	s_mov_b64 exec, 0xffff
	global_store_dword v9, v8, s[8:9]
	s_add_u32 s8, s8, 0x200
	s_addc_u32 s9, s9, 0
	s_cmp_lg_u32 s13, 0
	s_cbranch_scc1 .Lm2_nomc55
	global_store_dword v10, v12, s[10:11] offset:220
.Lm2_nomc55:
	s_waitcnt vmcnt(63)
	v_mul_f32_e32 v22, v18, v8
	v_fma_f32 v8, v187, v16, v22
	s_mov_b64 exec, -1
	s_waitcnt vmcnt(63)
	v_lshlrev_b32_e32 v24, 16, v114
	v_and_b32_e32 v25, 0xffff0000, v114
	v_lshlrev_b32_e32 v26, 16, v115
	v_and_b32_e32 v27, 0xffff0000, v115
	v_pk_mul_f32 v[24:25], v[16:17], v[24:25] op_sel_hi:[0,1]
	v_pk_mul_f32 v[26:27], v[16:17], v[26:27] op_sel_hi:[0,1]
	v_pk_fma_f32 v[4:5], v[4:5], v[18:19], v[24:25] op_sel_hi:[1,0,1]
	v_pk_fma_f32 v[6:7], v[6:7], v[18:19], v[26:27] op_sel_hi:[1,0,1]
	v_mov_b32_e32 v12, v15
	v_readlane_b32 s12, v2, 56
	v_readlane_b32 s14, v3, 56
	v_cvt_pk_bf16_f32 v20, v4, v5
	v_cvt_pk_bf16_f32 v21, v6, v7
	global_store_dwordx2 v1, v[20:21], s[4:5]
	s_add_u32 s4, s4, 0x8000
	s_addc_u32 s5, s5, 0
	v_add_f32_e32 v13, s12, v12
	v_max_f32_e64 v14, s14, s14
	v_max_f32_e32 v15, v13, v14
	v_sub_f32_e32 v13, v13, v15
	v_sub_f32_e32 v14, s14, v15
	v_mul_f32_e32 v14, 0x3fb8aa3b, v14
	v_mul_f32_e32 v13, 0x3fb8aa3b, v13
	v_exp_f32_e32 v16, v14
	v_exp_f32_e32 v18, v13
	s_mov_b64 exec, 0xffff
	global_store_dword v9, v8, s[8:9]
	s_add_u32 s8, s8, 0x200
	s_addc_u32 s9, s9, 0
	s_cmp_lg_u32 s13, 0
	s_cbranch_scc1 .Lm2_nomc56
	global_store_dword v10, v12, s[10:11] offset:224
.Lm2_nomc56:
	s_waitcnt vmcnt(63)
	v_mul_f32_e32 v22, v18, v8
	v_fma_f32 v8, v188, v16, v22
	s_mov_b64 exec, -1
	s_waitcnt vmcnt(62)
	v_lshlrev_b32_e32 v24, 16, v116
	v_and_b32_e32 v25, 0xffff0000, v116
	v_lshlrev_b32_e32 v26, 16, v117
	v_and_b32_e32 v27, 0xffff0000, v117
	v_pk_mul_f32 v[24:25], v[16:17], v[24:25] op_sel_hi:[0,1]
	v_pk_mul_f32 v[26:27], v[16:17], v[26:27] op_sel_hi:[0,1]
	v_pk_fma_f32 v[4:5], v[4:5], v[18:19], v[24:25] op_sel_hi:[1,0,1]
	v_pk_fma_f32 v[6:7], v[6:7], v[18:19], v[26:27] op_sel_hi:[1,0,1]
	v_mov_b32_e32 v12, v15
	v_readlane_b32 s12, v2, 57
	v_readlane_b32 s14, v3, 57
	v_cvt_pk_bf16_f32 v20, v4, v5
	v_cvt_pk_bf16_f32 v21, v6, v7
	global_store_dwordx2 v1, v[20:21], s[4:5]
	s_add_u32 s4, s4, 0x8000
	s_addc_u32 s5, s5, 0
	v_add_f32_e32 v13, s12, v12
	v_max_f32_e64 v14, s14, s14
	v_max_f32_e32 v15, v13, v14
	v_sub_f32_e32 v13, v13, v15
	v_sub_f32_e32 v14, s14, v15
	v_mul_f32_e32 v14, 0x3fb8aa3b, v14
	v_mul_f32_e32 v13, 0x3fb8aa3b, v13
	v_exp_f32_e32 v16, v14
	v_exp_f32_e32 v18, v13
	s_mov_b64 exec, 0xffff
	global_store_dword v9, v8, s[8:9]
	s_add_u32 s8, s8, 0x200
	s_addc_u32 s9, s9, 0
	s_cmp_lg_u32 s13, 0
	s_cbranch_scc1 .Lm2_nomc57
	global_store_dword v10, v12, s[10:11] offset:228
.Lm2_nomc57:
	s_waitcnt vmcnt(61)
	v_mul_f32_e32 v22, v18, v8
	v_fma_f32 v8, v189, v16, v22
	s_mov_b64 exec, -1
	s_waitcnt vmcnt(60)
	v_lshlrev_b32_e32 v24, 16, v118
	v_and_b32_e32 v25, 0xffff0000, v118
	v_lshlrev_b32_e32 v26, 16, v119
	v_and_b32_e32 v27, 0xffff0000, v119
	v_pk_mul_f32 v[24:25], v[16:17], v[24:25] op_sel_hi:[0,1]
	v_pk_mul_f32 v[26:27], v[16:17], v[26:27] op_sel_hi:[0,1]
	v_pk_fma_f32 v[4:5], v[4:5], v[18:19], v[24:25] op_sel_hi:[1,0,1]
	v_pk_fma_f32 v[6:7], v[6:7], v[18:19], v[26:27] op_sel_hi:[1,0,1]
	v_mov_b32_e32 v12, v15
	v_readlane_b32 s12, v2, 58
	v_readlane_b32 s14, v3, 58
	v_cvt_pk_bf16_f32 v20, v4, v5
	v_cvt_pk_bf16_f32 v21, v6, v7
	global_store_dwordx2 v1, v[20:21], s[4:5]
	s_add_u32 s4, s4, 0x8000
	s_addc_u32 s5, s5, 0
	v_add_f32_e32 v13, s12, v12
	v_max_f32_e64 v14, s14, s14
	v_max_f32_e32 v15, v13, v14
	v_sub_f32_e32 v13, v13, v15
	v_sub_f32_e32 v14, s14, v15
	v_mul_f32_e32 v14, 0x3fb8aa3b, v14
	v_mul_f32_e32 v13, 0x3fb8aa3b, v13
	v_exp_f32_e32 v16, v14
	v_exp_f32_e32 v18, v13
	s_mov_b64 exec, 0xffff
	global_store_dword v9, v8, s[8:9]
	s_add_u32 s8, s8, 0x200
	s_addc_u32 s9, s9, 0
	s_cmp_lg_u32 s13, 0
	s_cbranch_scc1 .Lm2_nomc58
	global_store_dword v10, v12, s[10:11] offset:232
.Lm2_nomc58:
	s_waitcnt vmcnt(59)
	v_mul_f32_e32 v22, v18, v8
	v_fma_f32 v8, v190, v16, v22
	s_mov_b64 exec, -1
	s_waitcnt vmcnt(58)
	v_lshlrev_b32_e32 v24, 16, v120
	v_and_b32_e32 v25, 0xffff0000, v120
	v_lshlrev_b32_e32 v26, 16, v121
	v_and_b32_e32 v27, 0xffff0000, v121
	v_pk_mul_f32 v[24:25], v[16:17], v[24:25] op_sel_hi:[0,1]
	v_pk_mul_f32 v[26:27], v[16:17], v[26:27] op_sel_hi:[0,1]
	v_pk_fma_f32 v[4:5], v[4:5], v[18:19], v[24:25] op_sel_hi:[1,0,1]
	v_pk_fma_f32 v[6:7], v[6:7], v[18:19], v[26:27] op_sel_hi:[1,0,1]
	v_mov_b32_e32 v12, v15
	v_readlane_b32 s12, v2, 59
	v_readlane_b32 s14, v3, 59
	v_cvt_pk_bf16_f32 v20, v4, v5
	v_cvt_pk_bf16_f32 v21, v6, v7
	global_store_dwordx2 v1, v[20:21], s[4:5]
	s_add_u32 s4, s4, 0x8000
	s_addc_u32 s5, s5, 0
	v_add_f32_e32 v13, s12, v12
	v_max_f32_e64 v14, s14, s14
	v_max_f32_e32 v15, v13, v14
	v_sub_f32_e32 v13, v13, v15
	v_sub_f32_e32 v14, s14, v15
	v_mul_f32_e32 v14, 0x3fb8aa3b, v14
	v_mul_f32_e32 v13, 0x3fb8aa3b, v13
	v_exp_f32_e32 v16, v14
	v_exp_f32_e32 v18, v13
	s_mov_b64 exec, 0xffff
	global_store_dword v9, v8, s[8:9]
	s_add_u32 s8, s8, 0x200
	s_addc_u32 s9, s9, 0
	s_cmp_lg_u32 s13, 0
	s_cbranch_scc1 .Lm2_nomc59
	global_store_dword v10, v12, s[10:11] offset:236
.Lm2_nomc59:
	s_waitcnt vmcnt(57)
	v_mul_f32_e32 v22, v18, v8
	v_fma_f32 v8, v191, v16, v22
	s_mov_b64 exec, -1
	s_waitcnt vmcnt(56)
	v_lshlrev_b32_e32 v24, 16, v122
	v_and_b32_e32 v25, 0xffff0000, v122
	v_lshlrev_b32_e32 v26, 16, v123
	v_and_b32_e32 v27, 0xffff0000, v123
	v_pk_mul_f32 v[24:25], v[16:17], v[24:25] op_sel_hi:[0,1]
	v_pk_mul_f32 v[26:27], v[16:17], v[26:27] op_sel_hi:[0,1]
	v_pk_fma_f32 v[4:5], v[4:5], v[18:19], v[24:25] op_sel_hi:[1,0,1]
	v_pk_fma_f32 v[6:7], v[6:7], v[18:19], v[26:27] op_sel_hi:[1,0,1]
	v_mov_b32_e32 v12, v15
	v_readlane_b32 s12, v2, 60
	v_readlane_b32 s14, v3, 60
	v_cvt_pk_bf16_f32 v20, v4, v5
	v_cvt_pk_bf16_f32 v21, v6, v7
	global_store_dwordx2 v1, v[20:21], s[4:5]
	s_add_u32 s4, s4, 0x8000
	s_addc_u32 s5, s5, 0
	v_add_f32_e32 v13, s12, v12
	v_max_f32_e64 v14, s14, s14
	v_max_f32_e32 v15, v13, v14
	v_sub_f32_e32 v13, v13, v15
	v_sub_f32_e32 v14, s14, v15
	v_mul_f32_e32 v14, 0x3fb8aa3b, v14
	v_mul_f32_e32 v13, 0x3fb8aa3b, v13
	v_exp_f32_e32 v16, v14
	v_exp_f32_e32 v18, v13
	s_mov_b64 exec, 0xffff
	global_store_dword v9, v8, s[8:9]
	s_add_u32 s8, s8, 0x200
	s_addc_u32 s9, s9, 0
	s_cmp_lg_u32 s13, 0
	s_cbranch_scc1 .Lm2_nomc60
	global_store_dword v10, v12, s[10:11] offset:240
.Lm2_nomc60:
	s_waitcnt vmcnt(55)
	v_mul_f32_e32 v22, v18, v8
	v_fma_f32 v8, v192, v16, v22
	s_mov_b64 exec, -1
	s_waitcnt vmcnt(54)
	v_lshlrev_b32_e32 v24, 16, v124
	v_and_b32_e32 v25, 0xffff0000, v124
	v_lshlrev_b32_e32 v26, 16, v125
	v_and_b32_e32 v27, 0xffff0000, v125
	v_pk_mul_f32 v[24:25], v[16:17], v[24:25] op_sel_hi:[0,1]
	v_pk_mul_f32 v[26:27], v[16:17], v[26:27] op_sel_hi:[0,1]
	v_pk_fma_f32 v[4:5], v[4:5], v[18:19], v[24:25] op_sel_hi:[1,0,1]
	v_pk_fma_f32 v[6:7], v[6:7], v[18:19], v[26:27] op_sel_hi:[1,0,1]
	v_mov_b32_e32 v12, v15
	v_readlane_b32 s12, v2, 61
	v_readlane_b32 s14, v3, 61
	v_cvt_pk_bf16_f32 v20, v4, v5
	v_cvt_pk_bf16_f32 v21, v6, v7
	global_store_dwordx2 v1, v[20:21], s[4:5]
	s_add_u32 s4, s4, 0x8000
	s_addc_u32 s5, s5, 0
	v_add_f32_e32 v13, s12, v12
	v_max_f32_e64 v14, s14, s14
	v_max_f32_e32 v15, v13, v14
	v_sub_f32_e32 v13, v13, v15
	v_sub_f32_e32 v14, s14, v15
	v_mul_f32_e32 v14, 0x3fb8aa3b, v14
	v_mul_f32_e32 v13, 0x3fb8aa3b, v13
	v_exp_f32_e32 v16, v14
	v_exp_f32_e32 v18, v13
	s_mov_b64 exec, 0xffff
	global_store_dword v9, v8, s[8:9]
	s_add_u32 s8, s8, 0x200
	s_addc_u32 s9, s9, 0
	s_cmp_lg_u32 s13, 0
	s_cbranch_scc1 .Lm2_nomc61
	global_store_dword v10, v12, s[10:11] offset:244
.Lm2_nomc61:
	s_waitcnt vmcnt(53)
	v_mul_f32_e32 v22, v18, v8
	v_fma_f32 v8, v193, v16, v22
	s_mov_b64 exec, -1
	s_waitcnt vmcnt(52)
	v_lshlrev_b32_e32 v24, 16, v126
	v_and_b32_e32 v25, 0xffff0000, v126
	v_lshlrev_b32_e32 v26, 16, v127
	v_and_b32_e32 v27, 0xffff0000, v127
	v_pk_mul_f32 v[24:25], v[16:17], v[24:25] op_sel_hi:[0,1]
	v_pk_mul_f32 v[26:27], v[16:17], v[26:27] op_sel_hi:[0,1]
	v_pk_fma_f32 v[4:5], v[4:5], v[18:19], v[24:25] op_sel_hi:[1,0,1]
	v_pk_fma_f32 v[6:7], v[6:7], v[18:19], v[26:27] op_sel_hi:[1,0,1]
	v_mov_b32_e32 v12, v15
	v_readlane_b32 s12, v2, 62
	v_readlane_b32 s14, v3, 62
	v_cvt_pk_bf16_f32 v20, v4, v5
	v_cvt_pk_bf16_f32 v21, v6, v7
	global_store_dwordx2 v1, v[20:21], s[4:5]
	s_add_u32 s4, s4, 0x8000
	s_addc_u32 s5, s5, 0
	v_add_f32_e32 v13, s12, v12
	v_max_f32_e64 v14, s14, s14
	v_max_f32_e32 v15, v13, v14
	v_sub_f32_e32 v13, v13, v15
	v_sub_f32_e32 v14, s14, v15
	v_mul_f32_e32 v14, 0x3fb8aa3b, v14
	v_mul_f32_e32 v13, 0x3fb8aa3b, v13
	v_exp_f32_e32 v16, v14
	v_exp_f32_e32 v18, v13
	s_mov_b64 exec, 0xffff
	global_store_dword v9, v8, s[8:9]
	s_add_u32 s8, s8, 0x200
	s_addc_u32 s9, s9, 0
	s_cmp_lg_u32 s13, 0
	s_cbranch_scc1 .Lm2_nomc62
	global_store_dword v10, v12, s[10:11] offset:248
.Lm2_nomc62:
	s_waitcnt vmcnt(51)
	v_mul_f32_e32 v22, v18, v8
	v_fma_f32 v8, v194, v16, v22
	s_mov_b64 exec, -1
	s_waitcnt vmcnt(50)
	v_lshlrev_b32_e32 v24, 16, v128
	v_and_b32_e32 v25, 0xffff0000, v128
	v_lshlrev_b32_e32 v26, 16, v129
	v_and_b32_e32 v27, 0xffff0000, v129
	v_pk_mul_f32 v[24:25], v[16:17], v[24:25] op_sel_hi:[0,1]
	v_pk_mul_f32 v[26:27], v[16:17], v[26:27] op_sel_hi:[0,1]
	v_pk_fma_f32 v[4:5], v[4:5], v[18:19], v[24:25] op_sel_hi:[1,0,1]
	v_pk_fma_f32 v[6:7], v[6:7], v[18:19], v[26:27] op_sel_hi:[1,0,1]
	v_mov_b32_e32 v12, v15
	v_readlane_b32 s12, v2, 63
	v_readlane_b32 s14, v3, 63
	v_cvt_pk_bf16_f32 v20, v4, v5
	v_cvt_pk_bf16_f32 v21, v6, v7
	global_store_dwordx2 v1, v[20:21], s[4:5]
	s_add_u32 s4, s4, 0x8000
	s_addc_u32 s5, s5, 0
	v_add_f32_e32 v13, s12, v12
	v_max_f32_e64 v14, s14, s14
	v_max_f32_e32 v15, v13, v14
	v_sub_f32_e32 v13, v13, v15
	v_sub_f32_e32 v14, s14, v15
	v_mul_f32_e32 v14, 0x3fb8aa3b, v14
	v_mul_f32_e32 v13, 0x3fb8aa3b, v13
	v_exp_f32_e32 v16, v14
	v_exp_f32_e32 v18, v13
	s_mov_b64 exec, 0xffff
	global_store_dword v9, v8, s[8:9]
	s_add_u32 s8, s8, 0x200
	s_addc_u32 s9, s9, 0
	s_cmp_lg_u32 s13, 0
	s_cbranch_scc1 .Lm2_nomc63
	global_store_dword v10, v12, s[10:11] offset:252
.Lm2_nomc63:
	s_waitcnt vmcnt(49)
	v_mul_f32_e32 v22, v18, v8
	v_fma_f32 v8, v195, v16, v22
	s_mov_b64 exec, -1
	s_waitcnt vmcnt(48)
	v_lshlrev_b32_e32 v24, 16, v130
	v_and_b32_e32 v25, 0xffff0000, v130
	v_lshlrev_b32_e32 v26, 16, v131
	v_and_b32_e32 v27, 0xffff0000, v131
	v_pk_mul_f32 v[24:25], v[16:17], v[24:25] op_sel_hi:[0,1]
	v_pk_mul_f32 v[26:27], v[16:17], v[26:27] op_sel_hi:[0,1]
	v_pk_fma_f32 v[4:5], v[4:5], v[18:19], v[24:25] op_sel_hi:[1,0,1]
	v_pk_fma_f32 v[6:7], v[6:7], v[18:19], v[26:27] op_sel_hi:[1,0,1]
	v_mov_b32_e32 v12, v15
	s_branch .Lm2_done
.Lm2_done:
.LBB0_483:
	s_or_b64 exec, exec, s[0:1]
	s_and_b32 s0, s86, 7
	s_cmp_lg_u32 s0, 0
	s_mov_b32 s38, s90
	s_cbranch_scc0 .LBB0_485
	s_cmpk_lt_i32 s38, 0x400
	s_cselect_b64 s[0:1], -1, 0
	s_cmpk_gt_i32 s38, 0x3ff
	s_cbranch_scc0 .LBB0_486
	s_branch .LBB0_529
